# chunk operands W and QE stored fragment-major so chunkrec fragment loads are lane-contiguous (1 KB per wave load)
# speedup vs baseline: 1.0155x; 1.0155x over previous
; __device__ __forceinline__ int opaque_tid() { int t = threadIdx.x; asm volatile("" : "+v"(t)); return t; }
; __device__ __forceinline__ int bid() { int b = blockIdx.x; asm volatile("" : "+s"(b)); return b; }
; __device__ __forceinline__ int gdim() { int g = gridDim.x; asm volatile("" : "+s"(g)); return g; }
; DI int xcd_group_item(int blk, int G) { if (G != 256) return blk; const int x = blk & 7, k = blk >> 3; return ((x + 8 * (k >> 2)) << 2) + (k & 3); }
; DI void phase_dn_chunkrec(PrmC p, unsigned char* smem) {
;     ...
;     const int tid = opaque_tid(), lane = tid & 63, wave = tid >> 6, r16 = lane & 15, q4 = lane >> 4, rt = wave >> 1, ct = wave & 1;
;     for (int item0 = bid(); item0 < 256; item0 += gdim()) {
;         const int item = xcd_group_item(item0, gdim());
;         const int sl = item & 3, dir = (item >> 2) & 1, h = (item >> 3) & 3, b = item >> 5, bh = b * 4 + h;
;         f32x4 Sacc[2];
;         Sacc[0] = (f32x4){0.f, 0.f, 0.f, 0.f}; Sacc[1] = Sacc[0];
;         __syncthreads();
;         for (int i = tid; i < 32 * DS_PITCH / 16; i += NTHR) *(uint4*)(smem + D_ST + i * 16) = make_uint4(0, 0, 0, 0);
;         uint4 wf0, wf1, wf2, wf3, qf0, qf1, qf2, qf3, qk0, qk1, kd00, kd01, kd10, kd11; uint2 uf;
;         uint4 nwf0, nwf1, nwf2, nwf3, nqf0, nqf1, nqf2, nqf3, nqk0, nqk1, nkd00, nkd01, nkd10, nkd11; uint2 nuf;
;     ...
;         if (tid < 36) ((float*)(smem + D_EG))[tid] = DEG[(size_t)dir * 1152 + bh * 36 + DC_CIDX(tid)];
;         DC_LOAD(0, );
;         __syncthreads();
.LBB0_286:
	s_andn2_b64 vcc, exec, s[6:7]
	s_cbranch_vccnz .LBB0_321
	s_waitcnt vmcnt(0)
	v_mov_b32_e32 v122, v195
	v_readlane_b32 s4, v254, 0
	s_cmpk_gt_i32 s4, 0xff
	s_cbranch_scc1 .LBB0_321
	v_bfe_u32 v11, v122, 4, 2
	v_lshlrev_b32_e32 v124, 4, v11
	v_mov_b32_e32 v125, v1
	v_lshl_add_u64 v[6:7], s[66:67], 0, v[124:125]
	s_mov_b64 s[12:13], 0x1f86a000
	v_lshl_add_u64 v[126:127], v[6:7], 0, s[12:13]
	s_mov_b64 s[12:13], 0x21c6a000
	v_ashrrev_i32_e32 v10, 7, v122
	v_lshl_add_u64 v[128:129], v[6:7], 0, s[12:13]
	s_mov_b64 s[12:13], 0x2646a000
	v_lshlrev_b32_e32 v2, 4, v10
	v_lshl_add_u64 v[130:131], v[6:7], 0, s[12:13]
	s_mov_b64 s[12:13], 0x2406a000
	v_ashrrev_i32_e32 v3, 31, v2
	v_lshl_add_u64 v[134:135], v[6:7], 0, s[12:13]
	v_lshrrev_b32_e32 v6, 2, v122
	v_and_b32_e32 v8, 15, v122
	v_lshlrev_b32_e32 v166, 11, v10
	v_lshl_add_u32 v166, v11, 7, v166
	v_lshlrev_b32_e32 v167, 3, v11
	v_sub_u32_e32 v166, v166, v167
	v_lshl_add_u32 v166, v8, 3, v166
	v_mov_b32_e32 v167, 0
	v_mov_b32_e32 v5, v3
	v_lshlrev_b32_e32 v0, 3, v11
	v_and_b32_e32 v12, 16, v6
	v_lshl_add_u64 v[6:7], v[2:3], 1, s[66:67]
	v_lshlrev_b32_e32 v3, 2, v11
	v_or_b32_e32 v4, v2, v8
	v_lshlrev_b32_e32 v10, 5, v10
	v_lshl_add_u64 v[6:7], v[6:7], 0, v[0:1]
	s_mov_b64 s[12:13], 0x2766a000
	v_or_b32_e32 v2, v3, v2
	v_lshl_add_u32 v9, v8, 2, 0
	v_or_b32_e32 v132, v10, v8
	v_or_b32_e32 v125, v12, v8
	v_lshl_add_u64 v[136:137], v[6:7], 0, s[12:13]
	v_lshlrev_b32_e32 v7, 1, v2
	v_lshlrev_b32_e32 v8, 2, v12
	v_lshlrev_b32_e32 v2, 7, v2
	v_add3_u32 v155, v9, v8, v2
	v_max_i32_e32 v2, 32, v122
	v_sub_u32_e32 v2, v2, v122
	s_movk_i32 s12, 0x110
	v_add_u32_e32 v2, 0x1ff, v2
	s_add_u32 s5, s66, 0x2be6a000
	v_mad_u32_u24 v6, v125, s12, 0
	v_lshlrev_b32_e32 v0, 7, v125
	v_lshlrev_b64 v[138:139], 7, v[4:5]
	v_lshrrev_b32_e32 v4, 9, v2
	s_addc_u32 s25, s67, 0
	v_sub_u32_e32 v153, v6, v0
	v_lshlrev_b32_e32 v0, 3, v122
	v_add_u32_e32 v4, 1, v4
	s_add_u32 s27, s66, 0x1554a000
	s_movk_i32 s6, 0x220
	v_or_b32_e32 v3, v3, v10
	v_and_b32_e32 v0, 24, v0
	s_movk_i32 s12, 0x1ff
	v_and_b32_e32 v156, 0xfffffe, v4
	s_addc_u32 s28, s67, 0
	v_cmp_gt_i32_e64 s[6:7], s6, v122
	v_cmp_lt_i32_e64 s[8:9], 35, v122
	v_cmp_gt_i32_e64 s[10:11], 4, v122
	v_sub_u32_e32 v145, 39, v122
	v_sub_u32_e32 v150, 3, v122
	v_lshl_add_u32 v151, v122, 2, 0
	v_ashrrev_i32_e32 v133, 31, v10
	v_add_u32_e32 v152, v6, v124
	v_lshl_add_u32 v154, v0, 2, 0
	v_cmp_lt_u32_e64 s[12:13], s12, v2
	v_lshl_add_u32 v157, v156, 9, v122
	v_add_u32_e32 v123, 0x200, v122
	v_cmp_ne_u32_e64 s[14:15], v4, v156
	v_lshl_add_u32 v158, v3, 1, v6
	v_lshlrev_b32_e32 v0, 1, v0
	v_add_u32_e32 v159, v153, v7

; DI void phase_dn_chunkrec(PrmC p, unsigned char* smem) {
;     ...
;         if (tid < 36) ((float*)(smem + D_EG))[tid] = DEG[(size_t)dir * 1152 + bh * 36 + DC_CIDX(tid)];
;         DC_LOAD(0, );
;         __syncthreads();
; #pragma unroll 1
;         for (int ch = 0; ch < 36; ++ch) {
.LBB0_301:
	s_or_b64 exec, exec, s[20:21]
	s_cmp_eq_u32 s31, 0
	s_cselect_b64 s[16:17], -1, 0
	s_and_b64 s[18:19], s[16:17], exec
	v_lshl_add_u64 v[142:143], v[60:61], 0, v[58:59]
	s_cselect_b32 s18, 0, 3
	v_or_b32_e32 v58, s18, v142
	v_mov_b32_e32 v59, v143
	v_lshlrev_b64 v[60:61], 13, v[58:59]
	v_lshl_add_u64 v[62:63], v[60:61], 0, v[166:167]
	v_lshl_add_u64 v[60:61], v[60:61], 0, v[138:139]
	v_lshlrev_b64 v[62:63], 1, v[62:63]
	v_lshl_add_u64 v[64:65], v[126:127], 0, v[62:63]
	v_lshl_add_u64 v[62:63], v[128:129], 0, v[62:63]
	global_load_dwordx4 v[114:117], v[64:65], off
	global_load_dwordx4 v[106:109], v[64:65], off offset:1024
	global_load_dwordx4 v[110:113], v[64:65], off offset:2048
	global_load_dwordx4 v[98:101], v[64:65], off offset:3072
	global_load_dwordx4 v[118:121], v[62:63], off
	global_load_dwordx4 v[102:105], v[62:63], off offset:1024
	global_load_dwordx4 v[94:97], v[62:63], off offset:2048
	global_load_dwordx4 v[90:93], v[62:63], off offset:3072
	v_lshl_add_u64 v[60:61], v[130:131], 0, v[60:61]
	v_lshlrev_b64 v[58:59], 7, v[58:59]
	s_lshl_b32 s18, s37, 5
	global_load_dwordx4 v[86:89], v[60:61], off
	global_load_dwordx4 v[82:85], v[60:61], off offset:64
	v_lshl_add_u64 v[60:61], v[58:59], 0, v[132:133]
	s_and_b32 s18, s18, 0x60
	v_lshlrev_b64 v[60:61], 7, v[60:61]
	v_or_b32_e32 v144, s18, v125
	v_lshl_add_u64 v[60:61], v[134:135], 0, v[60:61]
	v_or_b32_e32 v58, v58, v144
	global_load_dwordx4 v[70:73], v[60:61], off
	global_load_dwordx4 v[78:81], v[60:61], off offset:64
	global_load_dwordx4 v[74:77], v[60:61], off offset:2048
	global_load_dwordx4 v[66:69], v[60:61], off offset:2112
	v_lshlrev_b64 v[58:59], 7, v[58:59]
	v_lshl_add_u64 v[58:59], v[136:137], 0, v[58:59]
	global_load_dwordx2 v[148:149], v[58:59], off
	s_lshl_b32 s18, s18, 1
	s_add_u32 s20, s27, s18
	s_addc_u32 s21, s28, 0
	s_lshl_b32 s29, s29, 8
	s_add_u32 s20, s20, s29
	s_addc_u32 s21, s21, 0
	s_lshl_b32 s37, s30, 8
	v_mov_b32_e32 v58, 0
	s_mov_b32 s39, 0
	s_mul_i32 s18, s31, 0x4800
	s_mov_b32 s19, s36
	v_lshl_add_u64 v[146:147], s[20:21], 0, v[0:1]
	s_lshl_b32 s29, s30, 11
	s_addk_i32 s37, 0x4000
	v_mov_b32_e32 v59, v58
	v_mov_b32_e32 v60, v58
	v_mov_b32_e32 v61, v58
	v_mov_b32_e32 v62, v58
	v_mov_b32_e32 v63, v58
	v_mov_b32_e32 v64, v58
	v_mov_b32_e32 v65, v58
	s_waitcnt lgkmcnt(0)
	s_barrier
	s_add_i32 s38, s39, 1
	s_cmp_eq_u32 s39, 35
	s_cbranch_scc1 .LBB0_308
	s_branch .LBB0_303

; DI void phase_dn_chunkrec(PrmC p, unsigned char* smem) {
;     ...
;         if (tid < 36) ((float*)(smem + D_EG))[tid] = DEG[(size_t)dir * 1152 + bh * 36 + DC_CIDX(tid)];
;         DC_LOAD(0, );
;         __syncthreads();
; #pragma unroll 1
;         for (int ch = 0; ch < 36; ++ch) {
;             if (ch + 1 < 36) DC_LOAD(ch + 1, n);
.LBB0_307:
	s_mov_b32 s21, s36
	v_lshl_add_u64 v[42:43], v[142:143], 0, s[20:21]
	v_lshlrev_b64 v[2:3], 13, v[42:43]
	v_lshl_add_u64 v[34:35], v[2:3], 0, v[138:139]
	v_lshl_add_u64 v[2:3], v[2:3], 0, v[166:167]
	v_lshlrev_b64 v[2:3], 1, v[2:3]
	v_lshl_add_u64 v[14:15], v[126:127], 0, v[2:3]
	v_lshl_add_u64 v[30:31], v[128:129], 0, v[2:3]
	global_load_dwordx4 v[2:5], v[14:15], off
	global_load_dwordx4 v[6:9], v[14:15], off offset:1024
	global_load_dwordx4 v[10:13], v[14:15], off offset:2048
	s_nop 0
	global_load_dwordx4 v[14:17], v[14:15], off offset:3072
	s_nop 0
	global_load_dwordx4 v[18:21], v[30:31], off
	global_load_dwordx4 v[22:25], v[30:31], off offset:1024
	global_load_dwordx4 v[26:29], v[30:31], off offset:2048
	s_nop 0
	global_load_dwordx4 v[30:33], v[30:31], off offset:3072
	v_lshlrev_b64 v[140:141], 7, v[42:43]
	v_lshl_add_u64 v[42:43], v[140:141], 0, v[132:133]
	v_lshlrev_b64 v[42:43], 7, v[42:43]
	v_lshl_add_u64 v[38:39], v[130:131], 0, v[34:35]
	v_lshl_add_u64 v[54:55], v[134:135], 0, v[42:43]
	v_or_b32_e32 v140, v140, v144
	global_load_dwordx4 v[34:37], v[38:39], off
	s_nop 0
	global_load_dwordx4 v[38:41], v[38:39], off offset:64
	s_nop 0
	global_load_dwordx4 v[42:45], v[54:55], off
	global_load_dwordx4 v[46:49], v[54:55], off offset:64
	global_load_dwordx4 v[50:53], v[54:55], off offset:2048
	s_nop 0
	global_load_dwordx4 v[54:57], v[54:55], off offset:2112
	v_lshlrev_b64 v[140:141], 7, v[140:141]
	v_lshl_add_u64 v[140:141], v[136:137], 0, v[140:141]
	global_load_dwordx2 v[140:141], v[140:141], off

; DI void dn_solve_core(float (&x)[64], lf_t Ad) {
;     float4 cur[16], nxt[16];
;     cur[0] = *(const float4*)(Ad + 68);
; #pragma unroll
;     for (int pi = 1; pi < 64; ++pi) {
;         if (pi + 1 < 64) {
; #pragma unroll
;             for (int g4 = 0; g4 < (pi + 4) / 4; ++g4) nxt[g4] = *(const float4*)(Ad + (pi + 1) * 68 + 4 * g4);
;         }
;         float a = x[pi], a2 = 0.f;
; #pragma unroll
;         for (int g4 = 0; g4 < (pi + 3) / 4; ++g4) { const float4 av = cur[g4];
;             if (4 * g4 + 0 < pi) a -= av.x * x[4 * g4 + 0];
;             if (4 * g4 + 1 < pi) a2 -= av.y * x[4 * g4 + 1];
;             if (4 * g4 + 2 < pi) a -= av.z * x[4 * g4 + 2];
;             if (4 * g4 + 3 < pi) a2 -= av.w * x[4 * g4 + 3]; }
;         x[pi] = a + a2;
;         asm volatile("" ::: "memory");
; #pragma unroll
;         for (int g4 = 0; g4 < (pi + 4) / 4; ++g4) cur[g4] = nxt[g4];
;     }
; }
.LBB0_654:
	ds_read_b32 v0, v110 offset:272
	ds_read_b64 v[70:71], v110 offset:544
	ds_read_b96 v[78:80], v110 offset:816
	s_waitcnt lgkmcnt(2)
	v_fma_f32 v0, -v2, v0, v3
	v_add_f32_e32 v73, 0, v0
	s_waitcnt lgkmcnt(1)
	v_fma_f32 v3, -v2, v70, v50
	v_fma_f32 v0, -v71, v73, 0
	ds_read_b128 v[74:77], v110 offset:1088
	s_waitcnt lgkmcnt(1)
	v_fma_f32 v50, -v2, v78, v51
	v_add_f32_e32 v72, v3, v0
	v_fma_f32 v0, -v73, v79, 0
	v_fma_f32 v3, -v80, v72, v50
	v_add_f32_e32 v70, v0, v3
	ds_read_b128 v[78:81], v110 offset:1360
	ds_read_b32 v0, v110 offset:1376
	s_waitcnt lgkmcnt(2)
	v_fma_f32 v3, -v2, v74, v56
	v_fma_f32 v50, -v73, v75, 0
	v_fma_f32 v3, -v72, v76, v3
	v_fma_f32 v56, -v70, v77, v50
	ds_read_b128 v[74:77], v110 offset:1632
	ds_read_b64 v[50:51], v110 offset:1648
	s_waitcnt lgkmcnt(3)
	v_fma_f32 v57, -v2, v78, v57
	v_fma_f32 v71, -v73, v79, 0
	v_fma_f32 v57, -v72, v80, v57
	v_fma_f32 v89, -v70, v81, v71
	ds_read_b128 v[78:81], v110 offset:1904
	ds_read_b96 v[86:88], v110 offset:1920
	s_waitcnt lgkmcnt(3)
	v_fma_f32 v71, -v73, v75, 0
	v_fma_f32 v90, -v70, v77, v71
	v_fma_f32 v66, -v2, v74, v66
	s_waitcnt lgkmcnt(1)
	v_fma_f32 v71, -v73, v79, 0
	v_fma_f32 v79, -v70, v81, v71
	v_add_f32_e32 v71, v3, v56
	v_fma_f32 v67, -v2, v78, v67
	v_fma_f32 v0, -v71, v0, v57
	v_fma_f32 v66, -v72, v76, v66
	ds_read_b128 v[74:77], v110 offset:2176
	ds_read_b128 v[82:85], v110 offset:2192
	v_fma_f32 v78, -v72, v80, v67
	v_add_f32_e32 v67, v89, v0
	v_fma_f32 v0, -v71, v50, v66
	v_fma_f32 v3, -v67, v51, v90
	v_add_f32_e32 v66, v0, v3
	s_waitcnt lgkmcnt(2)
	v_fma_f32 v0, -v71, v86, v78
	v_fma_f32 v3, -v67, v87, v79
	v_fma_f32 v0, -v66, v88, v0
	v_add_f32_e32 v56, v3, v0
	ds_read_b128 v[78:81], v110 offset:2448
	ds_read_b128 v[86:89], v110 offset:2464
	ds_read_b32 v0, v110 offset:2480
	s_waitcnt lgkmcnt(4)
	v_fma_f32 v3, -v2, v74, v64
	v_fma_f32 v50, -v73, v75, 0
	v_fma_f32 v3, -v72, v76, v3
	v_fma_f32 v50, -v70, v77, v50
	s_waitcnt lgkmcnt(3)
	v_fma_f32 v3, -v71, v82, v3
	v_fma_f32 v50, -v67, v83, v50
	v_fma_f32 v3, -v66, v84, v3
	v_fma_f32 v57, -v56, v85, v50
	ds_read_b128 v[74:77], v110 offset:2720
	ds_read_b128 v[82:85], v110 offset:2736
	ds_read_b64 v[50:51], v110 offset:2752
	s_waitcnt lgkmcnt(5)
	v_fma_f32 v64, -v2, v78, v65
	v_fma_f32 v65, -v73, v79, 0
	v_fma_f32 v64, -v72, v80, v64
	v_fma_f32 v65, -v70, v81, v65
	s_waitcnt lgkmcnt(4)
	v_fma_f32 v64, -v71, v86, v64
	v_fma_f32 v65, -v67, v87, v65
	v_fma_f32 v64, -v66, v88, v64
	v_fma_f32 v65, -v56, v89, v65
	ds_read_b128 v[78:81], v110 offset:2992
	ds_read_b128 v[86:89], v110 offset:3008
	ds_read_b96 v[94:96], v110 offset:3024
	s_waitcnt lgkmcnt(5)
	v_fma_f32 v62, -v2, v74, v62
	v_fma_f32 v62, -v72, v76, v62
	s_waitcnt lgkmcnt(4)
	v_fma_f32 v62, -v71, v82, v62
	v_fma_f32 v97, -v66, v84, v62
	s_waitcnt lgkmcnt(2)
	v_fma_f32 v62, -v2, v78, v63
	v_fma_f32 v62, -v72, v80, v62
	v_fma_f32 v74, -v73, v75, 0
	s_waitcnt lgkmcnt(1)
	v_fma_f32 v62, -v71, v86, v62
	v_fma_f32 v74, -v70, v77, v74
	v_fma_f32 v78, -v66, v88, v62
	v_add_f32_e32 v62, v3, v57
	v_fma_f32 v74, -v67, v83, v74
	v_fma_f32 v63, -v73, v79, 0
	v_fma_f32 v0, -v62, v0, v64
	v_fma_f32 v98, -v56, v85, v74
	v_fma_f32 v63, -v70, v81, v63
	v_add_f32_e32 v57, v65, v0
	v_fma_f32 v63, -v67, v87, v63
	v_fma_f32 v0, -v62, v50, v97
	v_fma_f32 v3, -v57, v51, v98
	ds_read_b128 v[74:77], v110 offset:3264
	ds_read_b128 v[82:85], v110 offset:3280
	ds_read_b128 v[90:93], v110 offset:3296
	v_fma_f32 v63, -v56, v89, v63
	v_add_f32_e32 v51, v0, v3
	s_waitcnt lgkmcnt(3)
	v_fma_f32 v0, -v62, v94, v78
	v_fma_f32 v3, -v57, v95, v63
	v_fma_f32 v0, -v51, v96, v0
	v_add_f32_e32 v3, v3, v0
	ds_read_b128 v[78:81], v110 offset:3536
	ds_read_b128 v[86:89], v110 offset:3552
	ds_read_b128 v[94:97], v110 offset:3568
	ds_read_b32 v0, v110 offset:3584
	s_waitcnt lgkmcnt(6)
	v_fma_f32 v50, -v2, v74, v60
	v_fma_f32 v60, -v73, v75, 0
	v_fma_f32 v50, -v72, v76, v50
	v_fma_f32 v60, -v70, v77, v60
	s_waitcnt lgkmcnt(3)
	v_fma_f32 v61, -v2, v78, v61
	v_fma_f32 v63, -v73, v79, 0
	v_fma_f32 v50, -v71, v82, v50
	v_fma_f32 v60, -v67, v83, v60
	v_fma_f32 v61, -v72, v80, v61
	v_fma_f32 v63, -v70, v81, v63
	v_fma_f32 v50, -v66, v84, v50
	v_fma_f32 v60, -v56, v85, v60
	s_waitcnt lgkmcnt(2)
	v_fma_f32 v61, -v71, v86, v61
	v_fma_f32 v63, -v67, v87, v63
	v_fma_f32 v50, -v62, v90, v50
	v_fma_f32 v60, -v57, v91, v60
	v_fma_f32 v61, -v66, v88, v61
	v_fma_f32 v63, -v56, v89, v63
	v_fma_f32 v50, -v51, v92, v50
	v_fma_f32 v60, -v3, v93, v60
	ds_read_b128 v[74:77], v110 offset:3808
	ds_read_b128 v[82:85], v110 offset:3824
	ds_read_b128 v[90:93], v110 offset:3840
	ds_read_b64 v[64:65], v110 offset:3856
	s_waitcnt lgkmcnt(5)
	v_fma_f32 v61, -v62, v94, v61
	v_fma_f32 v63, -v57, v95, v63
	v_fma_f32 v61, -v51, v96, v61
	v_fma_f32 v63, -v3, v97, v63
	ds_read_b128 v[78:81], v110 offset:4080
	ds_read_b128 v[86:89], v110 offset:4096
	ds_read_b128 v[94:97], v110 offset:4112
	ds_read_b96 v[130:132], v110 offset:4128
	s_waitcnt lgkmcnt(7)
	v_fma_f32 v58, -v2, v74, v58
	v_fma_f32 v74, -v73, v75, 0
	s_waitcnt lgkmcnt(3)
	v_fma_f32 v59, -v2, v78, v59
	v_fma_f32 v58, -v72, v76, v58
	v_fma_f32 v74, -v70, v77, v74
	v_fma_f32 v59, -v72, v80, v59
	v_fma_f32 v58, -v71, v82, v58
	v_fma_f32 v74, -v67, v83, v74
	v_fma_f32 v78, -v73, v79, 0
	s_waitcnt lgkmcnt(2)
	v_fma_f32 v59, -v71, v86, v59
	v_fma_f32 v58, -v66, v84, v58
	v_fma_f32 v74, -v56, v85, v74
	v_fma_f32 v78, -v70, v81, v78
	v_fma_f32 v59, -v66, v88, v59
	v_add_f32_e32 v60, v50, v60
	v_fma_f32 v58, -v62, v90, v58
	v_fma_f32 v74, -v57, v91, v74
	v_fma_f32 v78, -v67, v87, v78
	s_waitcnt lgkmcnt(1)
; DI void dn_solve_core(float (&x)[64], lf_t Ad) {
;     float4 cur[16], nxt[16];
;     cur[0] = *(const float4*)(Ad + 68);
; #pragma unroll
;     for (int pi = 1; pi < 64; ++pi) {
;         if (pi + 1 < 64) {
; #pragma unroll
;             for (int g4 = 0; g4 < (pi + 4) / 4; ++g4) nxt[g4] = *(const float4*)(Ad + (pi + 1) * 68 + 4 * g4);
;         }
;         float a = x[pi], a2 = 0.f;
; #pragma unroll
;         for (int g4 = 0; g4 < (pi + 3) / 4; ++g4) { const float4 av = cur[g4];
;             if (4 * g4 + 0 < pi) a -= av.x * x[4 * g4 + 0];
;             if (4 * g4 + 1 < pi) a2 -= av.y * x[4 * g4 + 1];
;             if (4 * g4 + 2 < pi) a -= av.z * x[4 * g4 + 2];
;             if (4 * g4 + 3 < pi) a2 -= av.w * x[4 * g4 + 3]; }
;         x[pi] = a + a2;
;         asm volatile("" ::: "memory");
; #pragma unroll
;         for (int g4 = 0; g4 < (pi + 4) / 4; ++g4) cur[g4] = nxt[g4];
;     }
; }
	v_fma_f32 v59, -v62, v94, v59
	v_fma_f32 v0, -v60, v0, v61
	v_fma_f32 v58, -v51, v92, v58
	v_fma_f32 v98, -v3, v93, v74
	v_fma_f32 v78, -v56, v89, v78
	v_fma_f32 v79, -v51, v96, v59
	v_add_f32_e32 v59, v63, v0
	v_fma_f32 v78, -v57, v95, v78
	v_fma_f32 v0, -v60, v64, v58
	v_fma_f32 v50, -v59, v65, v98
	ds_read_b128 v[74:77], v110 offset:4352
	ds_read_b128 v[82:85], v110 offset:4368
	ds_read_b128 v[90:93], v110 offset:4384
	ds_read_b128 v[126:129], v110 offset:4400
	v_fma_f32 v78, -v3, v97, v78
	v_add_f32_e32 v58, v0, v50
	s_waitcnt lgkmcnt(4)
	v_fma_f32 v0, -v60, v130, v79
	v_fma_f32 v50, -v59, v131, v78
	v_fma_f32 v0, -v58, v132, v0
	v_add_f32_e32 v50, v50, v0
	ds_read_b128 v[78:81], v110 offset:4624
	ds_read_b128 v[86:89], v110 offset:4640
	ds_read_b128 v[94:97], v110 offset:4656
	ds_read_b128 v[130:133], v110 offset:4672
	ds_read_b32 v0, v110 offset:4688
	s_waitcnt lgkmcnt(8)
	v_fma_f32 v54, -v2, v74, v54
	v_fma_f32 v61, -v73, v75, 0
	v_fma_f32 v54, -v72, v76, v54
	v_fma_f32 v61, -v70, v77, v61
	s_waitcnt lgkmcnt(4)
	v_fma_f32 v55, -v2, v78, v55
	v_fma_f32 v54, -v71, v82, v54
	v_fma_f32 v61, -v67, v83, v61
	v_fma_f32 v55, -v72, v80, v55
	v_fma_f32 v54, -v66, v84, v54
	v_fma_f32 v61, -v56, v85, v61
	s_waitcnt lgkmcnt(3)
	v_fma_f32 v55, -v71, v86, v55
	v_fma_f32 v54, -v62, v90, v54
	v_fma_f32 v61, -v57, v91, v61
	v_fma_f32 v55, -v66, v88, v55
	v_fma_f32 v54, -v51, v92, v54
	v_fma_f32 v61, -v3, v93, v61
	s_waitcnt lgkmcnt(2)
	v_fma_f32 v55, -v62, v94, v55
	v_fma_f32 v54, -v60, v126, v54
	v_fma_f32 v61, -v59, v127, v61
	v_fma_f32 v55, -v51, v96, v55
	v_fma_f32 v54, -v58, v128, v54
	v_fma_f32 v61, -v50, v129, v61
	ds_read_b128 v[74:77], v110 offset:4896
	ds_read_b128 v[82:85], v110 offset:4912
	ds_read_b128 v[90:93], v110 offset:4928
	ds_read_b128 v[126:129], v110 offset:4944
	ds_read_b64 v[64:65], v110 offset:4960
	v_fma_f32 v63, -v73, v79, 0
	s_waitcnt lgkmcnt(6)
	v_fma_f32 v55, -v60, v130, v55
	v_fma_f32 v63, -v70, v81, v63
	v_fma_f32 v98, -v58, v132, v55
	s_waitcnt lgkmcnt(4)
	v_fma_f32 v55, -v73, v75, 0
	v_fma_f32 v63, -v67, v87, v63
	v_fma_f32 v55, -v70, v77, v55
	v_fma_f32 v63, -v56, v89, v63
	s_waitcnt lgkmcnt(3)
	v_fma_f32 v55, -v67, v83, v55
	v_fma_f32 v63, -v57, v95, v63
	v_fma_f32 v55, -v56, v85, v55
	v_fma_f32 v63, -v3, v97, v63
	s_waitcnt lgkmcnt(2)
	v_fma_f32 v55, -v57, v91, v55
	v_fma_f32 v63, -v59, v131, v63
	v_fma_f32 v55, -v3, v93, v55
	v_fma_f32 v63, -v50, v133, v63
	ds_read_b128 v[78:81], v110 offset:5168
	ds_read_b128 v[86:89], v110 offset:5184
	ds_read_b128 v[94:97], v110 offset:5200
	ds_read_b128 v[130:133], v110 offset:5216
	ds_read_b96 v[138:140], v110 offset:5232
	s_waitcnt lgkmcnt(6)
	v_fma_f32 v55, -v59, v127, v55
	v_fma_f32 v99, -v50, v129, v55
	s_waitcnt lgkmcnt(4)
	v_fma_f32 v55, -v73, v79, 0
	v_fma_f32 v55, -v70, v81, v55
	v_fma_f32 v52, -v2, v74, v52
	s_waitcnt lgkmcnt(3)
	v_fma_f32 v55, -v67, v87, v55
	v_fma_f32 v52, -v72, v76, v52
	v_fma_f32 v53, -v2, v78, v53
	v_fma_f32 v55, -v56, v89, v55
	v_fma_f32 v52, -v71, v82, v52
	v_fma_f32 v53, -v72, v80, v53
	s_waitcnt lgkmcnt(2)
	v_fma_f32 v55, -v57, v95, v55
	v_fma_f32 v52, -v66, v84, v52
	v_fma_f32 v53, -v71, v86, v53
	v_fma_f32 v55, -v3, v97, v55
	v_fma_f32 v52, -v62, v90, v52
	v_fma_f32 v53, -v66, v88, v53
	s_waitcnt lgkmcnt(1)
	v_fma_f32 v55, -v59, v131, v55
	v_fma_f32 v52, -v51, v92, v52
	v_fma_f32 v53, -v62, v94, v53
	v_fma_f32 v79, -v50, v133, v55
	v_add_f32_e32 v55, v54, v61
	v_fma_f32 v52, -v60, v126, v52
	v_fma_f32 v53, -v51, v96, v53
	v_fma_f32 v0, -v55, v0, v98
	v_fma_f32 v52, -v58, v128, v52
	v_fma_f32 v53, -v60, v130, v53
	v_add_f32_e32 v54, v63, v0
	v_fma_f32 v78, -v58, v132, v53
	v_fma_f32 v0, -v55, v64, v52
	v_fma_f32 v52, -v54, v65, v99
	v_add_f32_e32 v53, v0, v52
	s_waitcnt lgkmcnt(0)
	v_fma_f32 v0, -v55, v138, v78
	ds_read_b128 v[74:77], v110 offset:5440
	ds_read_b128 v[82:85], v110 offset:5456
	ds_read_b128 v[90:93], v110 offset:5472
	ds_read_b128 v[126:129], v110 offset:5488
	ds_read_b128 v[134:137], v110 offset:5504
	v_fma_f32 v52, -v54, v139, v79
	v_fma_f32 v0, -v53, v140, v0
	v_add_f32_e32 v52, v52, v0
	ds_read_b128 v[78:81], v110 offset:5712
	ds_read_b128 v[86:89], v110 offset:5728
	ds_read_b128 v[94:97], v110 offset:5744
	ds_read_b128 v[130:133], v110 offset:5760
	ds_read_b128 v[138:141], v110 offset:5776
	ds_read_b32 v0, v110 offset:5792
	s_waitcnt lgkmcnt(10)
	v_fma_f32 v48, -v2, v74, v48
	v_fma_f32 v61, -v73, v75, 0
	s_waitcnt lgkmcnt(5)
	v_fma_f32 v49, -v2, v78, v49
	v_fma_f32 v48, -v72, v76, v48
	v_fma_f32 v61, -v70, v77, v61
	v_fma_f32 v49, -v72, v80, v49
	v_fma_f32 v48, -v71, v82, v48
	v_fma_f32 v61, -v67, v83, v61
	s_waitcnt lgkmcnt(4)
	v_fma_f32 v49, -v71, v86, v49
	v_fma_f32 v48, -v66, v84, v48
	v_fma_f32 v61, -v56, v85, v61
	v_fma_f32 v49, -v66, v88, v49
	v_fma_f32 v48, -v62, v90, v48
	v_fma_f32 v61, -v57, v91, v61
	s_waitcnt lgkmcnt(3)
	v_fma_f32 v49, -v62, v94, v49
	v_fma_f32 v48, -v51, v92, v48
	v_fma_f32 v61, -v3, v93, v61
	v_fma_f32 v49, -v51, v96, v49
	v_fma_f32 v48, -v60, v126, v48
	v_fma_f32 v61, -v59, v127, v61
	s_waitcnt lgkmcnt(2)
	v_fma_f32 v49, -v60, v130, v49
	v_fma_f32 v48, -v58, v128, v48
	v_fma_f32 v61, -v50, v129, v61
	v_fma_f32 v49, -v58, v132, v49
	v_fma_f32 v48, -v55, v134, v48
	v_fma_f32 v61, -v54, v135, v61
	s_waitcnt lgkmcnt(1)
	v_fma_f32 v49, -v55, v138, v49
	v_fma_f32 v48, -v53, v136, v48
	v_fma_f32 v61, -v52, v137, v61
	ds_read_b128 v[74:77], v110 offset:5984
	ds_read_b128 v[82:85], v110 offset:6000
	ds_read_b128 v[90:93], v110 offset:6016
	ds_read_b128 v[126:129], v110 offset:6032
	ds_read_b128 v[134:137], v110 offset:6048
	ds_read_b64 v[64:65], v110 offset:6064
	v_fma_f32 v63, -v73, v79, 0
	v_fma_f32 v98, -v53, v140, v49
	s_waitcnt lgkmcnt(5)
; DI void dn_solve_core(float (&x)[64], lf_t Ad) {
;     float4 cur[16], nxt[16];
;     cur[0] = *(const float4*)(Ad + 68);
; #pragma unroll
;     for (int pi = 1; pi < 64; ++pi) {
;         if (pi + 1 < 64) {
; #pragma unroll
;             for (int g4 = 0; g4 < (pi + 4) / 4; ++g4) nxt[g4] = *(const float4*)(Ad + (pi + 1) * 68 + 4 * g4);
;         }
;         float a = x[pi], a2 = 0.f;
; #pragma unroll
;         for (int g4 = 0; g4 < (pi + 3) / 4; ++g4) { const float4 av = cur[g4];
;             if (4 * g4 + 0 < pi) a -= av.x * x[4 * g4 + 0];
;             if (4 * g4 + 1 < pi) a2 -= av.y * x[4 * g4 + 1];
;             if (4 * g4 + 2 < pi) a -= av.z * x[4 * g4 + 2];
;             if (4 * g4 + 3 < pi) a2 -= av.w * x[4 * g4 + 3]; }
;         x[pi] = a + a2;
;         asm volatile("" ::: "memory");
; #pragma unroll
;         for (int g4 = 0; g4 < (pi + 4) / 4; ++g4) cur[g4] = nxt[g4];
;     }
; }
	v_fma_f32 v49, -v73, v75, 0
	v_fma_f32 v63, -v70, v81, v63
	v_fma_f32 v49, -v70, v77, v49
	v_fma_f32 v63, -v67, v87, v63
	s_waitcnt lgkmcnt(4)
	v_fma_f32 v49, -v67, v83, v49
	v_fma_f32 v63, -v56, v89, v63
	v_fma_f32 v49, -v56, v85, v49
	v_fma_f32 v63, -v57, v95, v63
	s_waitcnt lgkmcnt(3)
	v_fma_f32 v49, -v57, v91, v49
	v_fma_f32 v63, -v3, v97, v63
	v_fma_f32 v49, -v3, v93, v49
	v_fma_f32 v63, -v59, v131, v63
	s_waitcnt lgkmcnt(2)
	v_fma_f32 v49, -v59, v127, v49
	v_fma_f32 v63, -v50, v133, v63
	v_fma_f32 v49, -v50, v129, v49
	v_fma_f32 v63, -v54, v139, v63
	s_waitcnt lgkmcnt(1)
	v_fma_f32 v49, -v54, v135, v49
	v_fma_f32 v63, -v52, v141, v63
	ds_read_b128 v[78:81], v110 offset:6256
	ds_read_b128 v[86:89], v110 offset:6272
	ds_read_b128 v[94:97], v110 offset:6288
	ds_read_b128 v[130:133], v110 offset:6304
	ds_read_b128 v[138:141], v110 offset:6320
	ds_read_b96 v[146:148], v110 offset:6336
	v_fma_f32 v99, -v52, v137, v49
	s_waitcnt lgkmcnt(5)
	v_fma_f32 v49, -v73, v79, 0
	v_fma_f32 v49, -v70, v81, v49
	v_fma_f32 v46, -v2, v74, v46
	s_waitcnt lgkmcnt(4)
	v_fma_f32 v49, -v67, v87, v49
	v_fma_f32 v46, -v72, v76, v46
	v_fma_f32 v47, -v2, v78, v47
	v_fma_f32 v49, -v56, v89, v49
	v_fma_f32 v46, -v71, v82, v46
	v_fma_f32 v47, -v72, v80, v47
	s_waitcnt lgkmcnt(3)
	v_fma_f32 v49, -v57, v95, v49
	v_fma_f32 v46, -v66, v84, v46
	v_fma_f32 v47, -v71, v86, v47
	v_fma_f32 v49, -v3, v97, v49
	v_fma_f32 v46, -v62, v90, v46
	v_fma_f32 v47, -v66, v88, v47
	s_waitcnt lgkmcnt(2)
	v_fma_f32 v49, -v59, v131, v49
	v_fma_f32 v46, -v51, v92, v46
	v_fma_f32 v47, -v62, v94, v47
	v_fma_f32 v49, -v50, v133, v49
	v_fma_f32 v46, -v60, v126, v46
	v_fma_f32 v47, -v51, v96, v47
	s_waitcnt lgkmcnt(1)
	v_fma_f32 v49, -v54, v139, v49
	v_fma_f32 v46, -v58, v128, v46
	v_fma_f32 v47, -v60, v130, v47
	v_fma_f32 v79, -v52, v141, v49
	v_add_f32_e32 v49, v48, v61
	v_fma_f32 v46, -v55, v134, v46
	v_fma_f32 v47, -v58, v132, v47
	v_fma_f32 v0, -v49, v0, v98
	v_fma_f32 v46, -v53, v136, v46
	v_fma_f32 v47, -v55, v138, v47
	v_add_f32_e32 v48, v63, v0
	v_fma_f32 v78, -v53, v140, v47
	v_fma_f32 v0, -v49, v64, v46
	v_fma_f32 v46, -v48, v65, v99
	v_add_f32_e32 v47, v0, v46
	s_waitcnt lgkmcnt(0)
	v_fma_f32 v0, -v49, v146, v78
	ds_read_b128 v[74:77], v110 offset:6528
	ds_read_b128 v[82:85], v110 offset:6544
	ds_read_b128 v[90:93], v110 offset:6560
	ds_read_b128 v[126:129], v110 offset:6576
	ds_read_b128 v[134:137], v110 offset:6592
	ds_read_b128 v[142:145], v110 offset:6608
	v_fma_f32 v46, -v48, v147, v79
	v_fma_f32 v0, -v47, v148, v0
	v_add_f32_e32 v46, v46, v0
	ds_read_b128 v[78:81], v110 offset:6800
	ds_read_b128 v[86:89], v110 offset:6816
	ds_read_b128 v[94:97], v110 offset:6832
	ds_read_b128 v[130:133], v110 offset:6848
	ds_read_b128 v[138:141], v110 offset:6864
	ds_read_b128 v[146:149], v110 offset:6880
	ds_read_b32 v0, v110 offset:6896
	s_waitcnt lgkmcnt(12)
	v_fma_f32 v44, -v2, v74, v44
	v_fma_f32 v61, -v73, v75, 0
	s_waitcnt lgkmcnt(6)
	v_fma_f32 v45, -v2, v78, v45
	v_fma_f32 v44, -v72, v76, v44
	v_fma_f32 v61, -v70, v77, v61
	v_fma_f32 v45, -v72, v80, v45
	v_fma_f32 v44, -v71, v82, v44
	v_fma_f32 v61, -v67, v83, v61
	s_waitcnt lgkmcnt(5)
	v_fma_f32 v45, -v71, v86, v45
	v_fma_f32 v44, -v66, v84, v44
	v_fma_f32 v61, -v56, v85, v61
	v_fma_f32 v45, -v66, v88, v45
	v_fma_f32 v44, -v62, v90, v44
	v_fma_f32 v61, -v57, v91, v61
	s_waitcnt lgkmcnt(4)
	v_fma_f32 v45, -v62, v94, v45
	v_fma_f32 v44, -v51, v92, v44
	v_fma_f32 v61, -v3, v93, v61
	v_fma_f32 v45, -v51, v96, v45
	v_fma_f32 v44, -v60, v126, v44
	v_fma_f32 v61, -v59, v127, v61
	s_waitcnt lgkmcnt(3)
	v_fma_f32 v45, -v60, v130, v45
	v_fma_f32 v44, -v58, v128, v44
	v_fma_f32 v61, -v50, v129, v61
	v_fma_f32 v45, -v58, v132, v45
	v_fma_f32 v44, -v55, v134, v44
	v_fma_f32 v61, -v54, v135, v61
	s_waitcnt lgkmcnt(2)
	v_fma_f32 v45, -v55, v138, v45
	v_fma_f32 v44, -v53, v136, v44
	v_fma_f32 v61, -v52, v137, v61
	v_fma_f32 v45, -v53, v140, v45
	v_fma_f32 v44, -v49, v142, v44
	v_fma_f32 v61, -v48, v143, v61
	s_waitcnt lgkmcnt(1)
	v_fma_f32 v45, -v49, v146, v45
	v_fma_f32 v44, -v47, v144, v44
	v_fma_f32 v61, -v46, v145, v61
	ds_read_b128 v[74:77], v110 offset:7072
	ds_read_b128 v[82:85], v110 offset:7088
	ds_read_b128 v[90:93], v110 offset:7104
	ds_read_b128 v[126:129], v110 offset:7120
	ds_read_b128 v[134:137], v110 offset:7136
	ds_read_b128 v[142:145], v110 offset:7152
	ds_read_b64 v[64:65], v110 offset:7168
	v_fma_f32 v63, -v73, v79, 0
	v_fma_f32 v98, -v47, v148, v45
	s_waitcnt lgkmcnt(6)
	v_fma_f32 v45, -v73, v75, 0
	v_fma_f32 v63, -v70, v81, v63
	v_fma_f32 v45, -v70, v77, v45
	v_fma_f32 v63, -v67, v87, v63
	s_waitcnt lgkmcnt(5)
	v_fma_f32 v45, -v67, v83, v45
	v_fma_f32 v63, -v56, v89, v63
	v_fma_f32 v45, -v56, v85, v45
	v_fma_f32 v63, -v57, v95, v63
	s_waitcnt lgkmcnt(4)
	v_fma_f32 v45, -v57, v91, v45
	v_fma_f32 v63, -v3, v97, v63
	v_fma_f32 v45, -v3, v93, v45
	v_fma_f32 v63, -v59, v131, v63
	s_waitcnt lgkmcnt(3)
	v_fma_f32 v45, -v59, v127, v45
	v_fma_f32 v63, -v50, v133, v63
	v_fma_f32 v45, -v50, v129, v45
	v_fma_f32 v63, -v54, v139, v63
	s_waitcnt lgkmcnt(2)
	v_fma_f32 v45, -v54, v135, v45
	v_fma_f32 v63, -v52, v141, v63
	v_fma_f32 v45, -v52, v137, v45
	v_fma_f32 v63, -v48, v147, v63
	s_waitcnt lgkmcnt(1)
	v_fma_f32 v45, -v48, v143, v45
	v_fma_f32 v63, -v46, v149, v63
	ds_read_b128 v[78:81], v110 offset:7344
	ds_read_b128 v[86:89], v110 offset:7360
	ds_read_b128 v[94:97], v110 offset:7376
	ds_read_b128 v[130:133], v110 offset:7392
	ds_read_b128 v[138:141], v110 offset:7408
	ds_read_b128 v[146:149], v110 offset:7424
	ds_read_b96 v[154:156], v110 offset:7440
	v_fma_f32 v99, -v46, v145, v45
	s_waitcnt lgkmcnt(6)
; DI void dn_solve_core(float (&x)[64], lf_t Ad) {
;     float4 cur[16], nxt[16];
;     cur[0] = *(const float4*)(Ad + 68);
; #pragma unroll
;     for (int pi = 1; pi < 64; ++pi) {
;         if (pi + 1 < 64) {
; #pragma unroll
;             for (int g4 = 0; g4 < (pi + 4) / 4; ++g4) nxt[g4] = *(const float4*)(Ad + (pi + 1) * 68 + 4 * g4);
;         }
;         float a = x[pi], a2 = 0.f;
; #pragma unroll
;         for (int g4 = 0; g4 < (pi + 3) / 4; ++g4) { const float4 av = cur[g4];
;             if (4 * g4 + 0 < pi) a -= av.x * x[4 * g4 + 0];
;             if (4 * g4 + 1 < pi) a2 -= av.y * x[4 * g4 + 1];
;             if (4 * g4 + 2 < pi) a -= av.z * x[4 * g4 + 2];
;             if (4 * g4 + 3 < pi) a2 -= av.w * x[4 * g4 + 3]; }
;         x[pi] = a + a2;
;         asm volatile("" ::: "memory");
; #pragma unroll
;         for (int g4 = 0; g4 < (pi + 4) / 4; ++g4) cur[g4] = nxt[g4];
;     }
; }
	v_fma_f32 v45, -v73, v79, 0
	v_fma_f32 v45, -v70, v81, v45
	v_fma_f32 v42, -v2, v74, v42
	s_waitcnt lgkmcnt(5)
	v_fma_f32 v45, -v67, v87, v45
	v_fma_f32 v42, -v72, v76, v42
	v_fma_f32 v43, -v2, v78, v43
	v_fma_f32 v45, -v56, v89, v45
	v_fma_f32 v42, -v71, v82, v42
	v_fma_f32 v43, -v72, v80, v43
	s_waitcnt lgkmcnt(4)
	v_fma_f32 v45, -v57, v95, v45
	v_fma_f32 v42, -v66, v84, v42
	v_fma_f32 v43, -v71, v86, v43
	v_fma_f32 v45, -v3, v97, v45
	v_fma_f32 v42, -v62, v90, v42
	v_fma_f32 v43, -v66, v88, v43
	s_waitcnt lgkmcnt(3)
	v_fma_f32 v45, -v59, v131, v45
	v_fma_f32 v42, -v51, v92, v42
	v_fma_f32 v43, -v62, v94, v43
	v_fma_f32 v45, -v50, v133, v45
	v_fma_f32 v42, -v60, v126, v42
	v_fma_f32 v43, -v51, v96, v43
	s_waitcnt lgkmcnt(2)
	v_fma_f32 v45, -v54, v139, v45
	v_fma_f32 v42, -v58, v128, v42
	v_fma_f32 v43, -v60, v130, v43
	v_fma_f32 v45, -v52, v141, v45
	v_fma_f32 v42, -v55, v134, v42
	v_fma_f32 v43, -v58, v132, v43
	s_waitcnt lgkmcnt(1)
	v_fma_f32 v45, -v48, v147, v45
	v_fma_f32 v42, -v53, v136, v42
	v_fma_f32 v43, -v55, v138, v43
	v_fma_f32 v79, -v46, v149, v45
	v_add_f32_e32 v45, v44, v61
	v_fma_f32 v42, -v49, v142, v42
	v_fma_f32 v43, -v53, v140, v43
	v_fma_f32 v0, -v45, v0, v98
	v_fma_f32 v42, -v47, v144, v42
	v_fma_f32 v43, -v49, v146, v43
	v_add_f32_e32 v44, v63, v0
	v_fma_f32 v78, -v47, v148, v43
	v_fma_f32 v0, -v45, v64, v42
	v_fma_f32 v42, -v44, v65, v99
	v_add_f32_e32 v43, v0, v42
	s_waitcnt lgkmcnt(0)
	v_fma_f32 v0, -v45, v154, v78
	ds_read_b128 v[74:77], v110 offset:7616
	ds_read_b128 v[82:85], v110 offset:7632
	ds_read_b128 v[90:93], v110 offset:7648
	ds_read_b128 v[126:129], v110 offset:7664
	ds_read_b128 v[134:137], v110 offset:7680
	ds_read_b128 v[142:145], v110 offset:7696
	ds_read_b128 v[150:153], v110 offset:7712
	v_fma_f32 v42, -v44, v155, v79
	v_fma_f32 v0, -v43, v156, v0
	v_add_f32_e32 v42, v42, v0
	ds_read_b128 v[78:81], v110 offset:7888
	ds_read_b128 v[86:89], v110 offset:7904
	ds_read_b128 v[94:97], v110 offset:7920
	ds_read_b128 v[130:133], v110 offset:7936
	ds_read_b128 v[138:141], v110 offset:7952
	ds_read_b128 v[146:149], v110 offset:7968
	ds_read_b128 v[154:157], v110 offset:7984
	ds_read_b32 v0, v110 offset:8000
	s_waitcnt lgkmcnt(14)
	v_fma_f32 v40, -v2, v74, v40
	v_fma_f32 v61, -v73, v75, 0
	s_waitcnt lgkmcnt(7)
	v_fma_f32 v41, -v2, v78, v41
	v_fma_f32 v40, -v72, v76, v40
	v_fma_f32 v61, -v70, v77, v61
	v_fma_f32 v41, -v72, v80, v41
	v_fma_f32 v40, -v71, v82, v40
	v_fma_f32 v61, -v67, v83, v61
	s_waitcnt lgkmcnt(6)
	v_fma_f32 v41, -v71, v86, v41
	v_fma_f32 v40, -v66, v84, v40
	v_fma_f32 v61, -v56, v85, v61
	v_fma_f32 v41, -v66, v88, v41
	v_fma_f32 v40, -v62, v90, v40
	v_fma_f32 v61, -v57, v91, v61
	s_waitcnt lgkmcnt(5)
	v_fma_f32 v41, -v62, v94, v41
	v_fma_f32 v40, -v51, v92, v40
	v_fma_f32 v61, -v3, v93, v61
	v_fma_f32 v41, -v51, v96, v41
	v_fma_f32 v40, -v60, v126, v40
	v_fma_f32 v61, -v59, v127, v61
	s_waitcnt lgkmcnt(4)
	v_fma_f32 v41, -v60, v130, v41
	v_fma_f32 v40, -v58, v128, v40
	v_fma_f32 v61, -v50, v129, v61
	v_fma_f32 v41, -v58, v132, v41
	v_fma_f32 v40, -v55, v134, v40
	v_fma_f32 v61, -v54, v135, v61
	s_waitcnt lgkmcnt(3)
	v_fma_f32 v41, -v55, v138, v41
	v_fma_f32 v40, -v53, v136, v40
	v_fma_f32 v61, -v52, v137, v61
	v_fma_f32 v41, -v53, v140, v41
	v_fma_f32 v40, -v49, v142, v40
	v_fma_f32 v61, -v48, v143, v61
	s_waitcnt lgkmcnt(2)
	v_fma_f32 v41, -v49, v146, v41
	v_fma_f32 v40, -v47, v144, v40
	v_fma_f32 v61, -v46, v145, v61
	v_fma_f32 v41, -v47, v148, v41
	v_fma_f32 v40, -v45, v150, v40
	v_fma_f32 v61, -v44, v151, v61
	s_waitcnt lgkmcnt(1)
	v_fma_f32 v41, -v45, v154, v41
	v_fma_f32 v40, -v43, v152, v40
	v_fma_f32 v61, -v42, v153, v61
	ds_read_b128 v[74:77], v110 offset:8160
	ds_read_b128 v[82:85], v110 offset:8176
	ds_read_b128 v[90:93], v110 offset:8192
	ds_read_b128 v[126:129], v110 offset:8208
	ds_read_b128 v[134:137], v110 offset:8224
	ds_read_b128 v[142:145], v110 offset:8240
	ds_read_b128 v[150:153], v110 offset:8256
	ds_read_b64 v[64:65], v110 offset:8272
	v_fma_f32 v63, -v73, v79, 0
	v_fma_f32 v98, -v43, v156, v41
	s_waitcnt lgkmcnt(7)
	v_fma_f32 v41, -v73, v75, 0
	v_fma_f32 v63, -v70, v81, v63
	v_fma_f32 v41, -v70, v77, v41
	v_fma_f32 v63, -v67, v87, v63
	s_waitcnt lgkmcnt(6)
	v_fma_f32 v41, -v67, v83, v41
	v_fma_f32 v63, -v56, v89, v63
	v_fma_f32 v41, -v56, v85, v41
	v_fma_f32 v63, -v57, v95, v63
	s_waitcnt lgkmcnt(5)
	v_fma_f32 v41, -v57, v91, v41
	v_fma_f32 v63, -v3, v97, v63
	v_fma_f32 v41, -v3, v93, v41
	v_fma_f32 v63, -v59, v131, v63
	s_waitcnt lgkmcnt(4)
	v_fma_f32 v41, -v59, v127, v41
	v_fma_f32 v63, -v50, v133, v63
	v_fma_f32 v41, -v50, v129, v41
	v_fma_f32 v63, -v54, v139, v63
	s_waitcnt lgkmcnt(3)
	v_fma_f32 v41, -v54, v135, v41
	v_fma_f32 v63, -v52, v141, v63
	v_fma_f32 v41, -v52, v137, v41
	v_fma_f32 v63, -v48, v147, v63
	s_waitcnt lgkmcnt(2)
	v_fma_f32 v41, -v48, v143, v41
	v_fma_f32 v63, -v46, v149, v63
	v_fma_f32 v41, -v46, v145, v41
	v_fma_f32 v63, -v44, v155, v63
	s_waitcnt lgkmcnt(1)
	v_fma_f32 v41, -v44, v151, v41
	v_fma_f32 v63, -v42, v157, v63
	ds_read_b128 v[78:81], v110 offset:8432
	ds_read_b128 v[86:89], v110 offset:8448
	ds_read_b128 v[94:97], v110 offset:8464
	ds_read_b128 v[130:133], v110 offset:8480
	ds_read_b128 v[138:141], v110 offset:8496
	ds_read_b128 v[146:149], v110 offset:8512
	ds_read_b128 v[154:157], v110 offset:8528
	ds_read_b96 v[162:164], v110 offset:8544
	v_fma_f32 v99, -v42, v153, v41
	s_waitcnt lgkmcnt(7)
	v_fma_f32 v41, -v73, v79, 0
	v_fma_f32 v41, -v70, v81, v41
	v_fma_f32 v38, -v2, v74, v38
	s_waitcnt lgkmcnt(6)
	v_fma_f32 v41, -v67, v87, v41
	v_fma_f32 v38, -v72, v76, v38
	v_fma_f32 v39, -v2, v78, v39
	v_fma_f32 v41, -v56, v89, v41
	v_fma_f32 v38, -v71, v82, v38
	v_fma_f32 v39, -v72, v80, v39
	s_waitcnt lgkmcnt(5)
; DI void dn_solve_core(float (&x)[64], lf_t Ad) {
;     float4 cur[16], nxt[16];
;     cur[0] = *(const float4*)(Ad + 68);
; #pragma unroll
;     for (int pi = 1; pi < 64; ++pi) {
;         if (pi + 1 < 64) {
; #pragma unroll
;             for (int g4 = 0; g4 < (pi + 4) / 4; ++g4) nxt[g4] = *(const float4*)(Ad + (pi + 1) * 68 + 4 * g4);
;         }
;         float a = x[pi], a2 = 0.f;
; #pragma unroll
;         for (int g4 = 0; g4 < (pi + 3) / 4; ++g4) { const float4 av = cur[g4];
;             if (4 * g4 + 0 < pi) a -= av.x * x[4 * g4 + 0];
;             if (4 * g4 + 1 < pi) a2 -= av.y * x[4 * g4 + 1];
;             if (4 * g4 + 2 < pi) a -= av.z * x[4 * g4 + 2];
;             if (4 * g4 + 3 < pi) a2 -= av.w * x[4 * g4 + 3]; }
;         x[pi] = a + a2;
;         asm volatile("" ::: "memory");
; #pragma unroll
;         for (int g4 = 0; g4 < (pi + 4) / 4; ++g4) cur[g4] = nxt[g4];
;     }
; }
	v_fma_f32 v41, -v57, v95, v41
	v_fma_f32 v38, -v66, v84, v38
	v_fma_f32 v39, -v71, v86, v39
	v_fma_f32 v41, -v3, v97, v41
	v_fma_f32 v38, -v62, v90, v38
	v_fma_f32 v39, -v66, v88, v39
	s_waitcnt lgkmcnt(4)
	v_fma_f32 v41, -v59, v131, v41
	v_fma_f32 v38, -v51, v92, v38
	v_fma_f32 v39, -v62, v94, v39
	v_fma_f32 v41, -v50, v133, v41
	v_fma_f32 v38, -v60, v126, v38
	v_fma_f32 v39, -v51, v96, v39
	s_waitcnt lgkmcnt(3)
	v_fma_f32 v41, -v54, v139, v41
	v_fma_f32 v38, -v58, v128, v38
	v_fma_f32 v39, -v60, v130, v39
	v_fma_f32 v41, -v52, v141, v41
	v_fma_f32 v38, -v55, v134, v38
	v_fma_f32 v39, -v58, v132, v39
	s_waitcnt lgkmcnt(2)
	v_fma_f32 v41, -v48, v147, v41
	v_fma_f32 v38, -v53, v136, v38
	v_fma_f32 v39, -v55, v138, v39
	v_fma_f32 v41, -v46, v149, v41
	v_fma_f32 v38, -v49, v142, v38
	v_fma_f32 v39, -v53, v140, v39
	s_waitcnt lgkmcnt(1)
	v_fma_f32 v41, -v44, v155, v41
	v_fma_f32 v38, -v47, v144, v38
	v_fma_f32 v39, -v49, v146, v39
	v_fma_f32 v79, -v42, v157, v41
	v_add_f32_e32 v41, v40, v61
	v_fma_f32 v38, -v45, v150, v38
	v_fma_f32 v39, -v47, v148, v39
	v_fma_f32 v0, -v41, v0, v98
	v_fma_f32 v38, -v43, v152, v38
	v_fma_f32 v39, -v45, v154, v39
	v_add_f32_e32 v40, v63, v0
	v_fma_f32 v78, -v43, v156, v39
	v_fma_f32 v0, -v41, v64, v38
	v_fma_f32 v38, -v40, v65, v99
	v_add_f32_e32 v39, v0, v38
	s_waitcnt lgkmcnt(0)
	v_fma_f32 v0, -v41, v162, v78
	ds_read_b128 v[74:77], v110 offset:8704
	ds_read_b128 v[82:85], v110 offset:8720
	ds_read_b128 v[90:93], v110 offset:8736
	ds_read_b128 v[126:129], v110 offset:8752
	ds_read_b128 v[134:137], v110 offset:8768
	ds_read_b128 v[142:145], v110 offset:8784
	ds_read_b128 v[150:153], v110 offset:8800
	ds_read_b128 v[158:161], v110 offset:8816
	v_fma_f32 v38, -v40, v163, v79
	v_fma_f32 v0, -v39, v164, v0
	v_add_f32_e32 v38, v38, v0
	ds_read_b128 v[78:81], v110 offset:8976
	ds_read_b128 v[86:89], v110 offset:8992
	ds_read_b128 v[94:97], v110 offset:9008
	ds_read_b128 v[130:133], v110 offset:9024
	ds_read_b128 v[138:141], v110 offset:9040
	ds_read_b128 v[146:149], v110 offset:9056
	ds_read_b128 v[154:157], v110 offset:9072
	ds_read_b128 v[162:165], v110 offset:9088
	ds_read_b32 v0, v110 offset:9104
	s_waitcnt lgkmcnt(14)
	v_fma_f32 v36, -v2, v74, v36
	v_fma_f32 v61, -v73, v75, 0
	s_waitcnt lgkmcnt(8)
	v_fma_f32 v37, -v2, v78, v37
	v_fma_f32 v36, -v72, v76, v36
	v_fma_f32 v61, -v70, v77, v61
	v_fma_f32 v37, -v72, v80, v37
	v_fma_f32 v36, -v71, v82, v36
	v_fma_f32 v61, -v67, v83, v61
	s_waitcnt lgkmcnt(7)
	v_fma_f32 v37, -v71, v86, v37
	v_fma_f32 v36, -v66, v84, v36
	v_fma_f32 v61, -v56, v85, v61
	v_fma_f32 v37, -v66, v88, v37
	v_fma_f32 v36, -v62, v90, v36
	v_fma_f32 v61, -v57, v91, v61
	s_waitcnt lgkmcnt(6)
	v_fma_f32 v37, -v62, v94, v37
	v_fma_f32 v36, -v51, v92, v36
	v_fma_f32 v61, -v3, v93, v61
	v_fma_f32 v37, -v51, v96, v37
	v_fma_f32 v36, -v60, v126, v36
	v_fma_f32 v61, -v59, v127, v61
	s_waitcnt lgkmcnt(5)
	v_fma_f32 v37, -v60, v130, v37
	v_fma_f32 v36, -v58, v128, v36
	v_fma_f32 v61, -v50, v129, v61
	v_fma_f32 v37, -v58, v132, v37
	v_fma_f32 v36, -v55, v134, v36
	v_fma_f32 v61, -v54, v135, v61
	s_waitcnt lgkmcnt(4)
	v_fma_f32 v37, -v55, v138, v37
	v_fma_f32 v36, -v53, v136, v36
	v_fma_f32 v61, -v52, v137, v61
	v_fma_f32 v37, -v53, v140, v37
	v_fma_f32 v36, -v49, v142, v36
	v_fma_f32 v61, -v48, v143, v61
	s_waitcnt lgkmcnt(3)
	v_fma_f32 v37, -v49, v146, v37
	v_fma_f32 v36, -v47, v144, v36
	v_fma_f32 v61, -v46, v145, v61
	v_fma_f32 v37, -v47, v148, v37
	v_fma_f32 v36, -v45, v150, v36
	v_fma_f32 v61, -v44, v151, v61
	s_waitcnt lgkmcnt(2)
	v_fma_f32 v37, -v45, v154, v37
	v_fma_f32 v36, -v43, v152, v36
	v_fma_f32 v61, -v42, v153, v61
	v_fma_f32 v37, -v43, v156, v37
	v_fma_f32 v36, -v41, v158, v36
	v_fma_f32 v61, -v40, v159, v61
	s_waitcnt lgkmcnt(1)
	v_fma_f32 v37, -v41, v162, v37
	v_fma_f32 v36, -v39, v160, v36
	v_fma_f32 v61, -v38, v161, v61
	ds_read_b128 v[74:77], v110 offset:9248
	ds_read_b128 v[82:85], v110 offset:9264
	ds_read_b128 v[90:93], v110 offset:9280
	ds_read_b128 v[126:129], v110 offset:9296
	ds_read_b128 v[134:137], v110 offset:9312
	ds_read_b128 v[142:145], v110 offset:9328
	ds_read_b128 v[150:153], v110 offset:9344
	ds_read_b128 v[158:161], v110 offset:9360
	ds_read_b64 v[64:65], v110 offset:9376
	v_fma_f32 v63, -v73, v79, 0
	v_fma_f32 v98, -v39, v164, v37
	s_waitcnt lgkmcnt(8)
	v_fma_f32 v37, -v73, v75, 0
	v_fma_f32 v63, -v70, v81, v63
	v_fma_f32 v37, -v70, v77, v37
	v_fma_f32 v63, -v67, v87, v63
	s_waitcnt lgkmcnt(7)
	v_fma_f32 v37, -v67, v83, v37
	v_fma_f32 v63, -v56, v89, v63
	v_fma_f32 v37, -v56, v85, v37
	v_fma_f32 v63, -v57, v95, v63
	s_waitcnt lgkmcnt(6)
	v_fma_f32 v37, -v57, v91, v37
	v_fma_f32 v63, -v3, v97, v63
	v_fma_f32 v37, -v3, v93, v37
	v_fma_f32 v63, -v59, v131, v63
	s_waitcnt lgkmcnt(5)
	v_fma_f32 v37, -v59, v127, v37
	v_fma_f32 v63, -v50, v133, v63
	v_fma_f32 v37, -v50, v129, v37
	v_fma_f32 v63, -v54, v139, v63
	s_waitcnt lgkmcnt(4)
	v_fma_f32 v37, -v54, v135, v37
	v_fma_f32 v63, -v52, v141, v63
	v_fma_f32 v37, -v52, v137, v37
	v_fma_f32 v63, -v48, v147, v63
	s_waitcnt lgkmcnt(3)
	v_fma_f32 v37, -v48, v143, v37
	v_fma_f32 v63, -v46, v149, v63
	v_fma_f32 v37, -v46, v145, v37
	v_fma_f32 v63, -v44, v155, v63
	s_waitcnt lgkmcnt(2)
	v_fma_f32 v37, -v44, v151, v37
	v_fma_f32 v63, -v42, v157, v63
	v_fma_f32 v37, -v42, v153, v37
	v_fma_f32 v63, -v40, v163, v63
	s_waitcnt lgkmcnt(1)
	v_fma_f32 v37, -v40, v159, v37
	v_fma_f32 v63, -v38, v165, v63
	ds_read_b128 v[78:81], v110 offset:9520
	ds_read_b128 v[86:89], v110 offset:9536
	ds_read_b128 v[94:97], v110 offset:9552
	ds_read_b128 v[130:133], v110 offset:9568
	ds_read_b128 v[138:141], v110 offset:9584
	ds_read_b128 v[146:149], v110 offset:9600
	ds_read_b128 v[154:157], v110 offset:9616
	ds_read_b128 v[162:165], v110 offset:9632
	ds_read_b96 v[170:172], v110 offset:9648
	v_fma_f32 v99, -v38, v161, v37
	s_waitcnt lgkmcnt(8)
; DI void dn_solve_core(float (&x)[64], lf_t Ad) {
;     float4 cur[16], nxt[16];
;     cur[0] = *(const float4*)(Ad + 68);
; #pragma unroll
;     for (int pi = 1; pi < 64; ++pi) {
;         if (pi + 1 < 64) {
; #pragma unroll
;             for (int g4 = 0; g4 < (pi + 4) / 4; ++g4) nxt[g4] = *(const float4*)(Ad + (pi + 1) * 68 + 4 * g4);
;         }
;         float a = x[pi], a2 = 0.f;
; #pragma unroll
;         for (int g4 = 0; g4 < (pi + 3) / 4; ++g4) { const float4 av = cur[g4];
;             if (4 * g4 + 0 < pi) a -= av.x * x[4 * g4 + 0];
;             if (4 * g4 + 1 < pi) a2 -= av.y * x[4 * g4 + 1];
;             if (4 * g4 + 2 < pi) a -= av.z * x[4 * g4 + 2];
;             if (4 * g4 + 3 < pi) a2 -= av.w * x[4 * g4 + 3]; }
;         x[pi] = a + a2;
;         asm volatile("" ::: "memory");
; #pragma unroll
;         for (int g4 = 0; g4 < (pi + 4) / 4; ++g4) cur[g4] = nxt[g4];
;     }
; }
	v_fma_f32 v37, -v73, v79, 0
	v_fma_f32 v37, -v70, v81, v37
	v_fma_f32 v34, -v2, v74, v34
	s_waitcnt lgkmcnt(7)
	v_fma_f32 v37, -v67, v87, v37
	v_fma_f32 v34, -v72, v76, v34
	v_fma_f32 v35, -v2, v78, v35
	v_fma_f32 v37, -v56, v89, v37
	v_fma_f32 v34, -v71, v82, v34
	v_fma_f32 v35, -v72, v80, v35
	s_waitcnt lgkmcnt(6)
	v_fma_f32 v37, -v57, v95, v37
	v_fma_f32 v34, -v66, v84, v34
	v_fma_f32 v35, -v71, v86, v35
	v_fma_f32 v37, -v3, v97, v37
	v_fma_f32 v34, -v62, v90, v34
	v_fma_f32 v35, -v66, v88, v35
	s_waitcnt lgkmcnt(5)
	v_fma_f32 v37, -v59, v131, v37
	v_fma_f32 v34, -v51, v92, v34
	v_fma_f32 v35, -v62, v94, v35
	v_fma_f32 v37, -v50, v133, v37
	v_fma_f32 v34, -v60, v126, v34
	v_fma_f32 v35, -v51, v96, v35
	s_waitcnt lgkmcnt(4)
	v_fma_f32 v37, -v54, v139, v37
	v_fma_f32 v34, -v58, v128, v34
	v_fma_f32 v35, -v60, v130, v35
	v_fma_f32 v37, -v52, v141, v37
	v_fma_f32 v34, -v55, v134, v34
	v_fma_f32 v35, -v58, v132, v35
	s_waitcnt lgkmcnt(3)
	v_fma_f32 v37, -v48, v147, v37
	v_fma_f32 v34, -v53, v136, v34
	v_fma_f32 v35, -v55, v138, v35
	v_fma_f32 v37, -v46, v149, v37
	v_fma_f32 v34, -v49, v142, v34
	v_fma_f32 v35, -v53, v140, v35
	s_waitcnt lgkmcnt(2)
	v_fma_f32 v37, -v44, v155, v37
	v_fma_f32 v34, -v47, v144, v34
	v_fma_f32 v35, -v49, v146, v35
	v_fma_f32 v37, -v42, v157, v37
	v_fma_f32 v34, -v45, v150, v34
	v_fma_f32 v35, -v47, v148, v35
	s_waitcnt lgkmcnt(1)
	v_fma_f32 v37, -v40, v163, v37
	v_fma_f32 v34, -v43, v152, v34
	v_fma_f32 v35, -v45, v154, v35
	v_fma_f32 v79, -v38, v165, v37
	v_add_f32_e32 v37, v36, v61
	v_fma_f32 v34, -v41, v158, v34
	v_fma_f32 v35, -v43, v156, v35
	v_fma_f32 v0, -v37, v0, v98
	v_fma_f32 v34, -v39, v160, v34
	v_fma_f32 v35, -v41, v162, v35
	v_add_f32_e32 v36, v63, v0
	v_fma_f32 v78, -v39, v164, v35
	v_fma_f32 v0, -v37, v64, v34
	v_fma_f32 v34, -v36, v65, v99
	v_add_f32_e32 v35, v0, v34
	s_waitcnt lgkmcnt(0)
	v_fma_f32 v0, -v37, v170, v78
	ds_read_b128 v[74:77], v110 offset:9792
	ds_read_b128 v[82:85], v110 offset:9808
	ds_read_b128 v[90:93], v110 offset:9824
	ds_read_b128 v[126:129], v110 offset:9840
	ds_read_b128 v[134:137], v110 offset:9856
	ds_read_b128 v[142:145], v110 offset:9872
	ds_read_b128 v[150:153], v110 offset:9888
	ds_read_b128 v[158:161], v110 offset:9904
	ds_read_b128 v[166:169], v110 offset:9920
	v_fma_f32 v34, -v36, v171, v79
	v_fma_f32 v0, -v35, v172, v0
	v_add_f32_e32 v34, v34, v0
	ds_read_b128 v[78:81], v110 offset:10064
	ds_read_b128 v[86:89], v110 offset:10080
	ds_read_b128 v[94:97], v110 offset:10096
	ds_read_b128 v[130:133], v110 offset:10112
	ds_read_b128 v[138:141], v110 offset:10128
	ds_read_b128 v[146:149], v110 offset:10144
	ds_read_b128 v[154:157], v110 offset:10160
	ds_read_b128 v[162:165], v110 offset:10176
	ds_read_b128 v[170:173], v110 offset:10192
	ds_read_b32 v0, v110 offset:10208
	s_waitcnt lgkmcnt(14)
	v_fma_f32 v32, -v2, v74, v32
	v_fma_f32 v61, -v73, v75, 0
	s_waitcnt lgkmcnt(9)
	v_fma_f32 v33, -v2, v78, v33
	v_fma_f32 v32, -v72, v76, v32
	v_fma_f32 v61, -v70, v77, v61
	v_fma_f32 v33, -v72, v80, v33
	v_fma_f32 v32, -v71, v82, v32
	v_fma_f32 v61, -v67, v83, v61
	s_waitcnt lgkmcnt(8)
	v_fma_f32 v33, -v71, v86, v33
	v_fma_f32 v32, -v66, v84, v32
	v_fma_f32 v61, -v56, v85, v61
	v_fma_f32 v33, -v66, v88, v33
	v_fma_f32 v32, -v62, v90, v32
	v_fma_f32 v61, -v57, v91, v61
	s_waitcnt lgkmcnt(7)
	v_fma_f32 v33, -v62, v94, v33
	v_fma_f32 v32, -v51, v92, v32
	v_fma_f32 v61, -v3, v93, v61
	v_fma_f32 v33, -v51, v96, v33
	v_fma_f32 v32, -v60, v126, v32
	v_fma_f32 v61, -v59, v127, v61
	s_waitcnt lgkmcnt(6)
	v_fma_f32 v33, -v60, v130, v33
	v_fma_f32 v32, -v58, v128, v32
	v_fma_f32 v61, -v50, v129, v61
	v_fma_f32 v33, -v58, v132, v33
	v_fma_f32 v32, -v55, v134, v32
	v_fma_f32 v61, -v54, v135, v61
	s_waitcnt lgkmcnt(5)
	v_fma_f32 v33, -v55, v138, v33
	v_fma_f32 v32, -v53, v136, v32
	v_fma_f32 v61, -v52, v137, v61
	v_fma_f32 v33, -v53, v140, v33
	v_fma_f32 v32, -v49, v142, v32
	v_fma_f32 v61, -v48, v143, v61
	s_waitcnt lgkmcnt(4)
	v_fma_f32 v33, -v49, v146, v33
	v_fma_f32 v32, -v47, v144, v32
	v_fma_f32 v61, -v46, v145, v61
	v_fma_f32 v33, -v47, v148, v33
	v_fma_f32 v32, -v45, v150, v32
	v_fma_f32 v61, -v44, v151, v61
	s_waitcnt lgkmcnt(3)
	v_fma_f32 v33, -v45, v154, v33
	v_fma_f32 v32, -v43, v152, v32
	v_fma_f32 v61, -v42, v153, v61
	v_fma_f32 v33, -v43, v156, v33
	v_fma_f32 v32, -v41, v158, v32
	v_fma_f32 v61, -v40, v159, v61
	s_waitcnt lgkmcnt(2)
	v_fma_f32 v33, -v41, v162, v33
	v_fma_f32 v32, -v39, v160, v32
	v_fma_f32 v61, -v38, v161, v61
	v_fma_f32 v33, -v39, v164, v33
	v_fma_f32 v32, -v37, v166, v32
	v_fma_f32 v61, -v36, v167, v61
	s_waitcnt lgkmcnt(1)
	v_fma_f32 v33, -v37, v170, v33
	v_fma_f32 v32, -v35, v168, v32
	v_fma_f32 v61, -v34, v169, v61
	ds_read_b128 v[74:77], v110 offset:10336
	ds_read_b128 v[82:85], v110 offset:10352
	ds_read_b128 v[90:93], v110 offset:10368
	ds_read_b128 v[126:129], v110 offset:10384
	ds_read_b128 v[134:137], v110 offset:10400
	ds_read_b128 v[142:145], v110 offset:10416
	ds_read_b128 v[150:153], v110 offset:10432
	ds_read_b128 v[158:161], v110 offset:10448
	ds_read_b128 v[166:169], v110 offset:10464
	ds_read_b64 v[64:65], v110 offset:10480
	v_fma_f32 v63, -v73, v79, 0
	v_fma_f32 v98, -v35, v172, v33
	s_waitcnt lgkmcnt(9)
	v_fma_f32 v33, -v73, v75, 0
	v_fma_f32 v63, -v70, v81, v63
	v_fma_f32 v33, -v70, v77, v33
	v_fma_f32 v63, -v67, v87, v63
	s_waitcnt lgkmcnt(8)
	v_fma_f32 v33, -v67, v83, v33
	v_fma_f32 v63, -v56, v89, v63
	v_fma_f32 v33, -v56, v85, v33
	v_fma_f32 v63, -v57, v95, v63
	s_waitcnt lgkmcnt(7)
	v_fma_f32 v33, -v57, v91, v33
	v_fma_f32 v63, -v3, v97, v63
	v_fma_f32 v33, -v3, v93, v33
	v_fma_f32 v63, -v59, v131, v63
	s_waitcnt lgkmcnt(6)
; DI void dn_solve_core(float (&x)[64], lf_t Ad) {
;     float4 cur[16], nxt[16];
;     cur[0] = *(const float4*)(Ad + 68);
; #pragma unroll
;     for (int pi = 1; pi < 64; ++pi) {
;         if (pi + 1 < 64) {
; #pragma unroll
;             for (int g4 = 0; g4 < (pi + 4) / 4; ++g4) nxt[g4] = *(const float4*)(Ad + (pi + 1) * 68 + 4 * g4);
;         }
;         float a = x[pi], a2 = 0.f;
; #pragma unroll
;         for (int g4 = 0; g4 < (pi + 3) / 4; ++g4) { const float4 av = cur[g4];
;             if (4 * g4 + 0 < pi) a -= av.x * x[4 * g4 + 0];
;             if (4 * g4 + 1 < pi) a2 -= av.y * x[4 * g4 + 1];
;             if (4 * g4 + 2 < pi) a -= av.z * x[4 * g4 + 2];
;             if (4 * g4 + 3 < pi) a2 -= av.w * x[4 * g4 + 3]; }
;         x[pi] = a + a2;
;         asm volatile("" ::: "memory");
; #pragma unroll
;         for (int g4 = 0; g4 < (pi + 4) / 4; ++g4) cur[g4] = nxt[g4];
;     }
; }
	v_fma_f32 v33, -v59, v127, v33
	v_fma_f32 v63, -v50, v133, v63
	v_fma_f32 v33, -v50, v129, v33
	v_fma_f32 v63, -v54, v139, v63
	s_waitcnt lgkmcnt(5)
	v_fma_f32 v33, -v54, v135, v33
	v_fma_f32 v63, -v52, v141, v63
	v_fma_f32 v33, -v52, v137, v33
	v_fma_f32 v63, -v48, v147, v63
	s_waitcnt lgkmcnt(4)
	v_fma_f32 v33, -v48, v143, v33
	v_fma_f32 v63, -v46, v149, v63
	v_fma_f32 v33, -v46, v145, v33
	v_fma_f32 v63, -v44, v155, v63
	s_waitcnt lgkmcnt(3)
	v_fma_f32 v33, -v44, v151, v33
	v_fma_f32 v63, -v42, v157, v63
	v_fma_f32 v33, -v42, v153, v33
	v_fma_f32 v63, -v40, v163, v63
	s_waitcnt lgkmcnt(2)
	v_fma_f32 v33, -v40, v159, v33
	v_fma_f32 v63, -v38, v165, v63
	v_fma_f32 v33, -v38, v161, v33
	v_fma_f32 v63, -v36, v171, v63
	s_waitcnt lgkmcnt(1)
	v_fma_f32 v33, -v36, v167, v33
	v_fma_f32 v63, -v34, v173, v63
	ds_read_b128 v[78:81], v110 offset:10608
	ds_read_b128 v[86:89], v110 offset:10624
	ds_read_b128 v[94:97], v110 offset:10640
	ds_read_b128 v[130:133], v110 offset:10656
	ds_read_b128 v[138:141], v110 offset:10672
	ds_read_b128 v[146:149], v110 offset:10688
	ds_read_b128 v[154:157], v110 offset:10704
	ds_read_b128 v[162:165], v110 offset:10720
	ds_read_b128 v[170:173], v110 offset:10736
	ds_read_b96 v[178:180], v110 offset:10752
	v_fma_f32 v99, -v34, v169, v33
	s_waitcnt lgkmcnt(9)
	v_fma_f32 v33, -v73, v79, 0
	v_fma_f32 v33, -v70, v81, v33
	v_fma_f32 v30, -v2, v74, v30
	s_waitcnt lgkmcnt(8)
	v_fma_f32 v33, -v67, v87, v33
	v_fma_f32 v30, -v72, v76, v30
	v_fma_f32 v31, -v2, v78, v31
	v_fma_f32 v33, -v56, v89, v33
	v_fma_f32 v30, -v71, v82, v30
	v_fma_f32 v31, -v72, v80, v31
	s_waitcnt lgkmcnt(7)
	v_fma_f32 v33, -v57, v95, v33
	v_fma_f32 v30, -v66, v84, v30
	v_fma_f32 v31, -v71, v86, v31
	v_fma_f32 v33, -v3, v97, v33
	v_fma_f32 v30, -v62, v90, v30
	v_fma_f32 v31, -v66, v88, v31
	s_waitcnt lgkmcnt(6)
	v_fma_f32 v33, -v59, v131, v33
	v_fma_f32 v30, -v51, v92, v30
	v_fma_f32 v31, -v62, v94, v31
	v_fma_f32 v33, -v50, v133, v33
	v_fma_f32 v30, -v60, v126, v30
	v_fma_f32 v31, -v51, v96, v31
	s_waitcnt lgkmcnt(5)
	v_fma_f32 v33, -v54, v139, v33
	v_fma_f32 v30, -v58, v128, v30
	v_fma_f32 v31, -v60, v130, v31
	v_fma_f32 v33, -v52, v141, v33
	v_fma_f32 v30, -v55, v134, v30
	v_fma_f32 v31, -v58, v132, v31
	s_waitcnt lgkmcnt(4)
	v_fma_f32 v33, -v48, v147, v33
	v_fma_f32 v30, -v53, v136, v30
	v_fma_f32 v31, -v55, v138, v31
	v_fma_f32 v33, -v46, v149, v33
	v_fma_f32 v30, -v49, v142, v30
	v_fma_f32 v31, -v53, v140, v31
	s_waitcnt lgkmcnt(3)
	v_fma_f32 v33, -v44, v155, v33
	v_fma_f32 v30, -v47, v144, v30
	v_fma_f32 v31, -v49, v146, v31
	v_fma_f32 v33, -v42, v157, v33
	v_fma_f32 v30, -v45, v150, v30
	v_fma_f32 v31, -v47, v148, v31
	s_waitcnt lgkmcnt(2)
	v_fma_f32 v33, -v40, v163, v33
	v_fma_f32 v30, -v43, v152, v30
	v_fma_f32 v31, -v45, v154, v31
	v_fma_f32 v33, -v38, v165, v33
	v_fma_f32 v30, -v41, v158, v30
	v_fma_f32 v31, -v43, v156, v31
	s_waitcnt lgkmcnt(1)
	v_fma_f32 v33, -v36, v171, v33
	v_fma_f32 v30, -v39, v160, v30
	v_fma_f32 v31, -v41, v162, v31
	v_fma_f32 v79, -v34, v173, v33
	v_add_f32_e32 v33, v32, v61
	v_fma_f32 v30, -v37, v166, v30
	v_fma_f32 v31, -v39, v164, v31
	v_fma_f32 v0, -v33, v0, v98
	v_fma_f32 v30, -v35, v168, v30
	v_fma_f32 v31, -v37, v170, v31
	v_add_f32_e32 v32, v63, v0
	v_fma_f32 v78, -v35, v172, v31
	v_fma_f32 v0, -v33, v64, v30
	v_fma_f32 v30, -v32, v65, v99
	v_add_f32_e32 v31, v0, v30
	s_waitcnt lgkmcnt(0)
	v_fma_f32 v0, -v33, v178, v78
	ds_read_b128 v[74:77], v110 offset:10880
	ds_read_b128 v[82:85], v110 offset:10896
	ds_read_b128 v[90:93], v110 offset:10912
	ds_read_b128 v[126:129], v110 offset:10928
	ds_read_b128 v[134:137], v110 offset:10944
	ds_read_b128 v[142:145], v110 offset:10960
	ds_read_b128 v[150:153], v110 offset:10976
	ds_read_b128 v[158:161], v110 offset:10992
	ds_read_b128 v[166:169], v110 offset:11008
	ds_read_b128 v[174:177], v110 offset:11024
	v_fma_f32 v30, -v32, v179, v79
	v_fma_f32 v0, -v31, v180, v0
	v_add_f32_e32 v30, v30, v0
	ds_read_b128 v[78:81], v110 offset:11152
	ds_read_b128 v[86:89], v110 offset:11168
	ds_read_b128 v[94:97], v110 offset:11184
	ds_read_b128 v[130:133], v110 offset:11200
	ds_read_b128 v[138:141], v110 offset:11216
	ds_read_b128 v[146:149], v110 offset:11232
	ds_read_b128 v[154:157], v110 offset:11248
	ds_read_b128 v[162:165], v110 offset:11264
	ds_read_b128 v[170:173], v110 offset:11280
	ds_read_b128 v[178:181], v110 offset:11296
	ds_read_b32 v0, v110 offset:11312
	s_waitcnt lgkmcnt(14)
	v_fma_f32 v28, -v2, v74, v28
	v_fma_f32 v61, -v73, v75, 0
	s_waitcnt lgkmcnt(10)
	v_fma_f32 v29, -v2, v78, v29
	v_fma_f32 v28, -v72, v76, v28
	v_fma_f32 v61, -v70, v77, v61
	v_fma_f32 v29, -v72, v80, v29
	v_fma_f32 v28, -v71, v82, v28
	v_fma_f32 v61, -v67, v83, v61
	s_waitcnt lgkmcnt(9)
	v_fma_f32 v29, -v71, v86, v29
	v_fma_f32 v28, -v66, v84, v28
	v_fma_f32 v61, -v56, v85, v61
	v_fma_f32 v29, -v66, v88, v29
	v_fma_f32 v28, -v62, v90, v28
	v_fma_f32 v61, -v57, v91, v61
	s_waitcnt lgkmcnt(8)
	v_fma_f32 v29, -v62, v94, v29
	v_fma_f32 v28, -v51, v92, v28
	v_fma_f32 v61, -v3, v93, v61
	v_fma_f32 v29, -v51, v96, v29
	v_fma_f32 v28, -v60, v126, v28
	v_fma_f32 v61, -v59, v127, v61
	s_waitcnt lgkmcnt(7)
	v_fma_f32 v29, -v60, v130, v29
	v_fma_f32 v28, -v58, v128, v28
	v_fma_f32 v61, -v50, v129, v61
	v_fma_f32 v29, -v58, v132, v29
	v_fma_f32 v28, -v55, v134, v28
	v_fma_f32 v61, -v54, v135, v61
	s_waitcnt lgkmcnt(6)
	v_fma_f32 v29, -v55, v138, v29
	v_fma_f32 v28, -v53, v136, v28
	v_fma_f32 v61, -v52, v137, v61
	v_fma_f32 v29, -v53, v140, v29
	v_fma_f32 v28, -v49, v142, v28
	v_fma_f32 v61, -v48, v143, v61
	s_waitcnt lgkmcnt(5)
; DI void dn_solve_core(float (&x)[64], lf_t Ad) {
;     float4 cur[16], nxt[16];
;     cur[0] = *(const float4*)(Ad + 68);
; #pragma unroll
;     for (int pi = 1; pi < 64; ++pi) {
;         if (pi + 1 < 64) {
; #pragma unroll
;             for (int g4 = 0; g4 < (pi + 4) / 4; ++g4) nxt[g4] = *(const float4*)(Ad + (pi + 1) * 68 + 4 * g4);
;         }
;         float a = x[pi], a2 = 0.f;
; #pragma unroll
;         for (int g4 = 0; g4 < (pi + 3) / 4; ++g4) { const float4 av = cur[g4];
;             if (4 * g4 + 0 < pi) a -= av.x * x[4 * g4 + 0];
;             if (4 * g4 + 1 < pi) a2 -= av.y * x[4 * g4 + 1];
;             if (4 * g4 + 2 < pi) a -= av.z * x[4 * g4 + 2];
;             if (4 * g4 + 3 < pi) a2 -= av.w * x[4 * g4 + 3]; }
;         x[pi] = a + a2;
;         asm volatile("" ::: "memory");
; #pragma unroll
;         for (int g4 = 0; g4 < (pi + 4) / 4; ++g4) cur[g4] = nxt[g4];
;     }
; }
	v_fma_f32 v29, -v49, v146, v29
	v_fma_f32 v28, -v47, v144, v28
	v_fma_f32 v61, -v46, v145, v61
	v_fma_f32 v29, -v47, v148, v29
	v_fma_f32 v28, -v45, v150, v28
	v_fma_f32 v61, -v44, v151, v61
	s_waitcnt lgkmcnt(4)
	v_fma_f32 v29, -v45, v154, v29
	v_fma_f32 v28, -v43, v152, v28
	v_fma_f32 v61, -v42, v153, v61
	v_fma_f32 v29, -v43, v156, v29
	v_fma_f32 v28, -v41, v158, v28
	v_fma_f32 v61, -v40, v159, v61
	s_waitcnt lgkmcnt(3)
	v_fma_f32 v29, -v41, v162, v29
	v_fma_f32 v28, -v39, v160, v28
	v_fma_f32 v61, -v38, v161, v61
	v_fma_f32 v29, -v39, v164, v29
	v_fma_f32 v28, -v37, v166, v28
	v_fma_f32 v61, -v36, v167, v61
	s_waitcnt lgkmcnt(2)
	v_fma_f32 v29, -v37, v170, v29
	v_fma_f32 v28, -v35, v168, v28
	v_fma_f32 v61, -v34, v169, v61
	v_fma_f32 v29, -v35, v172, v29
	v_fma_f32 v28, -v33, v174, v28
	v_fma_f32 v61, -v32, v175, v61
	s_waitcnt lgkmcnt(1)
	v_fma_f32 v29, -v33, v178, v29
	v_fma_f32 v28, -v31, v176, v28
	v_fma_f32 v61, -v30, v177, v61
	ds_read_b128 v[74:77], v110 offset:11424
	ds_read_b128 v[82:85], v110 offset:11440
	ds_read_b128 v[90:93], v110 offset:11456
	ds_read_b128 v[126:129], v110 offset:11472
	ds_read_b128 v[134:137], v110 offset:11488
	ds_read_b128 v[142:145], v110 offset:11504
	ds_read_b128 v[150:153], v110 offset:11520
	ds_read_b128 v[158:161], v110 offset:11536
	ds_read_b128 v[166:169], v110 offset:11552
	ds_read_b128 v[174:177], v110 offset:11568
	ds_read_b64 v[64:65], v110 offset:11584
	v_fma_f32 v63, -v73, v79, 0
	v_fma_f32 v98, -v31, v180, v29
	s_waitcnt lgkmcnt(10)
	v_fma_f32 v29, -v73, v75, 0
	v_fma_f32 v63, -v70, v81, v63
	v_fma_f32 v29, -v70, v77, v29
	v_fma_f32 v63, -v67, v87, v63
	s_waitcnt lgkmcnt(9)
	v_fma_f32 v29, -v67, v83, v29
	v_fma_f32 v63, -v56, v89, v63
	v_fma_f32 v29, -v56, v85, v29
	v_fma_f32 v63, -v57, v95, v63
	s_waitcnt lgkmcnt(8)
	v_fma_f32 v29, -v57, v91, v29
	v_fma_f32 v63, -v3, v97, v63
	v_fma_f32 v29, -v3, v93, v29
	v_fma_f32 v63, -v59, v131, v63
	s_waitcnt lgkmcnt(7)
	v_fma_f32 v29, -v59, v127, v29
	v_fma_f32 v63, -v50, v133, v63
	v_fma_f32 v29, -v50, v129, v29
	v_fma_f32 v63, -v54, v139, v63
	s_waitcnt lgkmcnt(6)
	v_fma_f32 v29, -v54, v135, v29
	v_fma_f32 v63, -v52, v141, v63
	v_fma_f32 v29, -v52, v137, v29
	v_fma_f32 v63, -v48, v147, v63
	s_waitcnt lgkmcnt(5)
	v_fma_f32 v29, -v48, v143, v29
	v_fma_f32 v63, -v46, v149, v63
	v_fma_f32 v29, -v46, v145, v29
	v_fma_f32 v63, -v44, v155, v63
	s_waitcnt lgkmcnt(4)
	v_fma_f32 v29, -v44, v151, v29
	v_fma_f32 v63, -v42, v157, v63
	v_fma_f32 v29, -v42, v153, v29
	v_fma_f32 v63, -v40, v163, v63
	s_waitcnt lgkmcnt(3)
	v_fma_f32 v29, -v40, v159, v29
	v_fma_f32 v63, -v38, v165, v63
	v_fma_f32 v29, -v38, v161, v29
	v_fma_f32 v63, -v36, v171, v63
	s_waitcnt lgkmcnt(2)
	v_fma_f32 v29, -v36, v167, v29
	v_fma_f32 v63, -v34, v173, v63
	v_fma_f32 v29, -v34, v169, v29
	v_fma_f32 v63, -v32, v179, v63
	s_waitcnt lgkmcnt(1)
	v_fma_f32 v29, -v32, v175, v29
	v_fma_f32 v63, -v30, v181, v63
	ds_read_b128 v[78:81], v110 offset:11696
	ds_read_b128 v[86:89], v110 offset:11712
	ds_read_b128 v[94:97], v110 offset:11728
	ds_read_b128 v[130:133], v110 offset:11744
	ds_read_b128 v[138:141], v110 offset:11760
	ds_read_b128 v[146:149], v110 offset:11776
	ds_read_b128 v[154:157], v110 offset:11792
	ds_read_b128 v[162:165], v110 offset:11808
	ds_read_b128 v[170:173], v110 offset:11824
	ds_read_b128 v[178:181], v110 offset:11840
	ds_read_b96 v[186:188], v110 offset:11856
	v_fma_f32 v99, -v30, v177, v29
	s_waitcnt lgkmcnt(10)
	v_fma_f32 v29, -v73, v79, 0
	v_fma_f32 v29, -v70, v81, v29
	v_fma_f32 v26, -v2, v74, v26
	s_waitcnt lgkmcnt(9)
	v_fma_f32 v29, -v67, v87, v29
	v_fma_f32 v26, -v72, v76, v26
	v_fma_f32 v27, -v2, v78, v27
	v_fma_f32 v29, -v56, v89, v29
	v_fma_f32 v26, -v71, v82, v26
	v_fma_f32 v27, -v72, v80, v27
	s_waitcnt lgkmcnt(8)
	v_fma_f32 v29, -v57, v95, v29
	v_fma_f32 v26, -v66, v84, v26
	v_fma_f32 v27, -v71, v86, v27
	v_fma_f32 v29, -v3, v97, v29
	v_fma_f32 v26, -v62, v90, v26
	v_fma_f32 v27, -v66, v88, v27
	s_waitcnt lgkmcnt(7)
	v_fma_f32 v29, -v59, v131, v29
	v_fma_f32 v26, -v51, v92, v26
	v_fma_f32 v27, -v62, v94, v27
	v_fma_f32 v29, -v50, v133, v29
	v_fma_f32 v26, -v60, v126, v26
	v_fma_f32 v27, -v51, v96, v27
	s_waitcnt lgkmcnt(6)
	v_fma_f32 v29, -v54, v139, v29
	v_fma_f32 v26, -v58, v128, v26
	v_fma_f32 v27, -v60, v130, v27
	v_fma_f32 v29, -v52, v141, v29
	v_fma_f32 v26, -v55, v134, v26
	v_fma_f32 v27, -v58, v132, v27
	s_waitcnt lgkmcnt(5)
	v_fma_f32 v29, -v48, v147, v29
	v_fma_f32 v26, -v53, v136, v26
	v_fma_f32 v27, -v55, v138, v27
	v_fma_f32 v29, -v46, v149, v29
	v_fma_f32 v26, -v49, v142, v26
	v_fma_f32 v27, -v53, v140, v27
	s_waitcnt lgkmcnt(4)
	v_fma_f32 v29, -v44, v155, v29
	v_fma_f32 v26, -v47, v144, v26
	v_fma_f32 v27, -v49, v146, v27
	v_fma_f32 v29, -v42, v157, v29
	v_fma_f32 v26, -v45, v150, v26
	v_fma_f32 v27, -v47, v148, v27
	s_waitcnt lgkmcnt(3)
	v_fma_f32 v29, -v40, v163, v29
	v_fma_f32 v26, -v43, v152, v26
	v_fma_f32 v27, -v45, v154, v27
	v_fma_f32 v29, -v38, v165, v29
	v_fma_f32 v26, -v41, v158, v26
	v_fma_f32 v27, -v43, v156, v27
	s_waitcnt lgkmcnt(2)
	v_fma_f32 v29, -v36, v171, v29
	v_fma_f32 v26, -v39, v160, v26
	v_fma_f32 v27, -v41, v162, v27
	v_fma_f32 v29, -v34, v173, v29
	v_fma_f32 v26, -v37, v166, v26
	v_fma_f32 v27, -v39, v164, v27
	s_waitcnt lgkmcnt(1)
	v_fma_f32 v29, -v32, v179, v29
	v_fma_f32 v26, -v35, v168, v26
	v_fma_f32 v27, -v37, v170, v27
	v_fma_f32 v79, -v30, v181, v29
	v_add_f32_e32 v29, v28, v61
	v_fma_f32 v26, -v33, v174, v26
	v_fma_f32 v27, -v35, v172, v27
	v_fma_f32 v0, -v29, v0, v98
	v_fma_f32 v26, -v31, v176, v26
	v_fma_f32 v27, -v33, v178, v27
	v_add_f32_e32 v28, v63, v0
	v_fma_f32 v78, -v31, v180, v27
	v_fma_f32 v0, -v29, v64, v26
	v_fma_f32 v26, -v28, v65, v99
	v_add_f32_e32 v27, v0, v26
	s_waitcnt lgkmcnt(0)
; DI void dn_solve_core(float (&x)[64], lf_t Ad) {
;     float4 cur[16], nxt[16];
;     cur[0] = *(const float4*)(Ad + 68);
; #pragma unroll
;     for (int pi = 1; pi < 64; ++pi) {
;         if (pi + 1 < 64) {
; #pragma unroll
;             for (int g4 = 0; g4 < (pi + 4) / 4; ++g4) nxt[g4] = *(const float4*)(Ad + (pi + 1) * 68 + 4 * g4);
;         }
;         float a = x[pi], a2 = 0.f;
; #pragma unroll
;         for (int g4 = 0; g4 < (pi + 3) / 4; ++g4) { const float4 av = cur[g4];
;             if (4 * g4 + 0 < pi) a -= av.x * x[4 * g4 + 0];
;             if (4 * g4 + 1 < pi) a2 -= av.y * x[4 * g4 + 1];
;             if (4 * g4 + 2 < pi) a -= av.z * x[4 * g4 + 2];
;             if (4 * g4 + 3 < pi) a2 -= av.w * x[4 * g4 + 3]; }
;         x[pi] = a + a2;
;         asm volatile("" ::: "memory");
; #pragma unroll
;         for (int g4 = 0; g4 < (pi + 4) / 4; ++g4) cur[g4] = nxt[g4];
;     }
; }
	v_fma_f32 v0, -v29, v186, v78
	ds_read_b128 v[74:77], v110 offset:11968
	ds_read_b128 v[82:85], v110 offset:11984
	ds_read_b128 v[90:93], v110 offset:12000
	ds_read_b128 v[126:129], v110 offset:12016
	ds_read_b128 v[134:137], v110 offset:12032
	ds_read_b128 v[142:145], v110 offset:12048
	ds_read_b128 v[150:153], v110 offset:12064
	ds_read_b128 v[158:161], v110 offset:12080
	ds_read_b128 v[166:169], v110 offset:12096
	ds_read_b128 v[174:177], v110 offset:12112
	ds_read_b128 v[182:185], v110 offset:12128
	v_fma_f32 v26, -v28, v187, v79
	v_fma_f32 v0, -v27, v188, v0
	v_add_f32_e32 v26, v26, v0
	ds_read_b128 v[78:81], v110 offset:12240
	ds_read_b128 v[86:89], v110 offset:12256
	ds_read_b128 v[94:97], v110 offset:12272
	ds_read_b128 v[130:133], v110 offset:12288
	ds_read_b128 v[138:141], v110 offset:12304
	ds_read_b128 v[146:149], v110 offset:12320
	ds_read_b128 v[154:157], v110 offset:12336
	ds_read_b128 v[162:165], v110 offset:12352
	ds_read_b128 v[170:173], v110 offset:12368
	ds_read_b128 v[178:181], v110 offset:12384
	ds_read_b128 v[186:189], v110 offset:12400
	ds_read_b32 v0, v110 offset:12416
	s_waitcnt lgkmcnt(14)
	v_fma_f32 v24, -v2, v74, v24
	v_fma_f32 v61, -v73, v75, 0
	s_waitcnt lgkmcnt(11)
	v_fma_f32 v25, -v2, v78, v25
	v_fma_f32 v24, -v72, v76, v24
	v_fma_f32 v61, -v70, v77, v61
	v_fma_f32 v25, -v72, v80, v25
	v_fma_f32 v24, -v71, v82, v24
	v_fma_f32 v61, -v67, v83, v61
	s_waitcnt lgkmcnt(10)
	v_fma_f32 v25, -v71, v86, v25
	v_fma_f32 v24, -v66, v84, v24
	v_fma_f32 v61, -v56, v85, v61
	v_fma_f32 v25, -v66, v88, v25
	v_fma_f32 v24, -v62, v90, v24
	v_fma_f32 v61, -v57, v91, v61
	s_waitcnt lgkmcnt(9)
	v_fma_f32 v25, -v62, v94, v25
	v_fma_f32 v24, -v51, v92, v24
	v_fma_f32 v61, -v3, v93, v61
	v_fma_f32 v25, -v51, v96, v25
	v_fma_f32 v24, -v60, v126, v24
	v_fma_f32 v61, -v59, v127, v61
	s_waitcnt lgkmcnt(8)
	v_fma_f32 v25, -v60, v130, v25
	v_fma_f32 v24, -v58, v128, v24
	v_fma_f32 v61, -v50, v129, v61
	v_fma_f32 v25, -v58, v132, v25
	v_fma_f32 v24, -v55, v134, v24
	v_fma_f32 v61, -v54, v135, v61
	s_waitcnt lgkmcnt(7)
	v_fma_f32 v25, -v55, v138, v25
	v_fma_f32 v24, -v53, v136, v24
	v_fma_f32 v61, -v52, v137, v61
	v_fma_f32 v25, -v53, v140, v25
	v_fma_f32 v24, -v49, v142, v24
	v_fma_f32 v61, -v48, v143, v61
	s_waitcnt lgkmcnt(6)
	v_fma_f32 v25, -v49, v146, v25
	v_fma_f32 v24, -v47, v144, v24
	v_fma_f32 v61, -v46, v145, v61
	v_fma_f32 v25, -v47, v148, v25
	v_fma_f32 v24, -v45, v150, v24
	v_fma_f32 v61, -v44, v151, v61
	s_waitcnt lgkmcnt(5)
	v_fma_f32 v25, -v45, v154, v25
	v_fma_f32 v24, -v43, v152, v24
	v_fma_f32 v61, -v42, v153, v61
	v_fma_f32 v25, -v43, v156, v25
	v_fma_f32 v24, -v41, v158, v24
	v_fma_f32 v61, -v40, v159, v61
	s_waitcnt lgkmcnt(4)
	v_fma_f32 v25, -v41, v162, v25
	v_fma_f32 v24, -v39, v160, v24
	v_fma_f32 v61, -v38, v161, v61
	v_fma_f32 v25, -v39, v164, v25
	v_fma_f32 v24, -v37, v166, v24
	v_fma_f32 v61, -v36, v167, v61
	s_waitcnt lgkmcnt(3)
	v_fma_f32 v25, -v37, v170, v25
	v_fma_f32 v24, -v35, v168, v24
	v_fma_f32 v61, -v34, v169, v61
	v_fma_f32 v25, -v35, v172, v25
	v_fma_f32 v24, -v33, v174, v24
	v_fma_f32 v61, -v32, v175, v61
	s_waitcnt lgkmcnt(2)
	v_fma_f32 v25, -v33, v178, v25
	v_fma_f32 v24, -v31, v176, v24
	v_fma_f32 v61, -v30, v177, v61
	v_fma_f32 v25, -v31, v180, v25
	v_fma_f32 v24, -v29, v182, v24
	v_fma_f32 v61, -v28, v183, v61
	s_waitcnt lgkmcnt(1)
	v_fma_f32 v25, -v29, v186, v25
	v_fma_f32 v24, -v27, v184, v24
	v_fma_f32 v61, -v26, v185, v61
	ds_read_b128 v[74:77], v110 offset:12512
	ds_read_b128 v[82:85], v110 offset:12528
	ds_read_b128 v[90:93], v110 offset:12544
	ds_read_b128 v[126:129], v110 offset:12560
	ds_read_b128 v[134:137], v110 offset:12576
	ds_read_b128 v[142:145], v110 offset:12592
	ds_read_b128 v[150:153], v110 offset:12608
	ds_read_b128 v[158:161], v110 offset:12624
	ds_read_b128 v[166:169], v110 offset:12640
	ds_read_b128 v[174:177], v110 offset:12656
	ds_read_b128 v[182:185], v110 offset:12672
	ds_read_b64 v[64:65], v110 offset:12688
	v_fma_f32 v63, -v73, v79, 0
	v_fma_f32 v98, -v27, v188, v25
	s_waitcnt lgkmcnt(11)
	v_fma_f32 v25, -v73, v75, 0
	v_fma_f32 v63, -v70, v81, v63
	v_fma_f32 v25, -v70, v77, v25
	v_fma_f32 v63, -v67, v87, v63
	s_waitcnt lgkmcnt(10)
	v_fma_f32 v25, -v67, v83, v25
	v_fma_f32 v63, -v56, v89, v63
	v_fma_f32 v25, -v56, v85, v25
	v_fma_f32 v63, -v57, v95, v63
	s_waitcnt lgkmcnt(9)
	v_fma_f32 v25, -v57, v91, v25
	v_fma_f32 v63, -v3, v97, v63
	v_fma_f32 v25, -v3, v93, v25
	v_fma_f32 v63, -v59, v131, v63
	s_waitcnt lgkmcnt(8)
	v_fma_f32 v25, -v59, v127, v25
	v_fma_f32 v63, -v50, v133, v63
	v_fma_f32 v25, -v50, v129, v25
	v_fma_f32 v63, -v54, v139, v63
	s_waitcnt lgkmcnt(7)
	v_fma_f32 v25, -v54, v135, v25
	v_fma_f32 v63, -v52, v141, v63
	v_fma_f32 v25, -v52, v137, v25
	v_fma_f32 v63, -v48, v147, v63
	s_waitcnt lgkmcnt(6)
	v_fma_f32 v25, -v48, v143, v25
	v_fma_f32 v63, -v46, v149, v63
	v_fma_f32 v25, -v46, v145, v25
	v_fma_f32 v63, -v44, v155, v63
	s_waitcnt lgkmcnt(5)
	v_fma_f32 v25, -v44, v151, v25
	v_fma_f32 v63, -v42, v157, v63
	v_fma_f32 v25, -v42, v153, v25
	v_fma_f32 v63, -v40, v163, v63
	s_waitcnt lgkmcnt(4)
	v_fma_f32 v25, -v40, v159, v25
	v_fma_f32 v63, -v38, v165, v63
	v_fma_f32 v25, -v38, v161, v25
	v_fma_f32 v63, -v36, v171, v63
	s_waitcnt lgkmcnt(3)
	v_fma_f32 v25, -v36, v167, v25
	v_fma_f32 v63, -v34, v173, v63
	v_fma_f32 v25, -v34, v169, v25
	v_fma_f32 v63, -v32, v179, v63
	s_waitcnt lgkmcnt(2)
	v_fma_f32 v25, -v32, v175, v25
	v_fma_f32 v63, -v30, v181, v63
	v_fma_f32 v25, -v30, v177, v25
	v_fma_f32 v63, -v28, v187, v63
	s_waitcnt lgkmcnt(1)
; DI void dn_solve_core(float (&x)[64], lf_t Ad) {
;     float4 cur[16], nxt[16];
;     cur[0] = *(const float4*)(Ad + 68);
; #pragma unroll
;     for (int pi = 1; pi < 64; ++pi) {
;         if (pi + 1 < 64) {
; #pragma unroll
;             for (int g4 = 0; g4 < (pi + 4) / 4; ++g4) nxt[g4] = *(const float4*)(Ad + (pi + 1) * 68 + 4 * g4);
;         }
;         float a = x[pi], a2 = 0.f;
; #pragma unroll
;         for (int g4 = 0; g4 < (pi + 3) / 4; ++g4) { const float4 av = cur[g4];
;             if (4 * g4 + 0 < pi) a -= av.x * x[4 * g4 + 0];
;             if (4 * g4 + 1 < pi) a2 -= av.y * x[4 * g4 + 1];
;             if (4 * g4 + 2 < pi) a -= av.z * x[4 * g4 + 2];
;             if (4 * g4 + 3 < pi) a2 -= av.w * x[4 * g4 + 3]; }
;         x[pi] = a + a2;
;         asm volatile("" ::: "memory");
; #pragma unroll
;         for (int g4 = 0; g4 < (pi + 4) / 4; ++g4) cur[g4] = nxt[g4];
;     }
; }
	v_fma_f32 v25, -v28, v183, v25
	v_fma_f32 v63, -v26, v189, v63
	ds_read_b128 v[78:81], v110 offset:12784
	ds_read_b128 v[86:89], v110 offset:12800
	ds_read_b128 v[94:97], v110 offset:12816
	ds_read_b128 v[130:133], v110 offset:12832
	ds_read_b128 v[138:141], v110 offset:12848
	ds_read_b128 v[146:149], v110 offset:12864
	ds_read_b128 v[154:157], v110 offset:12880
	ds_read_b128 v[162:165], v110 offset:12896
	ds_read_b128 v[170:173], v110 offset:12912
	ds_read_b128 v[178:181], v110 offset:12928
	ds_read_b128 v[186:189], v110 offset:12944
	ds_read_b96 v[198:200], v110 offset:12960
	v_fma_f32 v22, -v2, v74, v22
	v_fma_f32 v99, -v26, v185, v25
	s_waitcnt lgkmcnt(11)
	v_fma_f32 v25, -v73, v79, 0
	v_fma_f32 v22, -v72, v76, v22
	v_fma_f32 v25, -v70, v81, v25
	v_fma_f32 v22, -v71, v82, v22
	s_waitcnt lgkmcnt(10)
	v_fma_f32 v25, -v67, v87, v25
	v_fma_f32 v22, -v66, v84, v22
	v_fma_f32 v25, -v56, v89, v25
	v_fma_f32 v22, -v62, v90, v22
	s_waitcnt lgkmcnt(9)
	v_fma_f32 v25, -v57, v95, v25
	v_fma_f32 v22, -v51, v92, v22
	v_fma_f32 v25, -v3, v97, v25
	v_fma_f32 v22, -v60, v126, v22
	s_waitcnt lgkmcnt(8)
	v_fma_f32 v25, -v59, v131, v25
	v_fma_f32 v22, -v58, v128, v22
	v_fma_f32 v25, -v50, v133, v25
	v_fma_f32 v22, -v55, v134, v22
	s_waitcnt lgkmcnt(7)
	v_fma_f32 v25, -v54, v139, v25
	v_fma_f32 v22, -v53, v136, v22
	v_fma_f32 v25, -v52, v141, v25
	v_fma_f32 v22, -v49, v142, v22
	s_waitcnt lgkmcnt(6)
	v_fma_f32 v25, -v48, v147, v25
	v_fma_f32 v22, -v47, v144, v22
	v_fma_f32 v25, -v46, v149, v25
	v_fma_f32 v22, -v45, v150, v22
	s_waitcnt lgkmcnt(5)
	v_fma_f32 v25, -v44, v155, v25
	v_fma_f32 v22, -v43, v152, v22
	v_fma_f32 v25, -v42, v157, v25
	v_fma_f32 v22, -v41, v158, v22
	s_waitcnt lgkmcnt(4)
	v_fma_f32 v25, -v40, v163, v25
	v_fma_f32 v22, -v39, v160, v22
	v_fma_f32 v25, -v38, v165, v25
	v_fma_f32 v22, -v37, v166, v22
	s_waitcnt lgkmcnt(3)
	v_fma_f32 v25, -v36, v171, v25
	v_fma_f32 v22, -v35, v168, v22
	v_fma_f32 v25, -v34, v173, v25
	v_fma_f32 v22, -v33, v174, v22
	s_waitcnt lgkmcnt(2)
	v_fma_f32 v25, -v32, v179, v25
	v_fma_f32 v22, -v31, v176, v22
	v_fma_f32 v23, -v2, v78, v23
	v_fma_f32 v25, -v30, v181, v25
	v_fma_f32 v22, -v29, v182, v22
	v_fma_f32 v23, -v72, v80, v23
	s_waitcnt lgkmcnt(1)
	v_fma_f32 v25, -v28, v187, v25
	v_fma_f32 v22, -v27, v184, v22
	ds_read_b128 v[74:77], v110 offset:13056
	ds_read_b128 v[82:85], v110 offset:13072
	ds_read_b128 v[90:93], v110 offset:13088
	ds_read_b128 v[126:129], v110 offset:13104
	ds_read_b128 v[134:137], v110 offset:13120
	ds_read_b128 v[142:145], v110 offset:13136
	ds_read_b128 v[150:153], v110 offset:13152
	ds_read_b128 v[158:161], v110 offset:13168
	ds_read_b128 v[166:169], v110 offset:13184
	ds_read_b128 v[174:177], v110 offset:13200
	ds_read_b128 v[182:185], v110 offset:13216
	ds_read_b128 v[190:193], v110 offset:13232
	v_fma_f32 v23, -v71, v86, v23
	v_fma_f32 v79, -v26, v189, v25
	v_add_f32_e32 v25, v24, v61
	s_waitcnt lgkmcnt(11)
	v_fma_f32 v16, -v2, v74, v16
	v_fma_f32 v61, -v73, v75, 0
	v_fma_f32 v23, -v66, v88, v23
	v_fma_f32 v16, -v72, v76, v16
	v_fma_f32 v61, -v70, v77, v61
	v_fma_f32 v23, -v62, v94, v23
	s_waitcnt lgkmcnt(10)
	v_fma_f32 v16, -v71, v82, v16
	v_fma_f32 v61, -v67, v83, v61
	v_fma_f32 v23, -v51, v96, v23
	v_fma_f32 v16, -v66, v84, v16
	v_fma_f32 v61, -v56, v85, v61
	v_fma_f32 v23, -v60, v130, v23
	s_waitcnt lgkmcnt(9)
	v_fma_f32 v16, -v62, v90, v16
	v_fma_f32 v61, -v57, v91, v61
	v_fma_f32 v23, -v58, v132, v23
	v_fma_f32 v16, -v51, v92, v16
	v_fma_f32 v61, -v3, v93, v61
	v_fma_f32 v23, -v55, v138, v23
	s_waitcnt lgkmcnt(8)
	v_fma_f32 v16, -v60, v126, v16
	v_fma_f32 v61, -v59, v127, v61
	v_fma_f32 v23, -v53, v140, v23
	v_fma_f32 v16, -v58, v128, v16
	v_fma_f32 v61, -v50, v129, v61
	v_fma_f32 v23, -v49, v146, v23
	s_waitcnt lgkmcnt(7)
	v_fma_f32 v16, -v55, v134, v16
	v_fma_f32 v61, -v54, v135, v61
	v_fma_f32 v23, -v47, v148, v23
	v_fma_f32 v16, -v53, v136, v16
	v_fma_f32 v61, -v52, v137, v61
	v_fma_f32 v23, -v45, v154, v23
	s_waitcnt lgkmcnt(6)
	v_fma_f32 v16, -v49, v142, v16
	v_fma_f32 v61, -v48, v143, v61
	v_fma_f32 v23, -v43, v156, v23
	v_fma_f32 v16, -v47, v144, v16
	v_fma_f32 v61, -v46, v145, v61
	v_fma_f32 v23, -v41, v162, v23
	s_waitcnt lgkmcnt(5)
	v_fma_f32 v16, -v45, v150, v16
	v_fma_f32 v61, -v44, v151, v61
	v_fma_f32 v23, -v39, v164, v23
	v_fma_f32 v16, -v43, v152, v16
	v_fma_f32 v61, -v42, v153, v61
	v_fma_f32 v23, -v37, v170, v23
	s_waitcnt lgkmcnt(4)
	v_fma_f32 v16, -v41, v158, v16
	v_fma_f32 v61, -v40, v159, v61
	v_fma_f32 v23, -v35, v172, v23
	v_fma_f32 v16, -v39, v160, v16
	v_fma_f32 v61, -v38, v161, v61
	v_fma_f32 v23, -v33, v178, v23
	s_waitcnt lgkmcnt(3)
	v_fma_f32 v16, -v37, v166, v16
	v_fma_f32 v61, -v36, v167, v61
	v_fma_f32 v23, -v31, v180, v23
	v_fma_f32 v0, -v25, v0, v98
	v_fma_f32 v16, -v35, v168, v16
	v_fma_f32 v61, -v34, v169, v61
	v_fma_f32 v23, -v29, v186, v23
	v_add_f32_e32 v24, v63, v0
	s_waitcnt lgkmcnt(2)
	v_fma_f32 v16, -v33, v174, v16
	v_fma_f32 v61, -v32, v175, v61
	v_fma_f32 v78, -v27, v188, v23
	v_fma_f32 v0, -v25, v64, v22
	v_fma_f32 v22, -v24, v65, v99
	v_fma_f32 v16, -v31, v176, v16
	v_fma_f32 v61, -v30, v177, v61
	v_add_f32_e32 v23, v0, v22
	v_fma_f32 v0, -v25, v198, v78
	s_waitcnt lgkmcnt(1)
	v_fma_f32 v16, -v29, v182, v16
	v_fma_f32 v61, -v28, v183, v61
	v_fma_f32 v22, -v24, v199, v79
	v_fma_f32 v0, -v23, v200, v0
	v_fma_f32 v16, -v27, v184, v16
	v_fma_f32 v61, -v26, v185, v61
	v_add_f32_e32 v22, v22, v0
	ds_read_b128 v[78:81], v110 offset:13328
	ds_read_b128 v[86:89], v110 offset:13344
	ds_read_b128 v[94:97], v110 offset:13360
	ds_read_b128 v[130:133], v110 offset:13376
	ds_read_b128 v[138:141], v110 offset:13392
	ds_read_b128 v[146:149], v110 offset:13408
	ds_read_b128 v[154:157], v110 offset:13424
	ds_read_b128 v[162:165], v110 offset:13440
	ds_read_b128 v[170:173], v110 offset:13456
	ds_read_b128 v[178:181], v110 offset:13472
	ds_read_b128 v[186:189], v110 offset:13488
	ds_read_b128 v[198:201], v110 offset:13504
	ds_read_b32 v0, v110 offset:13520
	s_waitcnt lgkmcnt(13)
; DI void dn_solve_core(float (&x)[64], lf_t Ad) {
;     float4 cur[16], nxt[16];
;     cur[0] = *(const float4*)(Ad + 68);
; #pragma unroll
;     for (int pi = 1; pi < 64; ++pi) {
;         if (pi + 1 < 64) {
; #pragma unroll
;             for (int g4 = 0; g4 < (pi + 4) / 4; ++g4) nxt[g4] = *(const float4*)(Ad + (pi + 1) * 68 + 4 * g4);
;         }
;         float a = x[pi], a2 = 0.f;
; #pragma unroll
;         for (int g4 = 0; g4 < (pi + 3) / 4; ++g4) { const float4 av = cur[g4];
;             if (4 * g4 + 0 < pi) a -= av.x * x[4 * g4 + 0];
;             if (4 * g4 + 1 < pi) a2 -= av.y * x[4 * g4 + 1];
;             if (4 * g4 + 2 < pi) a -= av.z * x[4 * g4 + 2];
;             if (4 * g4 + 3 < pi) a2 -= av.w * x[4 * g4 + 3]; }
;         x[pi] = a + a2;
;         asm volatile("" ::: "memory");
; #pragma unroll
;         for (int g4 = 0; g4 < (pi + 4) / 4; ++g4) cur[g4] = nxt[g4];
;     }
; }
	v_fma_f32 v16, -v25, v190, v16
	v_fma_f32 v61, -v24, v191, v61
	v_fma_f32 v16, -v23, v192, v16
	v_fma_f32 v61, -v22, v193, v61
	ds_read_b128 v[74:77], v110 offset:13600
	ds_read_b128 v[82:85], v110 offset:13616
	ds_read_b128 v[90:93], v110 offset:13632
	ds_read_b128 v[126:129], v110 offset:13648
	ds_read_b128 v[134:137], v110 offset:13664
	ds_read_b128 v[142:145], v110 offset:13680
	ds_read_b128 v[150:153], v110 offset:13696
	ds_read_b128 v[158:161], v110 offset:13712
	ds_read_b128 v[166:169], v110 offset:13728
	ds_read_b128 v[174:177], v110 offset:13744
	ds_read_b128 v[182:185], v110 offset:13760
	ds_read_b128 v[190:193], v110 offset:13776
	ds_read_b64 v[98:99], v110 offset:13792
	s_waitcnt lgkmcnt(14)
	v_fma_f32 v17, -v2, v78, v17
	v_fma_f32 v63, -v73, v79, 0
	s_waitcnt lgkmcnt(12)
	v_fma_f32 v64, -v73, v75, 0
	v_fma_f32 v17, -v72, v80, v17
	v_fma_f32 v63, -v70, v81, v63
	v_fma_f32 v64, -v70, v77, v64
	v_fma_f32 v17, -v71, v86, v17
	v_fma_f32 v63, -v67, v87, v63
	v_fma_f32 v14, -v2, v74, v14
	s_waitcnt lgkmcnt(11)
	v_fma_f32 v64, -v67, v83, v64
	v_fma_f32 v17, -v66, v88, v17
	v_fma_f32 v63, -v56, v89, v63
	v_fma_f32 v14, -v72, v76, v14
	v_fma_f32 v64, -v56, v85, v64
	v_fma_f32 v17, -v62, v94, v17
	v_fma_f32 v63, -v57, v95, v63
	v_fma_f32 v14, -v71, v82, v14
	s_waitcnt lgkmcnt(10)
	v_fma_f32 v64, -v57, v91, v64
	v_fma_f32 v17, -v51, v96, v17
	v_fma_f32 v63, -v3, v97, v63
	v_fma_f32 v14, -v66, v84, v14
	v_fma_f32 v64, -v3, v93, v64
	v_fma_f32 v17, -v60, v130, v17
	v_fma_f32 v63, -v59, v131, v63
	v_fma_f32 v14, -v62, v90, v14
	s_waitcnt lgkmcnt(9)
	v_fma_f32 v64, -v59, v127, v64
	v_fma_f32 v17, -v58, v132, v17
	v_fma_f32 v63, -v50, v133, v63
	v_fma_f32 v14, -v51, v92, v14
	v_fma_f32 v64, -v50, v129, v64
	v_fma_f32 v17, -v55, v138, v17
	v_fma_f32 v63, -v54, v139, v63
	v_fma_f32 v14, -v60, v126, v14
	s_waitcnt lgkmcnt(8)
	v_fma_f32 v64, -v54, v135, v64
	v_fma_f32 v17, -v53, v140, v17
	v_fma_f32 v63, -v52, v141, v63
	v_fma_f32 v14, -v58, v128, v14
	v_fma_f32 v64, -v52, v137, v64
	v_fma_f32 v17, -v49, v146, v17
	v_fma_f32 v63, -v48, v147, v63
	v_fma_f32 v14, -v55, v134, v14
	s_waitcnt lgkmcnt(7)
	v_fma_f32 v64, -v48, v143, v64
	v_fma_f32 v17, -v47, v148, v17
	v_fma_f32 v63, -v46, v149, v63
	v_fma_f32 v14, -v53, v136, v14
	v_fma_f32 v64, -v46, v145, v64
	v_fma_f32 v17, -v45, v154, v17
	v_fma_f32 v63, -v44, v155, v63
	v_fma_f32 v14, -v49, v142, v14
	s_waitcnt lgkmcnt(6)
	v_fma_f32 v64, -v44, v151, v64
	v_fma_f32 v17, -v43, v156, v17
	v_fma_f32 v63, -v42, v157, v63
	v_fma_f32 v14, -v47, v144, v14
	v_fma_f32 v64, -v42, v153, v64
	v_fma_f32 v17, -v41, v162, v17
	v_fma_f32 v63, -v40, v163, v63
	v_fma_f32 v14, -v45, v150, v14
	s_waitcnt lgkmcnt(5)
	v_fma_f32 v64, -v40, v159, v64
	v_fma_f32 v17, -v39, v164, v17
	v_fma_f32 v63, -v38, v165, v63
	v_fma_f32 v14, -v43, v152, v14
	v_fma_f32 v64, -v38, v161, v64
	v_fma_f32 v17, -v37, v170, v17
	v_fma_f32 v63, -v36, v171, v63
	v_fma_f32 v14, -v41, v158, v14
	s_waitcnt lgkmcnt(4)
	v_fma_f32 v64, -v36, v167, v64
	v_fma_f32 v17, -v35, v172, v17
	v_fma_f32 v63, -v34, v173, v63
	v_fma_f32 v14, -v39, v160, v14
	v_fma_f32 v64, -v34, v169, v64
	v_fma_f32 v17, -v33, v178, v17
	v_fma_f32 v63, -v32, v179, v63
	v_fma_f32 v14, -v37, v166, v14
	s_waitcnt lgkmcnt(3)
	v_fma_f32 v64, -v32, v175, v64
	v_fma_f32 v17, -v31, v180, v17
	v_fma_f32 v63, -v30, v181, v63
	v_fma_f32 v14, -v35, v168, v14
	v_fma_f32 v64, -v30, v177, v64
	v_fma_f32 v17, -v29, v186, v17
	v_fma_f32 v63, -v28, v187, v63
	v_fma_f32 v14, -v33, v174, v14
	s_waitcnt lgkmcnt(2)
	v_fma_f32 v64, -v28, v183, v64
	v_fma_f32 v17, -v27, v188, v17
	v_fma_f32 v63, -v26, v189, v63
	v_fma_f32 v14, -v31, v176, v14
	v_fma_f32 v64, -v26, v185, v64
	v_fma_f32 v17, -v25, v198, v17
	v_fma_f32 v63, -v24, v199, v63
	v_fma_f32 v14, -v29, v182, v14
	s_waitcnt lgkmcnt(1)
	v_fma_f32 v64, -v24, v191, v64
	v_fma_f32 v17, -v23, v200, v17
	v_fma_f32 v63, -v22, v201, v63
	ds_read_b128 v[78:81], v110 offset:13872
	ds_read_b128 v[86:89], v110 offset:13888
	ds_read_b128 v[94:97], v110 offset:13904
	ds_read_b128 v[130:133], v110 offset:13920
	ds_read_b128 v[138:141], v110 offset:13936
	ds_read_b128 v[146:149], v110 offset:13952
	ds_read_b128 v[154:157], v110 offset:13968
	ds_read_b128 v[162:165], v110 offset:13984
	ds_read_b128 v[170:173], v110 offset:14000
	ds_read_b128 v[178:181], v110 offset:14016
	ds_read_b128 v[186:189], v110 offset:14032
	ds_read_b128 v[198:201], v110 offset:14048
	ds_read_b96 v[206:208], v110 offset:14064
	v_fma_f32 v14, -v27, v184, v14
	v_fma_f32 v125, -v22, v193, v64
	s_waitcnt lgkmcnt(12)
	v_fma_f32 v64, -v73, v79, 0
	v_fma_f32 v14, -v25, v190, v14
	v_fma_f32 v15, -v2, v78, v15
	v_fma_f32 v64, -v70, v81, v64
	v_fma_f32 v14, -v23, v192, v14
	ds_read_b128 v[74:77], v110 offset:14144
	ds_read_b128 v[82:85], v110 offset:14160
	ds_read_b128 v[90:93], v110 offset:14176
	ds_read_b128 v[126:129], v110 offset:14192
	ds_read_b128 v[134:137], v110 offset:14208
	ds_read_b128 v[142:145], v110 offset:14224
	ds_read_b128 v[150:153], v110 offset:14240
	ds_read_b128 v[158:161], v110 offset:14256
	ds_read_b128 v[166:169], v110 offset:14272
	ds_read_b128 v[174:177], v110 offset:14288
	ds_read_b128 v[182:185], v110 offset:14304
	ds_read_b128 v[190:193], v110 offset:14320
	ds_read_b128 v[202:205], v110 offset:14336
	v_fma_f32 v15, -v72, v80, v15
	s_waitcnt lgkmcnt(14)
	v_fma_f32 v64, -v67, v87, v64
	s_waitcnt lgkmcnt(12)
	v_fma_f32 v12, -v2, v74, v12
	v_fma_f32 v15, -v71, v86, v15
	v_fma_f32 v64, -v56, v89, v64
	v_fma_f32 v12, -v72, v76, v12
	v_fma_f32 v15, -v66, v88, v15
	v_fma_f32 v64, -v57, v95, v64
	s_waitcnt lgkmcnt(11)
; DI void dn_solve_core(float (&x)[64], lf_t Ad) {
;     float4 cur[16], nxt[16];
;     cur[0] = *(const float4*)(Ad + 68);
; #pragma unroll
;     for (int pi = 1; pi < 64; ++pi) {
;         if (pi + 1 < 64) {
; #pragma unroll
;             for (int g4 = 0; g4 < (pi + 4) / 4; ++g4) nxt[g4] = *(const float4*)(Ad + (pi + 1) * 68 + 4 * g4);
;         }
;         float a = x[pi], a2 = 0.f;
; #pragma unroll
;         for (int g4 = 0; g4 < (pi + 3) / 4; ++g4) { const float4 av = cur[g4];
;             if (4 * g4 + 0 < pi) a -= av.x * x[4 * g4 + 0];
;             if (4 * g4 + 1 < pi) a2 -= av.y * x[4 * g4 + 1];
;             if (4 * g4 + 2 < pi) a -= av.z * x[4 * g4 + 2];
;             if (4 * g4 + 3 < pi) a2 -= av.w * x[4 * g4 + 3]; }
;         x[pi] = a + a2;
;         asm volatile("" ::: "memory");
; #pragma unroll
;         for (int g4 = 0; g4 < (pi + 4) / 4; ++g4) cur[g4] = nxt[g4];
;     }
; }
	v_fma_f32 v12, -v71, v82, v12
	v_fma_f32 v15, -v62, v94, v15
	v_fma_f32 v64, -v3, v97, v64
	v_fma_f32 v12, -v66, v84, v12
	v_fma_f32 v15, -v51, v96, v15
	v_fma_f32 v64, -v59, v131, v64
	s_waitcnt lgkmcnt(10)
	v_fma_f32 v12, -v62, v90, v12
	v_fma_f32 v15, -v60, v130, v15
	v_fma_f32 v64, -v50, v133, v64
	v_fma_f32 v12, -v51, v92, v12
	v_fma_f32 v15, -v58, v132, v15
	v_fma_f32 v64, -v54, v139, v64
	s_waitcnt lgkmcnt(9)
	v_fma_f32 v12, -v60, v126, v12
	v_fma_f32 v15, -v55, v138, v15
	v_fma_f32 v64, -v52, v141, v64
	v_fma_f32 v12, -v58, v128, v12
	v_fma_f32 v15, -v53, v140, v15
	v_fma_f32 v64, -v48, v147, v64
	s_waitcnt lgkmcnt(8)
	v_fma_f32 v12, -v55, v134, v12
	v_fma_f32 v15, -v49, v146, v15
	v_fma_f32 v64, -v46, v149, v64
	v_fma_f32 v12, -v53, v136, v12
	v_fma_f32 v15, -v47, v148, v15
	v_fma_f32 v64, -v44, v155, v64
	s_waitcnt lgkmcnt(7)
	v_fma_f32 v12, -v49, v142, v12
	v_fma_f32 v15, -v45, v154, v15
	v_fma_f32 v64, -v42, v157, v64
	v_fma_f32 v12, -v47, v144, v12
	v_fma_f32 v15, -v43, v156, v15
	v_fma_f32 v64, -v40, v163, v64
	s_waitcnt lgkmcnt(6)
	v_fma_f32 v12, -v45, v150, v12
	v_fma_f32 v15, -v41, v162, v15
	v_fma_f32 v64, -v38, v165, v64
	v_fma_f32 v12, -v43, v152, v12
	v_fma_f32 v15, -v39, v164, v15
	v_fma_f32 v64, -v36, v171, v64
	s_waitcnt lgkmcnt(5)
	v_fma_f32 v12, -v41, v158, v12
	v_fma_f32 v15, -v37, v170, v15
	v_fma_f32 v64, -v34, v173, v64
	v_fma_f32 v12, -v39, v160, v12
	v_fma_f32 v15, -v35, v172, v15
	v_fma_f32 v64, -v32, v179, v64
	s_waitcnt lgkmcnt(4)
	v_fma_f32 v12, -v37, v166, v12
	v_fma_f32 v15, -v33, v178, v15
	v_fma_f32 v64, -v30, v181, v64
	v_fma_f32 v12, -v35, v168, v12
	v_fma_f32 v15, -v31, v180, v15
	v_fma_f32 v64, -v28, v187, v64
	s_waitcnt lgkmcnt(3)
	v_fma_f32 v12, -v33, v174, v12
	v_fma_f32 v15, -v29, v186, v15
	v_fma_f32 v64, -v26, v189, v64
	v_add_f32_e32 v65, v16, v61
	v_fma_f32 v12, -v31, v176, v12
	v_fma_f32 v15, -v27, v188, v15
	v_fma_f32 v64, -v24, v199, v64
	v_fma_f32 v0, -v65, v0, v17
	s_waitcnt lgkmcnt(2)
	v_fma_f32 v12, -v29, v182, v12
	v_fma_f32 v15, -v25, v198, v15
	v_fma_f32 v78, -v22, v201, v64
	v_add_f32_e32 v64, v63, v0
	v_fma_f32 v12, -v27, v184, v12
	v_fma_f32 v15, -v23, v200, v15
	v_fma_f32 v0, -v65, v98, v14
	v_fma_f32 v14, -v64, v99, v125
	s_waitcnt lgkmcnt(1)
	v_fma_f32 v12, -v25, v190, v12
	v_add_f32_e32 v63, v0, v14
	v_fma_f32 v0, -v65, v206, v15
	v_fma_f32 v74, -v73, v75, 0
	v_fma_f32 v12, -v23, v192, v12
	v_fma_f32 v14, -v64, v207, v78
	v_fma_f32 v0, -v63, v208, v0
	v_fma_f32 v74, -v70, v77, v74
	s_waitcnt lgkmcnt(0)
	v_fma_f32 v12, -v65, v202, v12
	v_add_f32_e32 v61, v14, v0
	ds_read_b128 v[14:17], v110 offset:14416
	ds_read_b128 v[78:81], v110 offset:14432
	ds_read_b128 v[86:89], v110 offset:14448
	ds_read_b128 v[94:97], v110 offset:14464
	ds_read_b128 v[130:133], v110 offset:14480
	ds_read_b128 v[138:141], v110 offset:14496
	ds_read_b128 v[146:149], v110 offset:14512
	ds_read_b128 v[154:157], v110 offset:14528
	ds_read_b128 v[162:165], v110 offset:14544
	ds_read_b128 v[170:173], v110 offset:14560
	ds_read_b128 v[178:181], v110 offset:14576
	ds_read_b128 v[186:189], v110 offset:14592
	ds_read_b128 v[198:201], v110 offset:14608
	ds_read_b32 v0, v110 offset:14624
	v_fma_f32 v74, -v67, v83, v74
	v_fma_f32 v125, -v63, v204, v12
	s_waitcnt lgkmcnt(13)
	v_fma_f32 v12, -v2, v14, v13
	v_fma_f32 v13, -v73, v15, 0
	v_fma_f32 v74, -v56, v85, v74
	v_fma_f32 v12, -v72, v16, v12
	v_fma_f32 v13, -v70, v17, v13
	v_fma_f32 v74, -v57, v91, v74
	s_waitcnt lgkmcnt(12)
	v_fma_f32 v12, -v71, v78, v12
	v_fma_f32 v13, -v67, v79, v13
	v_fma_f32 v74, -v3, v93, v74
	v_fma_f32 v12, -v66, v80, v12
	v_fma_f32 v13, -v56, v81, v13
	v_fma_f32 v74, -v59, v127, v74
	s_waitcnt lgkmcnt(11)
	v_fma_f32 v12, -v62, v86, v12
	v_fma_f32 v13, -v57, v87, v13
	v_fma_f32 v74, -v50, v129, v74
	v_fma_f32 v12, -v51, v88, v12
	v_fma_f32 v13, -v3, v89, v13
	v_fma_f32 v74, -v54, v135, v74
	s_waitcnt lgkmcnt(10)
	v_fma_f32 v12, -v60, v94, v12
	v_fma_f32 v13, -v59, v95, v13
	v_fma_f32 v74, -v52, v137, v74
	v_fma_f32 v12, -v58, v96, v12
	v_fma_f32 v13, -v50, v97, v13
	v_fma_f32 v74, -v48, v143, v74
	s_waitcnt lgkmcnt(9)
	v_fma_f32 v12, -v55, v130, v12
	v_fma_f32 v13, -v54, v131, v13
	v_fma_f32 v74, -v46, v145, v74
	v_fma_f32 v12, -v53, v132, v12
	v_fma_f32 v13, -v52, v133, v13
	v_fma_f32 v74, -v44, v151, v74
	s_waitcnt lgkmcnt(8)
	v_fma_f32 v12, -v49, v138, v12
	v_fma_f32 v13, -v48, v139, v13
	v_fma_f32 v74, -v42, v153, v74
	v_fma_f32 v12, -v47, v140, v12
	v_fma_f32 v13, -v46, v141, v13
	v_fma_f32 v74, -v40, v159, v74
	s_waitcnt lgkmcnt(7)
	v_fma_f32 v12, -v45, v146, v12
	v_fma_f32 v13, -v44, v147, v13
	v_fma_f32 v74, -v38, v161, v74
	v_fma_f32 v12, -v43, v148, v12
	v_fma_f32 v13, -v42, v149, v13
	v_fma_f32 v74, -v36, v167, v74
	s_waitcnt lgkmcnt(6)
	v_fma_f32 v12, -v41, v154, v12
	v_fma_f32 v13, -v40, v155, v13
	v_fma_f32 v74, -v34, v169, v74
	v_fma_f32 v12, -v39, v156, v12
	v_fma_f32 v13, -v38, v157, v13
	v_fma_f32 v74, -v32, v175, v74
	s_waitcnt lgkmcnt(5)
	v_fma_f32 v12, -v37, v162, v12
	v_fma_f32 v13, -v36, v163, v13
	v_fma_f32 v74, -v30, v177, v74
	v_fma_f32 v12, -v35, v164, v12
	v_fma_f32 v13, -v34, v165, v13
	v_fma_f32 v74, -v28, v183, v74
	s_waitcnt lgkmcnt(4)
	v_fma_f32 v12, -v33, v170, v12
	v_fma_f32 v13, -v32, v171, v13
	v_fma_f32 v74, -v26, v185, v74
	v_fma_f32 v12, -v31, v172, v12
	v_fma_f32 v13, -v30, v173, v13
	v_fma_f32 v74, -v24, v191, v74
	s_waitcnt lgkmcnt(3)
	v_fma_f32 v12, -v29, v178, v12
	v_fma_f32 v13, -v28, v179, v13
	v_fma_f32 v74, -v22, v193, v74
	v_fma_f32 v12, -v27, v180, v12
	v_fma_f32 v13, -v26, v181, v13
	v_fma_f32 v74, -v64, v203, v74
	s_waitcnt lgkmcnt(2)
; DI void dn_solve_core(float (&x)[64], lf_t Ad) {
;     float4 cur[16], nxt[16];
;     cur[0] = *(const float4*)(Ad + 68);
; #pragma unroll
;     for (int pi = 1; pi < 64; ++pi) {
;         if (pi + 1 < 64) {
; #pragma unroll
;             for (int g4 = 0; g4 < (pi + 4) / 4; ++g4) nxt[g4] = *(const float4*)(Ad + (pi + 1) * 68 + 4 * g4);
;         }
;         float a = x[pi], a2 = 0.f;
; #pragma unroll
;         for (int g4 = 0; g4 < (pi + 3) / 4; ++g4) { const float4 av = cur[g4];
;             if (4 * g4 + 0 < pi) a -= av.x * x[4 * g4 + 0];
;             if (4 * g4 + 1 < pi) a2 -= av.y * x[4 * g4 + 1];
;             if (4 * g4 + 2 < pi) a -= av.z * x[4 * g4 + 2];
;             if (4 * g4 + 3 < pi) a2 -= av.w * x[4 * g4 + 3]; }
;         x[pi] = a + a2;
;         asm volatile("" ::: "memory");
; #pragma unroll
;         for (int g4 = 0; g4 < (pi + 4) / 4; ++g4) cur[g4] = nxt[g4];
;     }
; }
	v_fma_f32 v12, -v25, v186, v12
	v_fma_f32 v13, -v24, v187, v13
	v_fma_f32 v197, -v61, v205, v74
	ds_read_b128 v[74:77], v110 offset:14688
	ds_read_b128 v[82:85], v110 offset:14704
	ds_read_b128 v[90:93], v110 offset:14720
	ds_read_b128 v[126:129], v110 offset:14736
	ds_read_b128 v[134:137], v110 offset:14752
	ds_read_b128 v[142:145], v110 offset:14768
	ds_read_b128 v[150:153], v110 offset:14784
	ds_read_b128 v[158:161], v110 offset:14800
	ds_read_b128 v[166:169], v110 offset:14816
	ds_read_b128 v[174:177], v110 offset:14832
	ds_read_b128 v[182:185], v110 offset:14848
	ds_read_b128 v[190:193], v110 offset:14864
	ds_read_b128 v[202:205], v110 offset:14880
	ds_read_b64 v[98:99], v110 offset:14896
	v_fma_f32 v12, -v23, v188, v12
	v_fma_f32 v13, -v22, v189, v13
	s_waitcnt lgkmcnt(14)
	v_fma_f32 v12, -v65, v198, v12
	v_fma_f32 v13, -v64, v199, v13
	s_waitcnt lgkmcnt(13)
	v_fma_f32 v10, -v2, v74, v10
	v_fma_f32 v74, -v73, v75, 0
	v_fma_f32 v16, -v63, v200, v12
	v_fma_f32 v17, -v61, v201, v13
	ds_read_b128 v[12:15], v110 offset:14960
	ds_read_b128 v[78:81], v110 offset:14976
	ds_read_b128 v[86:89], v110 offset:14992
	ds_read_b128 v[94:97], v110 offset:15008
	ds_read_b128 v[130:133], v110 offset:15024
	ds_read_b128 v[138:141], v110 offset:15040
	ds_read_b128 v[146:149], v110 offset:15056
	ds_read_b128 v[154:157], v110 offset:15072
	ds_read_b128 v[162:165], v110 offset:15088
	ds_read_b128 v[170:173], v110 offset:15104
	ds_read_b128 v[178:181], v110 offset:15120
	ds_read_b128 v[186:189], v110 offset:15136
	ds_read_b128 v[198:201], v110 offset:15152
	ds_read_b96 v[214:216], v110 offset:15168
	v_fma_f32 v10, -v72, v76, v10
	v_fma_f32 v74, -v70, v77, v74
	s_waitcnt lgkmcnt(13)
	v_fma_f32 v11, -v2, v12, v11
	v_fma_f32 v10, -v71, v82, v10
	v_fma_f32 v74, -v67, v83, v74
	v_fma_f32 v12, -v73, v13, 0
	v_fma_f32 v11, -v72, v14, v11
	v_fma_f32 v10, -v66, v84, v10
	v_fma_f32 v74, -v56, v85, v74
	v_fma_f32 v12, -v70, v15, v12
	s_waitcnt lgkmcnt(12)
	v_fma_f32 v11, -v71, v78, v11
	v_fma_f32 v10, -v62, v90, v10
	v_fma_f32 v74, -v57, v91, v74
	v_fma_f32 v12, -v67, v79, v12
	v_fma_f32 v11, -v66, v80, v11
	v_fma_f32 v10, -v51, v92, v10
	v_fma_f32 v74, -v3, v93, v74
	v_fma_f32 v12, -v56, v81, v12
	s_waitcnt lgkmcnt(11)
	v_fma_f32 v11, -v62, v86, v11
	v_fma_f32 v10, -v60, v126, v10
	v_fma_f32 v74, -v59, v127, v74
	v_fma_f32 v12, -v57, v87, v12
	v_fma_f32 v11, -v51, v88, v11
	v_fma_f32 v10, -v58, v128, v10
	v_fma_f32 v74, -v50, v129, v74
	v_fma_f32 v12, -v3, v89, v12
	s_waitcnt lgkmcnt(10)
	v_fma_f32 v11, -v60, v94, v11
	v_fma_f32 v10, -v55, v134, v10
	v_fma_f32 v74, -v54, v135, v74
	v_fma_f32 v12, -v59, v95, v12
	v_fma_f32 v11, -v58, v96, v11
	v_fma_f32 v10, -v53, v136, v10
	v_fma_f32 v74, -v52, v137, v74
	v_fma_f32 v12, -v50, v97, v12
	s_waitcnt lgkmcnt(9)
	v_fma_f32 v11, -v55, v130, v11
	v_fma_f32 v10, -v49, v142, v10
	v_fma_f32 v74, -v48, v143, v74
	v_fma_f32 v12, -v54, v131, v12
	v_fma_f32 v11, -v53, v132, v11
	v_fma_f32 v10, -v47, v144, v10
	v_fma_f32 v74, -v46, v145, v74
	v_fma_f32 v12, -v52, v133, v12
	s_waitcnt lgkmcnt(8)
	v_fma_f32 v11, -v49, v138, v11
	v_fma_f32 v10, -v45, v150, v10
	v_fma_f32 v74, -v44, v151, v74
	v_fma_f32 v12, -v48, v139, v12
	v_fma_f32 v11, -v47, v140, v11
	v_fma_f32 v10, -v43, v152, v10
	v_fma_f32 v74, -v42, v153, v74
	v_fma_f32 v12, -v46, v141, v12
	s_waitcnt lgkmcnt(7)
	v_fma_f32 v11, -v45, v146, v11
	v_fma_f32 v10, -v41, v158, v10
	v_fma_f32 v74, -v40, v159, v74
	v_fma_f32 v12, -v44, v147, v12
	v_fma_f32 v11, -v43, v148, v11
	v_fma_f32 v10, -v39, v160, v10
	v_fma_f32 v74, -v38, v161, v74
	v_fma_f32 v12, -v42, v149, v12
	s_waitcnt lgkmcnt(6)
	v_fma_f32 v11, -v41, v154, v11
	v_fma_f32 v10, -v37, v166, v10
	v_fma_f32 v74, -v36, v167, v74
	v_fma_f32 v12, -v40, v155, v12
	v_fma_f32 v11, -v39, v156, v11
	v_fma_f32 v10, -v35, v168, v10
	v_fma_f32 v74, -v34, v169, v74
	v_fma_f32 v12, -v38, v157, v12
	s_waitcnt lgkmcnt(5)
	v_fma_f32 v11, -v37, v162, v11
	v_fma_f32 v10, -v33, v174, v10
	v_fma_f32 v74, -v32, v175, v74
	v_fma_f32 v12, -v36, v163, v12
	v_fma_f32 v11, -v35, v164, v11
	v_fma_f32 v10, -v31, v176, v10
	v_fma_f32 v74, -v30, v177, v74
	v_fma_f32 v12, -v34, v165, v12
	s_waitcnt lgkmcnt(4)
	v_fma_f32 v11, -v33, v170, v11
	v_fma_f32 v10, -v29, v182, v10
	v_fma_f32 v74, -v28, v183, v74
	v_fma_f32 v12, -v32, v171, v12
	v_fma_f32 v11, -v31, v172, v11
	v_fma_f32 v10, -v27, v184, v10
	v_fma_f32 v74, -v26, v185, v74
	v_fma_f32 v12, -v30, v173, v12
	s_waitcnt lgkmcnt(3)
	v_fma_f32 v11, -v29, v178, v11
	v_fma_f32 v10, -v25, v190, v10
	v_fma_f32 v74, -v24, v191, v74
	v_fma_f32 v12, -v28, v179, v12
	v_fma_f32 v11, -v27, v180, v11
	v_fma_f32 v10, -v23, v192, v10
	v_fma_f32 v74, -v22, v193, v74
	v_fma_f32 v12, -v26, v181, v12
	s_waitcnt lgkmcnt(2)
	v_fma_f32 v11, -v25, v186, v11
	v_add_f32_e32 v76, v125, v197
	v_fma_f32 v10, -v65, v202, v10
	v_fma_f32 v74, -v64, v203, v74
	v_fma_f32 v12, -v24, v187, v12
	v_fma_f32 v11, -v23, v188, v11
	v_fma_f32 v0, -v76, v0, v16
	v_fma_f32 v10, -v63, v204, v10
	v_fma_f32 v74, -v61, v205, v74
	v_fma_f32 v12, -v22, v189, v12
	s_waitcnt lgkmcnt(1)
	v_fma_f32 v11, -v65, v198, v11
	v_add_f32_e32 v75, v17, v0
	v_fma_f32 v12, -v64, v199, v12
	v_fma_f32 v11, -v63, v200, v11
	v_fma_f32 v0, -v76, v98, v10
	v_fma_f32 v10, -v75, v99, v74
	ds_read_b128 v[82:85], v110 offset:15232
	ds_read_b128 v[90:93], v110 offset:15248
	ds_read_b128 v[126:129], v110 offset:15264
	ds_read_b128 v[134:137], v110 offset:15280
	ds_read_b128 v[142:145], v110 offset:15296
	ds_read_b128 v[150:153], v110 offset:15312
	ds_read_b128 v[158:161], v110 offset:15328
	ds_read_b128 v[166:169], v110 offset:15344
	ds_read_b128 v[174:177], v110 offset:15360
	ds_read_b128 v[182:185], v110 offset:15376
	ds_read_b128 v[190:193], v110 offset:15392
	ds_read_b128 v[202:205], v110 offset:15408
	ds_read_b128 v[206:209], v110 offset:15424
	ds_read_b128 v[210:213], v110 offset:15440
	v_fma_f32 v12, -v61, v201, v12
	v_add_f32_e32 v74, v0, v10
	s_waitcnt lgkmcnt(14)
; DI void dn_solve_core(float (&x)[64], lf_t Ad) {
;     float4 cur[16], nxt[16];
;     cur[0] = *(const float4*)(Ad + 68);
; #pragma unroll
;     for (int pi = 1; pi < 64; ++pi) {
;         if (pi + 1 < 64) {
; #pragma unroll
;             for (int g4 = 0; g4 < (pi + 4) / 4; ++g4) nxt[g4] = *(const float4*)(Ad + (pi + 1) * 68 + 4 * g4);
;         }
;         float a = x[pi], a2 = 0.f;
; #pragma unroll
;         for (int g4 = 0; g4 < (pi + 3) / 4; ++g4) { const float4 av = cur[g4];
;             if (4 * g4 + 0 < pi) a -= av.x * x[4 * g4 + 0];
;             if (4 * g4 + 1 < pi) a2 -= av.y * x[4 * g4 + 1];
;             if (4 * g4 + 2 < pi) a -= av.z * x[4 * g4 + 2];
;             if (4 * g4 + 3 < pi) a2 -= av.w * x[4 * g4 + 3]; }
;         x[pi] = a + a2;
;         asm volatile("" ::: "memory");
; #pragma unroll
;         for (int g4 = 0; g4 < (pi + 4) / 4; ++g4) cur[g4] = nxt[g4];
;     }
; }
	v_fma_f32 v0, -v76, v214, v11
	s_waitcnt lgkmcnt(13)
	v_fma_f32 v8, -v2, v82, v8
	v_fma_f32 v10, -v75, v215, v12
	v_fma_f32 v0, -v74, v216, v0
	v_fma_f32 v8, -v72, v84, v8
	v_add_f32_e32 v11, v10, v0
	v_fma_f32 v10, -v73, v83, 0
	s_waitcnt lgkmcnt(12)
	v_fma_f32 v8, -v71, v90, v8
	v_fma_f32 v10, -v70, v85, v10
	v_fma_f32 v8, -v66, v92, v8
	v_fma_f32 v10, -v67, v91, v10
	s_waitcnt lgkmcnt(11)
	v_fma_f32 v8, -v62, v126, v8
	v_fma_f32 v10, -v56, v93, v10
	v_fma_f32 v8, -v51, v128, v8
	v_fma_f32 v10, -v57, v127, v10
	s_waitcnt lgkmcnt(10)
	v_fma_f32 v8, -v60, v134, v8
	v_fma_f32 v10, -v3, v129, v10
	v_fma_f32 v8, -v58, v136, v8
	v_fma_f32 v10, -v59, v135, v10
	s_waitcnt lgkmcnt(9)
	v_fma_f32 v8, -v55, v142, v8
	v_fma_f32 v10, -v50, v137, v10
	v_fma_f32 v8, -v53, v144, v8
	v_fma_f32 v10, -v54, v143, v10
	s_waitcnt lgkmcnt(8)
	v_fma_f32 v8, -v49, v150, v8
	v_fma_f32 v10, -v52, v145, v10
	v_fma_f32 v8, -v47, v152, v8
	v_fma_f32 v10, -v48, v151, v10
	s_waitcnt lgkmcnt(7)
	v_fma_f32 v8, -v45, v158, v8
	v_fma_f32 v10, -v46, v153, v10
	v_fma_f32 v8, -v43, v160, v8
	v_fma_f32 v10, -v44, v159, v10
	s_waitcnt lgkmcnt(6)
	v_fma_f32 v8, -v41, v166, v8
	v_fma_f32 v10, -v42, v161, v10
	v_fma_f32 v8, -v39, v168, v8
	v_fma_f32 v10, -v40, v167, v10
	s_waitcnt lgkmcnt(5)
	v_fma_f32 v8, -v37, v174, v8
	v_fma_f32 v10, -v38, v169, v10
	v_fma_f32 v8, -v35, v176, v8
	v_fma_f32 v10, -v36, v175, v10
	s_waitcnt lgkmcnt(4)
	v_fma_f32 v8, -v33, v182, v8
	v_fma_f32 v10, -v34, v177, v10
	v_fma_f32 v8, -v31, v184, v8
	v_fma_f32 v10, -v32, v183, v10
	s_waitcnt lgkmcnt(3)
	v_fma_f32 v8, -v29, v190, v8
	v_fma_f32 v10, -v30, v185, v10
	v_fma_f32 v8, -v27, v192, v8
	v_fma_f32 v10, -v28, v191, v10
	s_waitcnt lgkmcnt(2)
	v_fma_f32 v8, -v25, v202, v8
	v_fma_f32 v10, -v26, v193, v10
	v_fma_f32 v8, -v23, v204, v8
	v_fma_f32 v10, -v24, v203, v10
	s_waitcnt lgkmcnt(1)
	v_fma_f32 v8, -v65, v206, v8
	v_fma_f32 v10, -v22, v205, v10
	v_fma_f32 v8, -v63, v208, v8
	v_fma_f32 v10, -v64, v207, v10
	s_waitcnt lgkmcnt(0)
	v_fma_f32 v8, -v76, v210, v8
	ds_read_b128 v[12:15], v110 offset:15504
	ds_read_b128 v[78:81], v110 offset:15520
	ds_read_b128 v[86:89], v110 offset:15536
	ds_read_b128 v[94:97], v110 offset:15552
	ds_read_b128 v[130:133], v110 offset:15568
	ds_read_b128 v[138:141], v110 offset:15584
	ds_read_b128 v[146:149], v110 offset:15600
	ds_read_b128 v[154:157], v110 offset:15616
	ds_read_b128 v[162:165], v110 offset:15632
	ds_read_b128 v[170:173], v110 offset:15648
	ds_read_b128 v[178:181], v110 offset:15664
	ds_read_b128 v[186:189], v110 offset:15680
	ds_read_b128 v[198:201], v110 offset:15696
	ds_read_b128 v[214:217], v110 offset:15712
	ds_read_b32 v0, v110 offset:15728
	v_fma_f32 v10, -v61, v209, v10
	v_fma_f32 v77, -v74, v212, v8
	s_waitcnt lgkmcnt(14)
	v_fma_f32 v8, -v2, v12, v9
	v_fma_f32 v9, -v73, v13, 0
	v_fma_f32 v10, -v75, v211, v10
	v_fma_f32 v8, -v72, v14, v8
	v_fma_f32 v9, -v70, v15, v9
	v_fma_f32 v98, -v11, v213, v10
	ds_read_b128 v[82:85], v110 offset:15776
	ds_read_b128 v[90:93], v110 offset:15792
	ds_read_b128 v[126:129], v110 offset:15808
	ds_read_b128 v[134:137], v110 offset:15824
	ds_read_b128 v[142:145], v110 offset:15840
	ds_read_b128 v[150:153], v110 offset:15856
	ds_read_b128 v[158:161], v110 offset:15872
	ds_read_b128 v[166:169], v110 offset:15888
	ds_read_b128 v[174:177], v110 offset:15904
	ds_read_b128 v[182:185], v110 offset:15920
	ds_read_b128 v[190:193], v110 offset:15936
	ds_read_b128 v[202:205], v110 offset:15952
	ds_read_b128 v[206:209], v110 offset:15968
	ds_read_b128 v[210:213], v110 offset:15984
	ds_read_b64 v[16:17], v110 offset:16000
	s_waitcnt lgkmcnt(14)
	v_fma_f32 v8, -v71, v78, v8
	v_fma_f32 v9, -v67, v79, v9
	v_fma_f32 v8, -v66, v80, v8
	v_fma_f32 v9, -v56, v81, v9
	v_fma_f32 v6, -v2, v82, v6
	v_fma_f32 v82, -v73, v83, 0
	v_fma_f32 v8, -v62, v86, v8
	v_fma_f32 v9, -v57, v87, v9
	v_fma_f32 v6, -v72, v84, v6
	v_fma_f32 v82, -v70, v85, v82
	v_fma_f32 v8, -v51, v88, v8
	v_fma_f32 v9, -v3, v89, v9
	s_waitcnt lgkmcnt(13)
	v_fma_f32 v6, -v71, v90, v6
	v_fma_f32 v82, -v67, v91, v82
	v_fma_f32 v8, -v60, v94, v8
	v_fma_f32 v9, -v59, v95, v9
	v_fma_f32 v6, -v66, v92, v6
	v_fma_f32 v82, -v56, v93, v82
	v_fma_f32 v8, -v58, v96, v8
	v_fma_f32 v9, -v50, v97, v9
	s_waitcnt lgkmcnt(12)
	v_fma_f32 v6, -v62, v126, v6
	v_fma_f32 v82, -v57, v127, v82
	v_fma_f32 v8, -v55, v130, v8
	v_fma_f32 v9, -v54, v131, v9
	v_fma_f32 v6, -v51, v128, v6
	v_fma_f32 v82, -v3, v129, v82
	v_fma_f32 v8, -v53, v132, v8
	v_fma_f32 v9, -v52, v133, v9
	s_waitcnt lgkmcnt(11)
	v_fma_f32 v6, -v60, v134, v6
	v_fma_f32 v82, -v59, v135, v82
	v_fma_f32 v8, -v49, v138, v8
	v_fma_f32 v9, -v48, v139, v9
	v_fma_f32 v6, -v58, v136, v6
	v_fma_f32 v82, -v50, v137, v82
	v_fma_f32 v8, -v47, v140, v8
	v_fma_f32 v9, -v46, v141, v9
	s_waitcnt lgkmcnt(10)
	v_fma_f32 v6, -v55, v142, v6
	v_fma_f32 v82, -v54, v143, v82
	v_fma_f32 v8, -v45, v146, v8
	v_fma_f32 v9, -v44, v147, v9
	v_fma_f32 v6, -v53, v144, v6
	v_fma_f32 v82, -v52, v145, v82
	v_fma_f32 v8, -v43, v148, v8
	v_fma_f32 v9, -v42, v149, v9
	s_waitcnt lgkmcnt(9)
	v_fma_f32 v6, -v49, v150, v6
	v_fma_f32 v82, -v48, v151, v82
	v_fma_f32 v8, -v41, v154, v8
	v_fma_f32 v9, -v40, v155, v9
	v_fma_f32 v6, -v47, v152, v6
	v_fma_f32 v82, -v46, v153, v82
	v_fma_f32 v8, -v39, v156, v8
	v_fma_f32 v9, -v38, v157, v9
	s_waitcnt lgkmcnt(8)
	v_fma_f32 v6, -v45, v158, v6
	v_fma_f32 v82, -v44, v159, v82
	v_fma_f32 v8, -v37, v162, v8
	v_fma_f32 v9, -v36, v163, v9
	v_fma_f32 v6, -v43, v160, v6
	v_fma_f32 v82, -v42, v161, v82
	v_fma_f32 v8, -v35, v164, v8
	v_fma_f32 v9, -v34, v165, v9
	s_waitcnt lgkmcnt(7)
; DI void dn_solve_core(float (&x)[64], lf_t Ad) {
;     float4 cur[16], nxt[16];
;     cur[0] = *(const float4*)(Ad + 68);
; #pragma unroll
;     for (int pi = 1; pi < 64; ++pi) {
;         if (pi + 1 < 64) {
; #pragma unroll
;             for (int g4 = 0; g4 < (pi + 4) / 4; ++g4) nxt[g4] = *(const float4*)(Ad + (pi + 1) * 68 + 4 * g4);
;         }
;         float a = x[pi], a2 = 0.f;
; #pragma unroll
;         for (int g4 = 0; g4 < (pi + 3) / 4; ++g4) { const float4 av = cur[g4];
;             if (4 * g4 + 0 < pi) a -= av.x * x[4 * g4 + 0];
;             if (4 * g4 + 1 < pi) a2 -= av.y * x[4 * g4 + 1];
;             if (4 * g4 + 2 < pi) a -= av.z * x[4 * g4 + 2];
;             if (4 * g4 + 3 < pi) a2 -= av.w * x[4 * g4 + 3]; }
;         x[pi] = a + a2;
;         asm volatile("" ::: "memory");
; #pragma unroll
;         for (int g4 = 0; g4 < (pi + 4) / 4; ++g4) cur[g4] = nxt[g4];
;     }
; }
	v_fma_f32 v6, -v41, v166, v6
	v_fma_f32 v82, -v40, v167, v82
	v_fma_f32 v8, -v33, v170, v8
	v_fma_f32 v9, -v32, v171, v9
	v_fma_f32 v6, -v39, v168, v6
	v_fma_f32 v82, -v38, v169, v82
	v_fma_f32 v8, -v31, v172, v8
	v_fma_f32 v9, -v30, v173, v9
	s_waitcnt lgkmcnt(6)
	v_fma_f32 v6, -v37, v174, v6
	v_fma_f32 v82, -v36, v175, v82
	v_fma_f32 v8, -v29, v178, v8
	v_fma_f32 v9, -v28, v179, v9
	v_fma_f32 v6, -v35, v176, v6
	v_fma_f32 v82, -v34, v177, v82
	v_fma_f32 v8, -v27, v180, v8
	v_fma_f32 v9, -v26, v181, v9
	s_waitcnt lgkmcnt(5)
	v_fma_f32 v6, -v33, v182, v6
	v_fma_f32 v82, -v32, v183, v82
	v_fma_f32 v8, -v25, v186, v8
	v_fma_f32 v9, -v24, v187, v9
	v_fma_f32 v6, -v31, v184, v6
	v_fma_f32 v82, -v30, v185, v82
	v_fma_f32 v8, -v23, v188, v8
	v_fma_f32 v9, -v22, v189, v9
	s_waitcnt lgkmcnt(4)
	v_fma_f32 v6, -v29, v190, v6
	v_fma_f32 v82, -v28, v191, v82
	v_fma_f32 v8, -v65, v198, v8
	v_fma_f32 v9, -v64, v199, v9
	v_fma_f32 v6, -v27, v192, v6
	v_fma_f32 v82, -v26, v193, v82
	v_fma_f32 v8, -v63, v200, v8
	v_fma_f32 v9, -v61, v201, v9
	s_waitcnt lgkmcnt(3)
	v_fma_f32 v6, -v25, v202, v6
	v_fma_f32 v82, -v24, v203, v82
	v_fma_f32 v8, -v76, v214, v8
	v_fma_f32 v9, -v75, v215, v9
	v_fma_f32 v6, -v23, v204, v6
	v_fma_f32 v82, -v22, v205, v82
	v_fma_f32 v99, -v74, v216, v8
	v_fma_f32 v125, -v11, v217, v9
	ds_read_b128 v[12:15], v110 offset:16048
	ds_read_b128 v[78:81], v110 offset:16064
	ds_read_b128 v[86:89], v110 offset:16080
	ds_read_b128 v[94:97], v110 offset:16096
	ds_read_b128 v[130:133], v110 offset:16112
	ds_read_b128 v[138:141], v110 offset:16128
	ds_read_b128 v[146:149], v110 offset:16144
	ds_read_b128 v[154:157], v110 offset:16160
	ds_read_b128 v[162:165], v110 offset:16176
	ds_read_b128 v[170:173], v110 offset:16192
	ds_read_b128 v[178:181], v110 offset:16208
	ds_read_b128 v[186:189], v110 offset:16224
	ds_read_b128 v[198:201], v110 offset:16240
	ds_read_b128 v[214:217], v110 offset:16256
	ds_read_b96 v[8:10], v110 offset:16272
	s_waitcnt lgkmcnt(14)
	v_fma_f32 v6, -v65, v206, v6
	v_fma_f32 v82, -v64, v207, v82
	v_fma_f32 v7, -v2, v12, v7
	v_fma_f32 v6, -v63, v208, v6
	v_fma_f32 v82, -v61, v209, v82
	v_fma_f32 v7, -v72, v14, v7
	v_fma_f32 v6, -v76, v210, v6
	v_fma_f32 v82, -v75, v211, v82
	s_waitcnt lgkmcnt(13)
	v_fma_f32 v7, -v71, v78, v7
	v_fma_f32 v6, -v74, v212, v6
	v_fma_f32 v197, -v11, v213, v82
	ds_read_b128 v[82:85], v110 offset:16320
	ds_read_b128 v[90:93], v110 offset:16336
	ds_read_b128 v[126:129], v110 offset:16352
	ds_read_b128 v[134:137], v110 offset:16368
	ds_read_b128 v[142:145], v110 offset:16384
	ds_read_b128 v[150:153], v110 offset:16400
	ds_read_b128 v[158:161], v110 offset:16416
	ds_read_b128 v[166:169], v110 offset:16432
	ds_read_b128 v[174:177], v110 offset:16448
	ds_read_b128 v[182:185], v110 offset:16464
	ds_read_b128 v[190:193], v110 offset:16480
	ds_read_b128 v[202:205], v110 offset:16496
	ds_read_b128 v[206:209], v110 offset:16512
	ds_read_b128 v[210:213], v110 offset:16528
	ds_read_b128 v[218:221], v110 offset:16544
	v_fma_f32 v12, -v73, v13, 0
	v_fma_f32 v7, -v66, v80, v7
	s_waitcnt lgkmcnt(14)
	v_fma_f32 v4, -v2, v82, v4
	v_fma_f32 v12, -v70, v15, v12
	v_fma_f32 v7, -v62, v86, v7
	v_fma_f32 v4, -v72, v84, v4
	v_fma_f32 v12, -v67, v79, v12
	v_fma_f32 v7, -v51, v88, v7
	s_waitcnt lgkmcnt(13)
	v_fma_f32 v4, -v71, v90, v4
	v_fma_f32 v12, -v56, v81, v12
	v_fma_f32 v7, -v60, v94, v7
	v_fma_f32 v4, -v66, v92, v4
	v_fma_f32 v12, -v57, v87, v12
	v_fma_f32 v7, -v58, v96, v7
	s_waitcnt lgkmcnt(12)
	v_fma_f32 v4, -v62, v126, v4
	v_fma_f32 v12, -v3, v89, v12
	v_fma_f32 v7, -v55, v130, v7
	v_fma_f32 v4, -v51, v128, v4
	v_fma_f32 v12, -v59, v95, v12
	v_fma_f32 v7, -v53, v132, v7
	s_waitcnt lgkmcnt(11)
	v_fma_f32 v4, -v60, v134, v4
	v_fma_f32 v12, -v50, v97, v12
	v_fma_f32 v7, -v49, v138, v7
	v_fma_f32 v4, -v58, v136, v4
	v_fma_f32 v12, -v54, v131, v12
	v_fma_f32 v7, -v47, v140, v7
	s_waitcnt lgkmcnt(10)
	v_fma_f32 v4, -v55, v142, v4
	v_fma_f32 v12, -v52, v133, v12
	v_fma_f32 v7, -v45, v146, v7
	v_fma_f32 v4, -v53, v144, v4
	v_fma_f32 v12, -v48, v139, v12
	v_fma_f32 v7, -v43, v148, v7
	s_waitcnt lgkmcnt(9)
	v_fma_f32 v4, -v49, v150, v4
	v_fma_f32 v12, -v46, v141, v12
	v_fma_f32 v7, -v41, v154, v7
	v_fma_f32 v4, -v47, v152, v4
	v_fma_f32 v12, -v44, v147, v12
	v_fma_f32 v7, -v39, v156, v7
	s_waitcnt lgkmcnt(8)
	v_fma_f32 v4, -v45, v158, v4
	v_fma_f32 v12, -v42, v149, v12
	v_fma_f32 v7, -v37, v162, v7
	v_fma_f32 v4, -v43, v160, v4
	v_fma_f32 v12, -v40, v155, v12
	v_fma_f32 v7, -v35, v164, v7
	s_waitcnt lgkmcnt(7)
	v_fma_f32 v4, -v41, v166, v4
	v_fma_f32 v12, -v38, v157, v12
	v_fma_f32 v7, -v33, v170, v7
	v_fma_f32 v4, -v39, v168, v4
	v_fma_f32 v12, -v36, v163, v12
	v_fma_f32 v7, -v31, v172, v7
	s_waitcnt lgkmcnt(6)
	v_fma_f32 v4, -v37, v174, v4
	v_fma_f32 v12, -v34, v165, v12
	v_fma_f32 v7, -v29, v178, v7
	v_fma_f32 v4, -v35, v176, v4
	v_fma_f32 v12, -v32, v171, v12
	v_fma_f32 v7, -v27, v180, v7
	s_waitcnt lgkmcnt(5)
	v_fma_f32 v4, -v33, v182, v4
	v_fma_f32 v12, -v30, v173, v12
	v_fma_f32 v7, -v25, v186, v7
	v_fma_f32 v4, -v31, v184, v4
	v_fma_f32 v12, -v28, v179, v12
	v_fma_f32 v7, -v23, v188, v7
	s_waitcnt lgkmcnt(4)
	v_fma_f32 v4, -v29, v190, v4
	v_fma_f32 v12, -v26, v181, v12
	v_fma_f32 v7, -v65, v198, v7
	v_add_f32_e32 v80, v77, v98
	v_fma_f32 v4, -v27, v192, v4
	v_fma_f32 v12, -v24, v187, v12
	v_fma_f32 v7, -v63, v200, v7
	v_fma_f32 v0, -v80, v0, v99
	s_waitcnt lgkmcnt(3)
	v_fma_f32 v4, -v25, v202, v4
	v_fma_f32 v12, -v22, v189, v12
	v_fma_f32 v7, -v76, v214, v7
	v_add_f32_e32 v79, v125, v0
	v_fma_f32 v4, -v23, v204, v4
	v_fma_f32 v12, -v64, v199, v12
	v_fma_f32 v7, -v74, v216, v7
	v_fma_f32 v0, -v80, v16, v6
	v_fma_f32 v6, -v79, v17, v197
	s_waitcnt lgkmcnt(2)
; DI void dn_solve_core(float (&x)[64], lf_t Ad) {
;     float4 cur[16], nxt[16];
;     cur[0] = *(const float4*)(Ad + 68);
; #pragma unroll
;     for (int pi = 1; pi < 64; ++pi) {
;         if (pi + 1 < 64) {
; #pragma unroll
;             for (int g4 = 0; g4 < (pi + 4) / 4; ++g4) nxt[g4] = *(const float4*)(Ad + (pi + 1) * 68 + 4 * g4);
;         }
;         float a = x[pi], a2 = 0.f;
; #pragma unroll
;         for (int g4 = 0; g4 < (pi + 3) / 4; ++g4) { const float4 av = cur[g4];
;             if (4 * g4 + 0 < pi) a -= av.x * x[4 * g4 + 0];
;             if (4 * g4 + 1 < pi) a2 -= av.y * x[4 * g4 + 1];
;             if (4 * g4 + 2 < pi) a -= av.z * x[4 * g4 + 2];
;             if (4 * g4 + 3 < pi) a2 -= av.w * x[4 * g4 + 3]; }
;         x[pi] = a + a2;
;         asm volatile("" ::: "memory");
; #pragma unroll
;         for (int g4 = 0; g4 < (pi + 4) / 4; ++g4) cur[g4] = nxt[g4];
;     }
; }
	v_fma_f32 v4, -v65, v206, v4
	v_fma_f32 v12, -v61, v201, v12
	v_add_f32_e32 v78, v0, v6
	v_fma_f32 v0, -v80, v8, v7
	v_fma_f32 v4, -v63, v208, v4
	v_fma_f32 v12, -v75, v215, v12
	v_fma_f32 v0, -v78, v10, v0
	v_fma_f32 v10, -v73, v83, 0
	s_waitcnt lgkmcnt(1)
	v_fma_f32 v4, -v76, v210, v4
	v_fma_f32 v12, -v11, v217, v12
	v_fma_f32 v10, -v70, v85, v10
	v_fma_f32 v4, -v74, v212, v4
	v_fma_f32 v6, -v79, v9, v12
	v_fma_f32 v10, -v67, v91, v10
	s_waitcnt lgkmcnt(0)
	v_fma_f32 v4, -v80, v218, v4
	v_add_f32_e32 v77, v6, v0
	ds_read_b128 v[6:9], v110 offset:16592
	ds_read_b128 v[12:15], v110 offset:16608
	ds_read_b128 v[86:89], v110 offset:16624
	ds_read_b128 v[94:97], v110 offset:16640
	ds_read_b128 v[130:133], v110 offset:16656
	ds_read_b128 v[138:141], v110 offset:16672
	ds_read_b128 v[146:149], v110 offset:16688
	ds_read_b128 v[154:157], v110 offset:16704
	ds_read_b128 v[162:165], v110 offset:16720
	ds_read_b128 v[170:173], v110 offset:16736
	ds_read_b128 v[178:181], v110 offset:16752
	ds_read_b128 v[186:189], v110 offset:16768
	ds_read_b128 v[198:201], v110 offset:16784
	ds_read_b128 v[214:217], v110 offset:16800
	ds_read_b128 v[222:225], v110 offset:16816
	ds_read_b32 v0, v110 offset:16832
	v_fma_f32 v10, -v56, v93, v10
	v_fma_f32 v81, -v78, v220, v4
	s_waitcnt lgkmcnt(14)
	v_fma_f32 v4, -v2, v6, v5
	v_fma_f32 v5, -v73, v7, 0
	v_fma_f32 v10, -v57, v127, v10
	v_fma_f32 v4, -v72, v8, v4
	v_fma_f32 v5, -v70, v9, v5
	v_fma_f32 v10, -v3, v129, v10
	v_fma_f32 v4, -v71, v12, v4
	v_fma_f32 v5, -v67, v13, v5
	v_fma_f32 v10, -v59, v135, v10
	v_fma_f32 v4, -v66, v14, v4
	v_fma_f32 v5, -v56, v15, v5
	v_fma_f32 v10, -v50, v137, v10
	s_waitcnt lgkmcnt(13)
	v_fma_f32 v4, -v62, v86, v4
	v_fma_f32 v5, -v57, v87, v5
	v_fma_f32 v10, -v54, v143, v10
	v_fma_f32 v4, -v51, v88, v4
	v_fma_f32 v5, -v3, v89, v5
	v_fma_f32 v10, -v52, v145, v10
	s_waitcnt lgkmcnt(12)
	v_fma_f32 v4, -v60, v94, v4
	v_fma_f32 v5, -v59, v95, v5
	v_fma_f32 v10, -v48, v151, v10
	v_fma_f32 v4, -v58, v96, v4
	v_fma_f32 v5, -v50, v97, v5
	v_fma_f32 v10, -v46, v153, v10
	s_waitcnt lgkmcnt(11)
	v_fma_f32 v4, -v55, v130, v4
	v_fma_f32 v5, -v54, v131, v5
	v_fma_f32 v10, -v44, v159, v10
	v_fma_f32 v4, -v53, v132, v4
	v_fma_f32 v5, -v52, v133, v5
	v_fma_f32 v10, -v42, v161, v10
	s_waitcnt lgkmcnt(10)
	v_fma_f32 v4, -v49, v138, v4
	v_fma_f32 v5, -v48, v139, v5
	v_fma_f32 v10, -v40, v167, v10
	v_fma_f32 v4, -v47, v140, v4
	v_fma_f32 v5, -v46, v141, v5
	v_fma_f32 v10, -v38, v169, v10
	s_waitcnt lgkmcnt(9)
	v_fma_f32 v4, -v45, v146, v4
	v_fma_f32 v5, -v44, v147, v5
	v_fma_f32 v10, -v36, v175, v10
	v_fma_f32 v4, -v43, v148, v4
	v_fma_f32 v5, -v42, v149, v5
	v_fma_f32 v10, -v34, v177, v10
	s_waitcnt lgkmcnt(8)
	v_fma_f32 v4, -v41, v154, v4
	v_fma_f32 v5, -v40, v155, v5
	v_fma_f32 v10, -v32, v183, v10
	v_fma_f32 v4, -v39, v156, v4
	v_fma_f32 v5, -v38, v157, v5
	v_fma_f32 v10, -v30, v185, v10
	s_waitcnt lgkmcnt(7)
	v_fma_f32 v4, -v37, v162, v4
	v_fma_f32 v5, -v36, v163, v5
	v_fma_f32 v10, -v28, v191, v10
	v_fma_f32 v4, -v35, v164, v4
	v_fma_f32 v5, -v34, v165, v5
	v_fma_f32 v10, -v26, v193, v10
	s_waitcnt lgkmcnt(6)
	v_fma_f32 v4, -v33, v170, v4
	v_fma_f32 v5, -v32, v171, v5
	v_fma_f32 v10, -v24, v203, v10
	v_fma_f32 v4, -v31, v172, v4
	v_fma_f32 v5, -v30, v173, v5
	v_fma_f32 v10, -v22, v205, v10
	s_waitcnt lgkmcnt(5)
	v_fma_f32 v4, -v29, v178, v4
	v_fma_f32 v5, -v28, v179, v5
	v_fma_f32 v10, -v64, v207, v10
	v_fma_f32 v4, -v27, v180, v4
	v_fma_f32 v5, -v26, v181, v5
	v_fma_f32 v10, -v61, v209, v10
	s_waitcnt lgkmcnt(4)
	v_fma_f32 v4, -v25, v186, v4
	v_fma_f32 v5, -v24, v187, v5
	v_fma_f32 v10, -v75, v211, v10
	v_fma_f32 v4, -v23, v188, v4
	v_fma_f32 v5, -v22, v189, v5
	v_fma_f32 v10, -v11, v213, v10
	s_waitcnt lgkmcnt(3)
	v_fma_f32 v4, -v65, v198, v4
	v_fma_f32 v5, -v64, v199, v5
	v_fma_f32 v10, -v79, v219, v10
	v_fma_f32 v4, -v63, v200, v4
	v_fma_f32 v5, -v61, v201, v5
	v_fma_f32 v98, -v77, v221, v10
	ds_read_b128 v[82:85], v110 offset:16864
	ds_read_b128 v[90:93], v110 offset:16880
	ds_read_b128 v[126:129], v110 offset:16896
	ds_read_b128 v[134:137], v110 offset:16912
	ds_read_b128 v[142:145], v110 offset:16928
	ds_read_b128 v[150:153], v110 offset:16944
	ds_read_b128 v[158:161], v110 offset:16960
	ds_read_b128 v[166:169], v110 offset:16976
	ds_read_b128 v[174:177], v110 offset:16992
	ds_read_b128 v[182:185], v110 offset:17008
	ds_read_b128 v[190:193], v110 offset:17024
	ds_read_b128 v[202:205], v110 offset:17040
	ds_read_b128 v[206:209], v110 offset:17056
	ds_read_b128 v[210:213], v110 offset:17072
	ds_read_b128 v[218:221], v110 offset:17088
	ds_read_b64 v[16:17], v110 offset:17104
	s_waitcnt lgkmcnt(14)
	v_fma_f32 v4, -v76, v214, v4
	v_fma_f32 v5, -v75, v215, v5
	v_fma_f32 v4, -v74, v216, v4
	v_fma_f32 v5, -v11, v217, v5
	v_fma_f32 v68, -v2, v82, v68
	v_fma_f32 v82, -v73, v83, 0
	v_fma_f32 v4, -v80, v222, v4
	v_fma_f32 v5, -v79, v223, v5
	v_fma_f32 v82, -v70, v85, v82
	v_fma_f32 v99, -v78, v224, v4
	v_fma_f32 v125, -v77, v225, v5
	ds_read_b128 v[4:7], v110 offset:17136
	ds_read_b128 v[12:15], v110 offset:17152
	ds_read_b128 v[86:89], v110 offset:17168
	ds_read_b128 v[94:97], v110 offset:17184
	ds_read_b128 v[130:133], v110 offset:17200
	ds_read_b128 v[138:141], v110 offset:17216
	ds_read_b128 v[146:149], v110 offset:17232
	ds_read_b128 v[154:157], v110 offset:17248
	ds_read_b128 v[162:165], v110 offset:17264
	ds_read_b128 v[170:173], v110 offset:17280
	ds_read_b128 v[178:181], v110 offset:17296
	ds_read_b128 v[186:189], v110 offset:17312
	ds_read_b128 v[198:201], v110 offset:17328
	ds_read_b128 v[214:217], v110 offset:17344
	ds_read_b128 v[222:225], v110 offset:17360
	ds_read_b96 v[8:10], v110 offset:17376
	v_fma_f32 v82, -v67, v91, v82
	v_fma_f32 v68, -v72, v84, v68
	v_fma_f32 v82, -v56, v93, v82
	s_waitcnt lgkmcnt(14)
; DI uint4 pack8(const float* f) { uint4 o; o.x = pk2(f[0], f[1]); o.y = pk2(f[2], f[3]); o.z = pk2(f[4], f[5]); o.w = pk2(f[6], f[7]); return o; }
; DI void dn_solve_core(float (&x)[64], lf_t Ad) {
;     ...
;     for (int pi = 1; pi < 64; ++pi) {
;         if (pi + 1 < 64) {
; #pragma unroll
;             for (int g4 = 0; g4 < (pi + 4) / 4; ++g4) nxt[g4] = *(const float4*)(Ad + (pi + 1) * 68 + 4 * g4);
;         }
;         float a = x[pi], a2 = 0.f;
; #pragma unroll
;         for (int g4 = 0; g4 < (pi + 3) / 4; ++g4) { const float4 av = cur[g4];
;             if (4 * g4 + 0 < pi) a -= av.x * x[4 * g4 + 0];
;             if (4 * g4 + 1 < pi) a2 -= av.y * x[4 * g4 + 1];
;             if (4 * g4 + 2 < pi) a -= av.z * x[4 * g4 + 2];
;             if (4 * g4 + 3 < pi) a2 -= av.w * x[4 * g4 + 3]; }
;         x[pi] = a + a2;
;         asm volatile("" ::: "memory");
; #pragma unroll
;         for (int g4 = 0; g4 < (pi + 4) / 4; ++g4) cur[g4] = nxt[g4];
;     }
; }
; template <int D> DI void dn_out(float (&x)[64], lf_t Kl, lf_t Ql, lf_t Gn, bf16_t* DW, bf16_t* DQE, bf16_t* DKT, bf16_t* DUT, float* DEG, int item, int t) {
;     ...
;             if (t < 128) { bf16_t* uo = DUT + (((size_t)D * 1152 + item) * 128 + t) * 64;
; #pragma unroll
;                 for (int g8 = 0; g8 < 8; ++g8) *(uint4*)(uo + 8 * g8) = pack8(x + 8 * g8);
;             } else { bf16_t* wbase = DW + (((size_t)D * 1152 + item) * 64) * 128; unsigned woff = (unsigned)((t - 128) * 2);
	v_fma_f32 v4, -v2, v4, v69
	v_fma_f32 v68, -v71, v90, v68
	v_fma_f32 v82, -v57, v127, v82
	v_fma_f32 v5, -v73, v5, 0
	v_fma_f32 v4, -v72, v6, v4
	v_fma_f32 v68, -v66, v92, v68
	v_fma_f32 v82, -v3, v129, v82
	v_fma_f32 v5, -v70, v7, v5
	v_fma_f32 v4, -v71, v12, v4
	v_fma_f32 v68, -v62, v126, v68
	v_fma_f32 v82, -v59, v135, v82
	v_fma_f32 v5, -v67, v13, v5
	v_fma_f32 v4, -v66, v14, v4
	v_fma_f32 v68, -v51, v128, v68
	v_fma_f32 v82, -v50, v137, v82
	v_fma_f32 v5, -v56, v15, v5
	s_waitcnt lgkmcnt(13)
	v_fma_f32 v4, -v62, v86, v4
	v_fma_f32 v68, -v60, v134, v68
	v_fma_f32 v82, -v54, v143, v82
	v_fma_f32 v5, -v57, v87, v5
	v_fma_f32 v4, -v51, v88, v4
	v_fma_f32 v68, -v58, v136, v68
	v_fma_f32 v82, -v52, v145, v82
	v_fma_f32 v5, -v3, v89, v5
	s_waitcnt lgkmcnt(12)
	v_fma_f32 v4, -v60, v94, v4
	v_fma_f32 v68, -v55, v142, v68
	v_fma_f32 v82, -v48, v151, v82
	v_fma_f32 v5, -v59, v95, v5
	v_fma_f32 v4, -v58, v96, v4
	v_fma_f32 v68, -v53, v144, v68
	v_fma_f32 v82, -v46, v153, v82
	v_fma_f32 v5, -v50, v97, v5
	s_waitcnt lgkmcnt(11)
	v_fma_f32 v4, -v55, v130, v4
	v_fma_f32 v68, -v49, v150, v68
	v_fma_f32 v82, -v44, v159, v82
	v_fma_f32 v5, -v54, v131, v5
	v_fma_f32 v4, -v53, v132, v4
	v_fma_f32 v68, -v47, v152, v68
	v_fma_f32 v82, -v42, v161, v82
	v_fma_f32 v5, -v52, v133, v5
	s_waitcnt lgkmcnt(10)
	v_fma_f32 v4, -v49, v138, v4
	v_fma_f32 v68, -v45, v158, v68
	v_fma_f32 v82, -v40, v167, v82
	v_fma_f32 v5, -v48, v139, v5
	v_fma_f32 v4, -v47, v140, v4
	v_fma_f32 v68, -v43, v160, v68
	v_fma_f32 v82, -v38, v169, v82
	v_fma_f32 v5, -v46, v141, v5
	s_waitcnt lgkmcnt(9)
	v_fma_f32 v4, -v45, v146, v4
	v_fma_f32 v68, -v41, v166, v68
	v_fma_f32 v82, -v36, v175, v82
	v_fma_f32 v5, -v44, v147, v5
	v_fma_f32 v4, -v43, v148, v4
	v_fma_f32 v68, -v39, v168, v68
	v_fma_f32 v82, -v34, v177, v82
	v_fma_f32 v5, -v42, v149, v5
	s_waitcnt lgkmcnt(8)
	v_fma_f32 v4, -v41, v154, v4
	v_fma_f32 v68, -v37, v174, v68
	v_fma_f32 v82, -v32, v183, v82
	v_fma_f32 v5, -v40, v155, v5
	v_fma_f32 v4, -v39, v156, v4
	v_fma_f32 v68, -v35, v176, v68
	v_fma_f32 v82, -v30, v185, v82
	v_fma_f32 v5, -v38, v157, v5
	s_waitcnt lgkmcnt(7)
	v_fma_f32 v4, -v37, v162, v4
	v_fma_f32 v68, -v33, v182, v68
	v_fma_f32 v82, -v28, v191, v82
	v_fma_f32 v5, -v36, v163, v5
	v_fma_f32 v4, -v35, v164, v4
	v_fma_f32 v68, -v31, v184, v68
	v_fma_f32 v82, -v26, v193, v82
	v_fma_f32 v5, -v34, v165, v5
	s_waitcnt lgkmcnt(6)
	v_fma_f32 v4, -v33, v170, v4
	v_fma_f32 v68, -v29, v190, v68
	v_fma_f32 v82, -v24, v203, v82
	v_fma_f32 v5, -v32, v171, v5
	v_fma_f32 v4, -v31, v172, v4
	v_fma_f32 v68, -v27, v192, v68
	v_fma_f32 v82, -v22, v205, v82
	v_fma_f32 v5, -v30, v173, v5
	s_waitcnt lgkmcnt(5)
	v_fma_f32 v4, -v29, v178, v4
	v_fma_f32 v68, -v25, v202, v68
	v_fma_f32 v82, -v64, v207, v82
	v_fma_f32 v5, -v28, v179, v5
	v_fma_f32 v4, -v27, v180, v4
	v_fma_f32 v68, -v23, v204, v68
	v_fma_f32 v82, -v61, v209, v82
	v_fma_f32 v5, -v26, v181, v5
	s_waitcnt lgkmcnt(4)
	v_fma_f32 v4, -v25, v186, v4
	v_fma_f32 v68, -v65, v206, v68
	v_fma_f32 v82, -v75, v211, v82
	v_fma_f32 v5, -v24, v187, v5
	v_fma_f32 v4, -v23, v188, v4
	v_fma_f32 v68, -v63, v208, v68
	v_fma_f32 v82, -v11, v213, v82
	v_fma_f32 v5, -v22, v189, v5
	s_waitcnt lgkmcnt(3)
	v_fma_f32 v4, -v65, v198, v4
	v_fma_f32 v68, -v76, v210, v68
	v_fma_f32 v82, -v79, v219, v82
	v_fma_f32 v5, -v64, v199, v5
	v_fma_f32 v4, -v63, v200, v4
	v_fma_f32 v68, -v74, v212, v68
	v_fma_f32 v83, -v77, v221, v82
	v_fma_f32 v5, -v61, v201, v5
	s_waitcnt lgkmcnt(2)
	v_fma_f32 v4, -v76, v214, v4
	v_add_f32_e32 v82, v81, v98
	v_fma_f32 v68, -v80, v218, v68
	v_fma_f32 v5, -v75, v215, v5
	v_fma_f32 v4, -v74, v216, v4
	v_fma_f32 v0, -v82, v0, v99
	v_fma_f32 v68, -v78, v220, v68
	v_fma_f32 v5, -v11, v217, v5
	s_waitcnt lgkmcnt(1)
	v_fma_f32 v4, -v80, v222, v4
	v_add_f32_e32 v81, v125, v0
	v_fma_f32 v5, -v79, v223, v5
	v_fma_f32 v4, -v78, v224, v4
	v_fma_f32 v0, -v82, v16, v68
	v_fma_f32 v6, -v81, v17, v83
	v_fma_f32 v5, -v77, v225, v5
	v_add_f32_e32 v69, v0, v6
	s_waitcnt lgkmcnt(0)
	v_fma_f32 v0, -v82, v8, v4
	v_fma_f32 v4, -v81, v9, v5
	v_fma_f32 v0, -v69, v10, v0
	v_add_f32_e32 v68, v4, v0
	s_mov_b64 s[20:21], -1
	s_and_b64 vcc, exec, s[50:51]
	s_cbranch_vccz .LBB0_662
	v_mov_b32_e32 v4, v107
	s_movk_i32 s4, 0x7f
	s_add_i32 s20, s38, 0x480
	s_ashr_i32 s21, s20, 31
	v_cmp_lt_i32_e32 vcc, s4, v4
	s_and_saveexec_b64 s[28:29], vcc
	s_xor_b64 s[44:45], exec, s[28:29]
	s_cbranch_execz .LBB0_657
; DI unsigned f2bf(float f) { unsigned u = __float_as_uint(f); return (u + 0x7fffu + ((u >> 16) & 1u)) >> 16; }
; template <int D> DI void dn_out(float (&x)[64], lf_t Kl, lf_t Ql, lf_t Gn, bf16_t* DW, bf16_t* DQE, bf16_t* DKT, bf16_t* DUT, float* DEG, int item, int t) {
;     ...
;             } else { bf16_t* wbase = DW + (((size_t)D * 1152 + item) * 64) * 128; unsigned woff = (unsigned)((t - 128) * 2);
; #pragma unroll
;                 for (int pi = 0; pi < 64; ++pi) { *(bf16_t*)((char*)wbase + woff) = (bf16_t)f2bf(x[pi]); woff += 256; asm volatile("" : "+v"(woff)); } }
	s_lshl_b64 s[42:43], s[20:21], 14
	s_add_u32 vcc_lo, s63, s42
	v_lshrrev_b32_e32 v0, 3, v4
	v_and_b32_e32 v5, 7, v4
	v_lshlrev_b32_e32 v0, 8, v0
	v_lshl_add_u32 v0, v5, 1, v0
	v_bfe_u32 v6, v2, 16, 1
	s_addc_u32 vcc_hi, s73, s43
	v_add_u32_e32 v5, 0xfffff000, v0
	v_add_u32_e32 v0, 0xfffff010, v0
	v_add3_u32 v6, v2, v6, s71
	global_store_short_d16_hi v5, v6, vcc
	v_bfe_u32 v5, v73, 16, 1
	v_add3_u32 v5, v73, v5, s71
	global_store_short_d16_hi v0, v5, vcc
	v_add_u32_e32 v0, 16, v0
	v_bfe_u32 v5, v72, 16, 1
	v_add3_u32 v5, v72, v5, s71
	global_store_short_d16_hi v0, v5, vcc
	v_add_u32_e32 v0, 16, v0
	v_bfe_u32 v5, v70, 16, 1
	v_add3_u32 v5, v70, v5, s71
	global_store_short_d16_hi v0, v5, vcc
	v_add_u32_e32 v0, 16, v0
	v_bfe_u32 v5, v71, 16, 1
	v_add3_u32 v5, v71, v5, s71
	global_store_short_d16_hi v0, v5, vcc
	v_add_u32_e32 v0, 16, v0
	v_bfe_u32 v5, v67, 16, 1
	v_add3_u32 v5, v67, v5, s71
	global_store_short_d16_hi v0, v5, vcc
	v_add_u32_e32 v0, 16, v0
	v_bfe_u32 v5, v66, 16, 1
	v_add3_u32 v5, v66, v5, s71
	global_store_short_d16_hi v0, v5, vcc
	v_add_u32_e32 v0, 16, v0
	v_bfe_u32 v5, v56, 16, 1
	v_add3_u32 v5, v56, v5, s71
	global_store_short_d16_hi v0, v5, vcc
	v_add_u32_e32 v0, 16, v0
	v_bfe_u32 v5, v62, 16, 1
	v_add3_u32 v5, v62, v5, s71
	global_store_short_d16_hi v0, v5, vcc
	v_add_u32_e32 v0, 16, v0
	v_bfe_u32 v5, v57, 16, 1
	v_add3_u32 v5, v57, v5, s71
	global_store_short_d16_hi v0, v5, vcc
	v_add_u32_e32 v0, 16, v0
	v_bfe_u32 v5, v51, 16, 1
	v_add3_u32 v5, v51, v5, s71
	global_store_short_d16_hi v0, v5, vcc
	v_add_u32_e32 v0, 16, v0
	v_bfe_u32 v5, v3, 16, 1
	v_add3_u32 v5, v3, v5, s71
	global_store_short_d16_hi v0, v5, vcc
	v_add_u32_e32 v0, 16, v0
	v_bfe_u32 v5, v60, 16, 1
	v_add3_u32 v5, v60, v5, s71
	global_store_short_d16_hi v0, v5, vcc
	v_add_u32_e32 v0, 16, v0
	v_bfe_u32 v5, v59, 16, 1
	v_add3_u32 v5, v59, v5, s71
	global_store_short_d16_hi v0, v5, vcc
	v_add_u32_e32 v0, 16, v0
	v_bfe_u32 v5, v58, 16, 1
	v_add3_u32 v5, v58, v5, s71
	global_store_short_d16_hi v0, v5, vcc
	v_add_u32_e32 v0, 16, v0
	v_bfe_u32 v5, v50, 16, 1
	v_add3_u32 v5, v50, v5, s71
	global_store_short_d16_hi v0, v5, vcc
	v_add_u32_e32 v0, 0xf10, v0
	v_bfe_u32 v5, v55, 16, 1
	v_add3_u32 v5, v55, v5, s71
	global_store_short_d16_hi v0, v5, vcc
	v_add_u32_e32 v0, 16, v0
	v_bfe_u32 v5, v54, 16, 1
	v_add3_u32 v5, v54, v5, s71
	global_store_short_d16_hi v0, v5, vcc
	v_add_u32_e32 v0, 16, v0
	v_bfe_u32 v5, v53, 16, 1
	v_add3_u32 v5, v53, v5, s71
	global_store_short_d16_hi v0, v5, vcc
	v_add_u32_e32 v0, 16, v0
	v_bfe_u32 v5, v52, 16, 1
	v_add3_u32 v5, v52, v5, s71
	global_store_short_d16_hi v0, v5, vcc
	v_add_u32_e32 v0, 16, v0
	v_bfe_u32 v5, v49, 16, 1
	v_add3_u32 v5, v49, v5, s71
	global_store_short_d16_hi v0, v5, vcc
	v_add_u32_e32 v0, 16, v0
	v_bfe_u32 v5, v48, 16, 1
	v_add3_u32 v5, v48, v5, s71
	global_store_short_d16_hi v0, v5, vcc
	v_add_u32_e32 v0, 16, v0
	v_bfe_u32 v5, v47, 16, 1
	v_add3_u32 v5, v47, v5, s71
	global_store_short_d16_hi v0, v5, vcc
	v_add_u32_e32 v0, 16, v0
	v_bfe_u32 v5, v46, 16, 1
	v_add3_u32 v5, v46, v5, s71
	global_store_short_d16_hi v0, v5, vcc
	v_add_u32_e32 v0, 16, v0
	v_bfe_u32 v5, v45, 16, 1
	v_add3_u32 v5, v45, v5, s71
	global_store_short_d16_hi v0, v5, vcc
	v_add_u32_e32 v0, 16, v0
	v_bfe_u32 v5, v44, 16, 1
	v_add3_u32 v5, v44, v5, s71
	global_store_short_d16_hi v0, v5, vcc
	v_add_u32_e32 v0, 16, v0
	v_bfe_u32 v5, v43, 16, 1
	v_add3_u32 v5, v43, v5, s71
	global_store_short_d16_hi v0, v5, vcc
	v_add_u32_e32 v0, 16, v0
	v_bfe_u32 v5, v42, 16, 1
	v_add3_u32 v5, v42, v5, s71
	global_store_short_d16_hi v0, v5, vcc
	v_add_u32_e32 v0, 16, v0
	v_bfe_u32 v5, v41, 16, 1
	v_add3_u32 v5, v41, v5, s71
	global_store_short_d16_hi v0, v5, vcc
	v_add_u32_e32 v0, 16, v0
	v_bfe_u32 v5, v40, 16, 1
	v_add3_u32 v5, v40, v5, s71
	global_store_short_d16_hi v0, v5, vcc
	v_add_u32_e32 v0, 16, v0
	v_bfe_u32 v5, v39, 16, 1
	v_add3_u32 v5, v39, v5, s71
	global_store_short_d16_hi v0, v5, vcc
	v_add_u32_e32 v0, 16, v0
; DI unsigned f2bf(float f) { unsigned u = __float_as_uint(f); return (u + 0x7fffu + ((u >> 16) & 1u)) >> 16; }
; template <int D> DI void dn_out(float (&x)[64], lf_t Kl, lf_t Ql, lf_t Gn, bf16_t* DW, bf16_t* DQE, bf16_t* DKT, bf16_t* DUT, float* DEG, int item, int t) {
;     ...
;             } else { bf16_t* wbase = DW + (((size_t)D * 1152 + item) * 64) * 128; unsigned woff = (unsigned)((t - 128) * 2);
; #pragma unroll
;                 for (int pi = 0; pi < 64; ++pi) { *(bf16_t*)((char*)wbase + woff) = (bf16_t)f2bf(x[pi]); woff += 256; asm volatile("" : "+v"(woff)); } }
	v_bfe_u32 v5, v38, 16, 1
	v_add3_u32 v5, v38, v5, s71
	global_store_short_d16_hi v0, v5, vcc
	v_add_u32_e32 v0, 0xf10, v0
	v_bfe_u32 v5, v37, 16, 1
	v_add3_u32 v5, v37, v5, s71
	global_store_short_d16_hi v0, v5, vcc
	v_add_u32_e32 v0, 16, v0
	v_bfe_u32 v5, v36, 16, 1
	v_add3_u32 v5, v36, v5, s71
	global_store_short_d16_hi v0, v5, vcc
	v_add_u32_e32 v0, 16, v0
	v_bfe_u32 v5, v35, 16, 1
	v_add3_u32 v5, v35, v5, s71
	global_store_short_d16_hi v0, v5, vcc
	v_add_u32_e32 v0, 16, v0
	v_bfe_u32 v5, v34, 16, 1
	v_add3_u32 v5, v34, v5, s71
	global_store_short_d16_hi v0, v5, vcc
	v_add_u32_e32 v0, 16, v0
	v_bfe_u32 v5, v33, 16, 1
	v_add3_u32 v5, v33, v5, s71
	global_store_short_d16_hi v0, v5, vcc
	v_add_u32_e32 v0, 16, v0
	v_bfe_u32 v5, v32, 16, 1
	v_add3_u32 v5, v32, v5, s71
	global_store_short_d16_hi v0, v5, vcc
	v_add_u32_e32 v0, 16, v0
	v_bfe_u32 v5, v31, 16, 1
	v_add3_u32 v5, v31, v5, s71
	global_store_short_d16_hi v0, v5, vcc
	v_add_u32_e32 v0, 16, v0
	v_bfe_u32 v5, v30, 16, 1
	v_add3_u32 v5, v30, v5, s71
	global_store_short_d16_hi v0, v5, vcc
	v_add_u32_e32 v0, 16, v0
	v_bfe_u32 v5, v29, 16, 1
	v_add3_u32 v5, v29, v5, s71
	global_store_short_d16_hi v0, v5, vcc
	v_add_u32_e32 v0, 16, v0
	v_bfe_u32 v5, v28, 16, 1
	v_add3_u32 v5, v28, v5, s71
	global_store_short_d16_hi v0, v5, vcc
	v_add_u32_e32 v0, 16, v0
	v_bfe_u32 v5, v27, 16, 1
	v_add3_u32 v5, v27, v5, s71
	global_store_short_d16_hi v0, v5, vcc
	v_add_u32_e32 v0, 16, v0
	v_bfe_u32 v5, v26, 16, 1
	v_add3_u32 v5, v26, v5, s71
	global_store_short_d16_hi v0, v5, vcc
	v_add_u32_e32 v0, 16, v0
	v_bfe_u32 v5, v25, 16, 1
	v_add3_u32 v5, v25, v5, s71
	global_store_short_d16_hi v0, v5, vcc
	v_add_u32_e32 v0, 16, v0
	v_bfe_u32 v5, v24, 16, 1
	v_add3_u32 v5, v24, v5, s71
	global_store_short_d16_hi v0, v5, vcc
	v_add_u32_e32 v0, 16, v0
	v_bfe_u32 v5, v23, 16, 1
	v_add3_u32 v5, v23, v5, s71
	global_store_short_d16_hi v0, v5, vcc
	v_add_u32_e32 v0, 16, v0
	v_bfe_u32 v5, v22, 16, 1
	v_add3_u32 v5, v22, v5, s71
	global_store_short_d16_hi v0, v5, vcc
	v_add_u32_e32 v0, 0xf10, v0
	v_bfe_u32 v5, v65, 16, 1
	v_add3_u32 v5, v65, v5, s71
	global_store_short_d16_hi v0, v5, vcc
	v_add_u32_e32 v0, 16, v0
	v_bfe_u32 v5, v64, 16, 1
	v_add3_u32 v5, v64, v5, s71
	global_store_short_d16_hi v0, v5, vcc
	v_add_u32_e32 v0, 16, v0
	v_bfe_u32 v5, v63, 16, 1
	v_add3_u32 v5, v63, v5, s71
	global_store_short_d16_hi v0, v5, vcc
	v_add_u32_e32 v0, 16, v0
	v_bfe_u32 v5, v61, 16, 1
	v_add3_u32 v5, v61, v5, s71
	global_store_short_d16_hi v0, v5, vcc
	v_add_u32_e32 v0, 16, v0
	v_bfe_u32 v5, v76, 16, 1
	v_add3_u32 v5, v76, v5, s71
	global_store_short_d16_hi v0, v5, vcc
	v_add_u32_e32 v0, 16, v0
	v_bfe_u32 v5, v75, 16, 1
	v_add3_u32 v5, v75, v5, s71
	global_store_short_d16_hi v0, v5, vcc
	v_add_u32_e32 v0, 16, v0
	v_bfe_u32 v5, v74, 16, 1
	v_add3_u32 v5, v74, v5, s71
	global_store_short_d16_hi v0, v5, vcc
	v_add_u32_e32 v0, 16, v0
	v_bfe_u32 v5, v11, 16, 1
	v_add3_u32 v5, v11, v5, s71
	global_store_short_d16_hi v0, v5, vcc
	v_add_u32_e32 v0, 16, v0
	v_bfe_u32 v5, v80, 16, 1
	v_add3_u32 v5, v80, v5, s71
	global_store_short_d16_hi v0, v5, vcc
	v_add_u32_e32 v0, 16, v0
	v_bfe_u32 v5, v79, 16, 1
	v_add3_u32 v5, v79, v5, s71
	global_store_short_d16_hi v0, v5, vcc
	v_add_u32_e32 v0, 16, v0
	v_bfe_u32 v5, v78, 16, 1
	v_add3_u32 v5, v78, v5, s71
	global_store_short_d16_hi v0, v5, vcc
	v_add_u32_e32 v0, 16, v0
	v_bfe_u32 v5, v77, 16, 1
	v_add3_u32 v5, v77, v5, s71
	global_store_short_d16_hi v0, v5, vcc
	v_add_u32_e32 v0, 16, v0
	v_bfe_u32 v5, v82, 16, 1
	v_add3_u32 v5, v82, v5, s71
	global_store_short_d16_hi v0, v5, vcc
	v_add_u32_e32 v0, 16, v0
	v_bfe_u32 v5, v81, 16, 1
	v_add3_u32 v5, v81, v5, s71
	global_store_short_d16_hi v0, v5, vcc
	v_add_u32_e32 v0, 16, v0
	v_bfe_u32 v5, v69, 16, 1
	v_add3_u32 v5, v69, v5, s71
	global_store_short_d16_hi v0, v5, vcc
	v_add_u32_e32 v0, 16, v0
	v_bfe_u32 v5, v68, 16, 1
	v_add3_u32 v5, v68, v5, s71
	global_store_short_d16_hi v0, v5, vcc
	v_add_u32_e32 v0, 0xf10, v0

; DI unsigned pk2(float lo, float hi) { return f2bf(lo) | (f2bf(hi) << 16); }
; template <int D> DI void dn_out(float (&x)[64], lf_t Kl, lf_t Ql, lf_t Gn, bf16_t* DW, bf16_t* DQE, bf16_t* DKT, bf16_t* DUT, float* DEG, int item, int t) {
;     ...
;             const float glast = Gd[D ? 0 : 63];
; #pragma unroll
;             for (int i = 0; i < 4; ++i) { const int idx = t + 256 * i, pi = idx >> 4, seg = idx & 15, n = D ? 63 - pi : pi; const float e = __expf(Gd[n]);
;                 const float4 a0 = *(const float4*)(Ql + n * 132 + seg * 8), a1 = *(const float4*)(Ql + n * 132 + seg * 8 + 4);
;                 uint4 o; o.x = pk2(a0.x * e, a0.y * e); o.y = pk2(a0.z * e, a0.w * e); o.z = pk2(a1.x * e, a1.y * e); o.w = pk2(a1.z * e, a1.w * e);
;                 *(uint4*)(DQE + (((size_t)D * 1152 + item) * 64 + pi) * 128 + seg * 8) = o; }
.LBB0_659:
	s_or_b64 exec, exec, s[44:45]
	v_ashrrev_i32_e32 v16, 4, v4
	v_lshlrev_b32_e32 v6, 2, v16
	v_sub_u32_e32 v6, v104, v6
	v_lshlrev_b32_e32 v0, 3, v4
	ds_read_b32 v12, v6 offset:508
	v_and_b32_e32 v0, 0x78, v0
	v_lshl_add_u32 v10, v0, 2, v103
	v_lshl_add_u64 v[6:7], s[86:87], 0, v[8:9]
	v_lshlrev_b32_e32 v0, 5, v0
	v_lshl_add_u64 v[92:93], v[6:7], 0, v[0:1]
	v_sub_u32_e32 v6, 63, v16
	v_mad_u64_u32 v[6:7], s[20:21], v6, s84, v[10:11]
	s_waitcnt lgkmcnt(0)
	v_mul_f32_e32 v0, 0x3fb8aa3b, v12
	ds_read_b128 v[12:15], v6
	v_exp_f32_e32 v0, v0
	v_ashrrev_i32_e32 v17, 31, v16
	v_and_b32_e32 v84, 15, v16
	v_lshrrev_b32_e32 v85, 4, v16
	v_lshlrev_b32_e32 v84, 4, v84
	v_lshl_add_u32 v84, v85, 12, v84
	v_mov_b32_e32 v85, 0
	v_lshl_add_u64 v[94:95], v[92:93], 0, v[84:85]
	ds_read_b128 v[84:87], v6 offset:16
	s_waitcnt lgkmcnt(1)
	v_mov_b32_e32 v6, v12
	v_mov_b32_e32 v7, v14
	v_pk_mul_f32 v[6:7], v[6:7], v[0:1] op_sel_hi:[1,0]
	v_mov_b32_e32 v14, v13
	v_pk_mul_f32 v[12:13], v[14:15], v[0:1] op_sel_hi:[1,0]
	v_and_b32_sdwa v14, v7, v242 dst_sel:DWORD dst_unused:UNUSED_PAD src0_sel:WORD_1 src1_sel:DWORD
	v_and_b32_sdwa v15, v6, v242 dst_sel:DWORD dst_unused:UNUSED_PAD src0_sel:WORD_1 src1_sel:DWORD
	v_add3_u32 v6, v6, v15, s71
	v_add3_u32 v7, v7, v14, s71
	v_and_b32_sdwa v14, v13, v242 dst_sel:DWORD dst_unused:UNUSED_PAD src0_sel:WORD_1 src1_sel:DWORD
	v_and_b32_sdwa v15, v12, v242 dst_sel:DWORD dst_unused:UNUSED_PAD src0_sel:WORD_1 src1_sel:DWORD
	v_add3_u32 v13, v13, v14, s71
	v_add3_u32 v12, v12, v15, s71
	v_and_b32_e32 v13, 0xffff0000, v13
	v_and_b32_e32 v12, 0xffff0000, v12
	v_or_b32_sdwa v89, v13, v7 dst_sel:DWORD dst_unused:UNUSED_PAD src0_sel:DWORD src1_sel:WORD_1
	v_or_b32_sdwa v88, v12, v6 dst_sel:DWORD dst_unused:UNUSED_PAD src0_sel:DWORD src1_sel:WORD_1
	s_waitcnt lgkmcnt(0)
	v_mov_b32_e32 v6, v84
	v_mov_b32_e32 v7, v86
	v_pk_mul_f32 v[6:7], v[0:1], v[6:7] op_sel_hi:[0,1]
	v_mov_b32_e32 v86, v85
	v_pk_mul_f32 v[12:13], v[0:1], v[86:87] op_sel_hi:[0,1]
	v_and_b32_sdwa v0, v7, v242 dst_sel:DWORD dst_unused:UNUSED_PAD src0_sel:WORD_1 src1_sel:DWORD
	v_and_b32_sdwa v14, v6, v242 dst_sel:DWORD dst_unused:UNUSED_PAD src0_sel:WORD_1 src1_sel:DWORD
	v_add3_u32 v0, v7, v0, s71
	v_and_b32_sdwa v7, v13, v242 dst_sel:DWORD dst_unused:UNUSED_PAD src0_sel:WORD_1 src1_sel:DWORD
	v_add3_u32 v6, v6, v14, s71
	v_and_b32_sdwa v14, v12, v242 dst_sel:DWORD dst_unused:UNUSED_PAD src0_sel:WORD_1 src1_sel:DWORD
	v_add3_u32 v7, v13, v7, s71
	v_add_u32_e32 v13, 0x100, v4
	v_add3_u32 v12, v12, v14, s71
	v_ashrrev_i32_e32 v14, 4, v13
	v_lshlrev_b32_e32 v13, 2, v14
	v_sub_u32_e32 v13, v104, v13
	ds_read_b32 v13, v13 offset:508
	v_and_b32_e32 v12, 0xffff0000, v12
	v_and_b32_e32 v7, 0xffff0000, v7
	v_or_b32_sdwa v90, v12, v6 dst_sel:DWORD dst_unused:UNUSED_PAD src0_sel:DWORD src1_sel:WORD_1
	v_sub_u32_e32 v6, 63, v14
	v_or_b32_sdwa v91, v7, v0 dst_sel:DWORD dst_unused:UNUSED_PAD src0_sel:DWORD src1_sel:WORD_1
	v_mad_u64_u32 v[6:7], s[20:21], v6, s84, v[10:11]
	ds_read_b128 v[84:87], v6
	s_waitcnt lgkmcnt(1)
	v_mul_f32_e32 v0, 0x3fb8aa3b, v13
	v_exp_f32_e32 v0, v0
	global_store_dwordx4 v[94:95], v[88:91], off
	v_ashrrev_i32_e32 v15, 31, v14
	ds_read_b128 v[88:91], v6 offset:16
	s_waitcnt lgkmcnt(1)
	v_mov_b32_e32 v6, v84
	v_mov_b32_e32 v7, v86
	v_and_b32_e32 v12, 15, v14
	v_lshrrev_b32_e32 v13, 4, v14
	v_lshlrev_b32_e32 v12, 4, v12
	v_lshl_add_u32 v12, v13, 12, v12
	v_mov_b32_e32 v13, 0
	v_pk_mul_f32 v[6:7], v[6:7], v[0:1] op_sel_hi:[1,0]
	v_mov_b32_e32 v86, v85
	v_lshl_add_u64 v[94:95], v[92:93], 0, v[12:13]
	v_pk_mul_f32 v[12:13], v[86:87], v[0:1] op_sel_hi:[1,0]
	v_and_b32_sdwa v15, v7, v242 dst_sel:DWORD dst_unused:UNUSED_PAD src0_sel:WORD_1 src1_sel:DWORD
	v_and_b32_sdwa v17, v6, v242 dst_sel:DWORD dst_unused:UNUSED_PAD src0_sel:WORD_1 src1_sel:DWORD
	v_add3_u32 v6, v6, v17, s71
	v_add3_u32 v7, v7, v15, s71
	v_and_b32_sdwa v15, v13, v242 dst_sel:DWORD dst_unused:UNUSED_PAD src0_sel:WORD_1 src1_sel:DWORD
	v_and_b32_sdwa v17, v12, v242 dst_sel:DWORD dst_unused:UNUSED_PAD src0_sel:WORD_1 src1_sel:DWORD
	v_add3_u32 v13, v13, v15, s71
	v_add3_u32 v12, v12, v17, s71
	v_and_b32_e32 v13, 0xffff0000, v13
	v_and_b32_e32 v12, 0xffff0000, v12
	v_or_b32_sdwa v85, v13, v7 dst_sel:DWORD dst_unused:UNUSED_PAD src0_sel:DWORD src1_sel:WORD_1
	v_or_b32_sdwa v84, v12, v6 dst_sel:DWORD dst_unused:UNUSED_PAD src0_sel:DWORD src1_sel:WORD_1
	s_waitcnt lgkmcnt(0)
	v_mov_b32_e32 v6, v88
	v_mov_b32_e32 v7, v90
	v_pk_mul_f32 v[6:7], v[0:1], v[6:7] op_sel_hi:[0,1]
	v_mov_b32_e32 v90, v89
	v_pk_mul_f32 v[12:13], v[0:1], v[90:91] op_sel_hi:[0,1]
	v_and_b32_sdwa v15, v6, v242 dst_sel:DWORD dst_unused:UNUSED_PAD src0_sel:WORD_1 src1_sel:DWORD
	v_and_b32_sdwa v0, v7, v242 dst_sel:DWORD dst_unused:UNUSED_PAD src0_sel:WORD_1 src1_sel:DWORD
	v_add3_u32 v6, v6, v15, s71
	v_and_b32_sdwa v15, v12, v242 dst_sel:DWORD dst_unused:UNUSED_PAD src0_sel:WORD_1 src1_sel:DWORD
	v_add3_u32 v0, v7, v0, s71
	v_and_b32_sdwa v7, v13, v242 dst_sel:DWORD dst_unused:UNUSED_PAD src0_sel:WORD_1 src1_sel:DWORD
	v_add3_u32 v12, v12, v15, s71
	v_add3_u32 v7, v13, v7, s71
	v_and_b32_e32 v13, 0xffff0000, v12
	v_add_u32_e32 v12, 0x200, v4
	v_ashrrev_i32_e32 v12, 4, v12
	v_lshlrev_b32_e32 v15, 2, v12
	v_sub_u32_e32 v15, v104, v15
	ds_read_b32 v15, v15 offset:508
	v_and_b32_e32 v7, 0xffff0000, v7
	v_or_b32_sdwa v86, v13, v6 dst_sel:DWORD dst_unused:UNUSED_PAD src0_sel:DWORD src1_sel:WORD_1
	v_sub_u32_e32 v6, 63, v12
	v_or_b32_sdwa v87, v7, v0 dst_sel:DWORD dst_unused:UNUSED_PAD src0_sel:DWORD src1_sel:WORD_1
	v_mad_u64_u32 v[6:7], s[20:21], v6, s84, v[10:11]
	global_store_dwordx4 v[94:95], v[84:87], off
	ds_read_b128 v[84:87], v6
	s_waitcnt lgkmcnt(1)
; DI unsigned pk2(float lo, float hi) { return f2bf(lo) | (f2bf(hi) << 16); }
; DI uint4 pack8(const float* f) { uint4 o; o.x = pk2(f[0], f[1]); o.y = pk2(f[2], f[3]); o.z = pk2(f[4], f[5]); o.w = pk2(f[6], f[7]); return o; }
; template <int D> DI void dn_out(float (&x)[64], lf_t Kl, lf_t Ql, lf_t Gn, bf16_t* DW, bf16_t* DQE, bf16_t* DKT, bf16_t* DUT, float* DEG, int item, int t) {
;     ...
;             for (int i = 0; i < 4; ++i) { const int idx = t + 256 * i, pi = idx >> 4, seg = idx & 15, n = D ? 63 - pi : pi; const float e = __expf(Gd[n]);
;                 const float4 a0 = *(const float4*)(Ql + n * 132 + seg * 8), a1 = *(const float4*)(Ql + n * 132 + seg * 8 + 4);
;                 uint4 o; o.x = pk2(a0.x * e, a0.y * e); o.y = pk2(a0.z * e, a0.w * e); o.z = pk2(a1.x * e, a1.y * e); o.w = pk2(a1.z * e, a1.w * e);
;                 *(uint4*)(DQE + (((size_t)D * 1152 + item) * 64 + pi) * 128 + seg * 8) = o; }
; #pragma unroll
;             for (int i = 0; i < 4; ++i) { const int idx = t + 256 * i, dk = idx & 127, pg = idx >> 7; float v[8];
; #pragma unroll
;                 for (int e = 0; e < 8; ++e) { const int pi = 8 * pg + e, n = D ? 63 - pi : pi; v[e] = Kl[n * 132 + dk] * __expf(glast - Gd[n]); }
;                 *(uint4*)(DKT + (((size_t)D * 1152 + item) * 128 + dk) * 64 + 8 * pg) = pack8(v); }
	v_mul_f32_e32 v0, 0x3fb8aa3b, v15
	v_exp_f32_e32 v0, v0
	v_ashrrev_i32_e32 v13, 31, v12
	v_and_b32_e32 v88, 15, v12
	v_lshrrev_b32_e32 v89, 4, v12
	v_lshlrev_b32_e32 v88, 4, v88
	v_lshl_add_u32 v88, v89, 12, v88
	v_mov_b32_e32 v89, 0
	v_lshl_add_u64 v[94:95], v[92:93], 0, v[88:89]
	ds_read_b128 v[88:91], v6 offset:16
	s_waitcnt lgkmcnt(1)
	v_mov_b32_e32 v6, v84
	v_mov_b32_e32 v7, v86
	v_pk_mul_f32 v[6:7], v[6:7], v[0:1] op_sel_hi:[1,0]
	v_mov_b32_e32 v86, v85
	v_pk_mul_f32 v[84:85], v[86:87], v[0:1] op_sel_hi:[1,0]
	v_and_b32_sdwa v13, v7, v242 dst_sel:DWORD dst_unused:UNUSED_PAD src0_sel:WORD_1 src1_sel:DWORD
	v_and_b32_sdwa v15, v6, v242 dst_sel:DWORD dst_unused:UNUSED_PAD src0_sel:WORD_1 src1_sel:DWORD
	v_add3_u32 v6, v6, v15, s71
	v_add3_u32 v7, v7, v13, s71
	v_and_b32_sdwa v13, v85, v242 dst_sel:DWORD dst_unused:UNUSED_PAD src0_sel:WORD_1 src1_sel:DWORD
	v_and_b32_sdwa v15, v84, v242 dst_sel:DWORD dst_unused:UNUSED_PAD src0_sel:WORD_1 src1_sel:DWORD
	v_add3_u32 v13, v85, v13, s71
	v_add3_u32 v15, v84, v15, s71
	v_and_b32_e32 v13, 0xffff0000, v13
	v_and_b32_e32 v15, 0xffff0000, v15
	v_or_b32_sdwa v85, v13, v7 dst_sel:DWORD dst_unused:UNUSED_PAD src0_sel:DWORD src1_sel:WORD_1
	v_or_b32_sdwa v84, v15, v6 dst_sel:DWORD dst_unused:UNUSED_PAD src0_sel:DWORD src1_sel:WORD_1
	s_waitcnt lgkmcnt(0)
	v_mov_b32_e32 v6, v88
	v_mov_b32_e32 v7, v90
	v_pk_mul_f32 v[6:7], v[0:1], v[6:7] op_sel_hi:[0,1]
	v_mov_b32_e32 v90, v89
	v_pk_mul_f32 v[86:87], v[0:1], v[90:91] op_sel_hi:[0,1]
	v_and_b32_sdwa v13, v6, v242 dst_sel:DWORD dst_unused:UNUSED_PAD src0_sel:WORD_1 src1_sel:DWORD
	v_add3_u32 v13, v6, v13, s71
	v_and_b32_sdwa v6, v87, v242 dst_sel:DWORD dst_unused:UNUSED_PAD src0_sel:WORD_1 src1_sel:DWORD
	v_add3_u32 v6, v87, v6, s71
	v_and_b32_e32 v15, 0xffff0000, v6
	v_add_u32_e32 v6, 0x300, v4
	v_ashrrev_i32_e32 v6, 4, v6
	v_and_b32_sdwa v0, v7, v242 dst_sel:DWORD dst_unused:UNUSED_PAD src0_sel:WORD_1 src1_sel:DWORD
	v_lshlrev_b32_e32 v17, 2, v6
	v_add3_u32 v0, v7, v0, s71
	v_and_b32_sdwa v7, v86, v242 dst_sel:DWORD dst_unused:UNUSED_PAD src0_sel:WORD_1 src1_sel:DWORD
	v_sub_u32_e32 v17, v104, v17
	v_add3_u32 v7, v86, v7, s71
	ds_read_b32 v17, v17 offset:508
	v_and_b32_e32 v7, 0xffff0000, v7
	v_or_b32_sdwa v86, v7, v13 dst_sel:DWORD dst_unused:UNUSED_PAD src0_sel:DWORD src1_sel:WORD_1
	v_sub_u32_e32 v7, 63, v6
	v_or_b32_sdwa v87, v15, v0 dst_sel:DWORD dst_unused:UNUSED_PAD src0_sel:DWORD src1_sel:WORD_1
	v_mad_u64_u32 v[88:89], s[20:21], v7, s84, v[10:11]
	global_store_dwordx4 v[94:95], v[84:87], off
	ds_read_b128 v[84:87], v88
	s_waitcnt lgkmcnt(1)
	v_mul_f32_e32 v0, 0x3fb8aa3b, v17
	v_ashrrev_i32_e32 v7, 31, v6
	v_exp_f32_e32 v0, v0
	v_and_b32_e32 v90, 15, v6
	v_lshrrev_b32_e32 v91, 4, v6
	v_lshlrev_b32_e32 v90, 4, v90
	v_lshl_add_u32 v90, v91, 12, v90
	v_mov_b32_e32 v91, 0
	v_lshl_add_u64 v[92:93], v[92:93], 0, v[90:91]
	ds_read_b128 v[88:91], v88 offset:16
	s_waitcnt lgkmcnt(1)
	v_mov_b32_e32 v95, v86
	v_mov_b32_e32 v86, v85
	v_mov_b32_e32 v94, v84
	v_pk_mul_f32 v[84:85], v[86:87], v[0:1] op_sel_hi:[1,0]
	v_pk_mul_f32 v[94:95], v[94:95], v[0:1] op_sel_hi:[1,0]
	v_and_b32_sdwa v13, v85, v242 dst_sel:DWORD dst_unused:UNUSED_PAD src0_sel:WORD_1 src1_sel:DWORD
	v_and_b32_sdwa v15, v84, v242 dst_sel:DWORD dst_unused:UNUSED_PAD src0_sel:WORD_1 src1_sel:DWORD
	v_and_b32_sdwa v7, v95, v242 dst_sel:DWORD dst_unused:UNUSED_PAD src0_sel:WORD_1 src1_sel:DWORD
	v_and_b32_sdwa v10, v94, v242 dst_sel:DWORD dst_unused:UNUSED_PAD src0_sel:WORD_1 src1_sel:DWORD
	v_add3_u32 v13, v85, v13, s71
	v_add3_u32 v15, v84, v15, s71
	s_waitcnt lgkmcnt(0)
	v_mov_b32_e32 v87, v90
	v_mov_b32_e32 v90, v89
	v_add3_u32 v10, v94, v10, s71
	v_add3_u32 v7, v95, v7, s71
	v_and_b32_e32 v13, 0xffff0000, v13
	v_and_b32_e32 v15, 0xffff0000, v15
	v_mov_b32_e32 v86, v88
	v_pk_mul_f32 v[88:89], v[0:1], v[90:91] op_sel_hi:[0,1]
	v_or_b32_sdwa v85, v13, v7 dst_sel:DWORD dst_unused:UNUSED_PAD src0_sel:DWORD src1_sel:WORD_1
	v_or_b32_sdwa v84, v15, v10 dst_sel:DWORD dst_unused:UNUSED_PAD src0_sel:DWORD src1_sel:WORD_1
	v_pk_mul_f32 v[86:87], v[0:1], v[86:87] op_sel_hi:[0,1]
	v_and_b32_sdwa v10, v89, v242 dst_sel:DWORD dst_unused:UNUSED_PAD src0_sel:WORD_1 src1_sel:DWORD
	v_and_b32_sdwa v13, v88, v242 dst_sel:DWORD dst_unused:UNUSED_PAD src0_sel:WORD_1 src1_sel:DWORD
	v_and_b32_sdwa v0, v87, v242 dst_sel:DWORD dst_unused:UNUSED_PAD src0_sel:WORD_1 src1_sel:DWORD
	v_and_b32_sdwa v7, v86, v242 dst_sel:DWORD dst_unused:UNUSED_PAD src0_sel:WORD_1 src1_sel:DWORD
	v_add3_u32 v10, v89, v10, s71
	v_add3_u32 v13, v88, v13, s71
	v_add3_u32 v7, v86, v7, s71
	v_add3_u32 v0, v87, v0, s71
	v_and_b32_e32 v10, 0xffff0000, v10
	v_and_b32_e32 v13, 0xffff0000, v13
	v_or_b32_sdwa v87, v10, v0 dst_sel:DWORD dst_unused:UNUSED_PAD src0_sel:DWORD src1_sel:WORD_1
	v_or_b32_sdwa v86, v13, v7 dst_sel:DWORD dst_unused:UNUSED_PAD src0_sel:DWORD src1_sel:WORD_1
	v_and_b32_e32 v0, 0x7f, v4
	global_store_dwordx4 v[92:93], v[84:87], off
	v_lshl_add_u32 v10, v0, 2, v100
	v_lshl_add_u64 v[8:9], s[48:49], 0, v[8:9]
	v_lshlrev_b32_e32 v0, 7, v0
	v_and_b32_e32 v84, -8, v16
	v_lshl_add_u64 v[8:9], v[8:9], 0, v[0:1]
	v_lshlrev_b32_e32 v0, 2, v84
	v_sub_u32_e32 v0, v104, v0
	ds_read_b32 v5, v104 offset:256
	ds_read_b32 v0, v0 offset:508
	v_sub_u32_e32 v7, 63, v84
	v_mad_u64_u32 v[86:87], s[20:21], v7, s84, v[10:11]
	ds_read_b32 v86, v86
	s_waitcnt lgkmcnt(1)
	v_sub_f32_e32 v0, v5, v0
	v_mul_f32_e32 v0, 0x3fb8aa3b, v0
	v_exp_f32_e32 v88, v0
	v_or_b32_e32 v0, 2, v84
	v_lshlrev_b32_e32 v7, 2, v0
	v_sub_u32_e32 v7, v104, v7
	ds_read2_b32 v[90:91], v7 offset0:127 offset1:128
	v_sub_u32_e32 v7, 62, v84
	v_mad_u64_u32 v[92:93], s[20:21], v7, s84, v[10:11]
	v_sub_u32_e32 v0, 63, v0
	s_waitcnt lgkmcnt(0)
; DI uint4 pack8(const float* f) { uint4 o; o.x = pk2(f[0], f[1]); o.y = pk2(f[2], f[3]); o.z = pk2(f[4], f[5]); o.w = pk2(f[6], f[7]); return o; }
; template <int D> DI void dn_out(float (&x)[64], lf_t Kl, lf_t Ql, lf_t Gn, bf16_t* DW, bf16_t* DQE, bf16_t* DKT, bf16_t* DUT, float* DEG, int item, int t) {
;     ...
;             for (int i = 0; i < 4; ++i) { const int idx = t + 256 * i, dk = idx & 127, pg = idx >> 7; float v[8];
; #pragma unroll
;                 for (int e = 0; e < 8; ++e) { const int pi = 8 * pg + e, n = D ? 63 - pi : pi; v[e] = Kl[n * 132 + dk] * __expf(glast - Gd[n]); }
;                 *(uint4*)(DKT + (((size_t)D * 1152 + item) * 128 + dk) * 64 + 8 * pg) = pack8(v); }
	v_sub_f32_e32 v7, v5, v91
	v_mul_f32_e32 v7, 0x3fb8aa3b, v7
	v_exp_f32_e32 v94, v7
	v_or_b32_e32 v7, 4, v84
	v_lshlrev_b32_e32 v13, 2, v7
	v_sub_u32_e32 v13, v104, v13
	v_mad_u64_u32 v[96:97], s[20:21], v0, s84, v[10:11]
	v_sub_f32_e32 v0, v5, v90
	ds_read2_b32 v[90:91], v13 offset0:127 offset1:128
	v_mul_f32_e32 v0, 0x3fb8aa3b, v0
	v_exp_f32_e32 v89, v0
	v_or_b32_e32 v0, 3, v84
	v_sub_u32_e32 v0, 63, v0
	v_mad_u64_u32 v[98:99], s[20:21], v0, s84, v[10:11]
	s_waitcnt lgkmcnt(0)
	v_sub_f32_e32 v0, v5, v91
	v_mul_f32_e32 v0, 0x3fb8aa3b, v0
	v_exp_f32_e32 v95, v0
	v_sub_u32_e32 v0, 63, v7
	v_or_b32_e32 v7, 6, v84
	v_lshlrev_b32_e32 v13, 2, v7
	v_sub_u32_e32 v13, v104, v13
	ds_read_b32 v92, v92
	ds_read_b32 v87, v96
	ds_read_b32 v93, v98
	ds_read2_b32 v[98:99], v13 offset0:127 offset1:128
	v_mad_u64_u32 v[96:97], s[20:21], v0, s84, v[10:11]
	v_sub_f32_e32 v0, v5, v90
	v_mul_f32_e32 v0, 0x3fb8aa3b, v0
	v_exp_f32_e32 v90, v0
	v_or_b32_e32 v0, 5, v84
	v_sub_u32_e32 v0, 63, v0
	v_mad_u64_u32 v[126:127], s[20:21], v0, s84, v[10:11]
	s_waitcnt lgkmcnt(0)
	v_sub_f32_e32 v0, v5, v99
	v_mul_f32_e32 v0, 0x3fb8aa3b, v0
	v_exp_f32_e32 v128, v0
	v_sub_u32_e32 v0, 63, v7
	v_mad_u64_u32 v[130:131], s[20:21], v0, s84, v[10:11]
	v_sub_f32_e32 v0, v5, v98
	v_mul_f32_e32 v0, 0x3fb8aa3b, v0
	v_exp_f32_e32 v91, v0
	v_or_b32_e32 v0, 7, v16
	v_sub_u32_e32 v7, 63, v0
	v_lshlrev_b32_e32 v0, 2, v0
	v_sub_u32_e32 v0, v104, v0
	ds_read_b32 v96, v96
	ds_read_b32 v126, v126
	ds_read_b32 v0, v0 offset:508
	v_mad_u64_u32 v[16:17], s[20:21], v7, s84, v[10:11]
	ds_read_b32 v97, v130
	ds_read_b32 v127, v16
	v_ashrrev_i32_e32 v85, 31, v84
	s_waitcnt lgkmcnt(2)
	v_sub_f32_e32 v0, v5, v0
	v_mul_f32_e32 v0, 0x3fb8aa3b, v0
	v_exp_f32_e32 v129, v0
	v_lshl_add_u64 v[16:17], v[84:85], 1, v[8:9]
	v_pk_mul_f32 v[84:85], v[86:87], v[88:89]
	v_pk_mul_f32 v[86:87], v[92:93], v[94:95]
	v_and_b32_sdwa v0, v85, v242 dst_sel:DWORD dst_unused:UNUSED_PAD src0_sel:WORD_1 src1_sel:DWORD
	v_and_b32_sdwa v13, v87, v242 dst_sel:DWORD dst_unused:UNUSED_PAD src0_sel:WORD_1 src1_sel:DWORD
	v_and_b32_sdwa v15, v86, v242 dst_sel:DWORD dst_unused:UNUSED_PAD src0_sel:WORD_1 src1_sel:DWORD
	v_and_b32_sdwa v7, v84, v242 dst_sel:DWORD dst_unused:UNUSED_PAD src0_sel:WORD_1 src1_sel:DWORD
	v_add3_u32 v13, v87, v13, s71
	v_add3_u32 v15, v86, v15, s71
	v_add3_u32 v7, v84, v7, s71
	v_add3_u32 v0, v85, v0, s71
	v_and_b32_e32 v13, 0xffff0000, v13
	v_and_b32_e32 v15, 0xffff0000, v15
	s_waitcnt lgkmcnt(0)
	v_pk_mul_f32 v[88:89], v[126:127], v[128:129]
	v_or_b32_sdwa v85, v13, v0 dst_sel:DWORD dst_unused:UNUSED_PAD src0_sel:DWORD src1_sel:WORD_1
	v_or_b32_sdwa v84, v15, v7 dst_sel:DWORD dst_unused:UNUSED_PAD src0_sel:DWORD src1_sel:WORD_1
	v_pk_mul_f32 v[86:87], v[96:97], v[90:91]
	v_and_b32_sdwa v13, v89, v242 dst_sel:DWORD dst_unused:UNUSED_PAD src0_sel:WORD_1 src1_sel:DWORD
	v_and_b32_sdwa v15, v88, v242 dst_sel:DWORD dst_unused:UNUSED_PAD src0_sel:WORD_1 src1_sel:DWORD
	v_and_b32_sdwa v0, v87, v242 dst_sel:DWORD dst_unused:UNUSED_PAD src0_sel:WORD_1 src1_sel:DWORD
	v_and_b32_sdwa v7, v86, v242 dst_sel:DWORD dst_unused:UNUSED_PAD src0_sel:WORD_1 src1_sel:DWORD
	v_add3_u32 v13, v89, v13, s71
	v_add3_u32 v15, v88, v15, s71
	v_add3_u32 v7, v86, v7, s71
	v_add3_u32 v0, v87, v0, s71
	v_and_b32_e32 v13, 0xffff0000, v13
	v_and_b32_e32 v15, 0xffff0000, v15
	v_or_b32_sdwa v87, v13, v0 dst_sel:DWORD dst_unused:UNUSED_PAD src0_sel:DWORD src1_sel:WORD_1
	v_or_b32_sdwa v86, v15, v7 dst_sel:DWORD dst_unused:UNUSED_PAD src0_sel:DWORD src1_sel:WORD_1
	global_store_dwordx4 v[16:17], v[84:87], off
	v_and_b32_e32 v16, -8, v14
	v_lshlrev_b32_e32 v0, 2, v16
	v_sub_u32_e32 v0, v104, v0
	ds_read_b32 v0, v0 offset:508
	v_sub_u32_e32 v7, 63, v16
	v_mad_u64_u32 v[84:85], s[20:21], v7, s84, v[10:11]
	ds_read_b32 v84, v84
	s_waitcnt lgkmcnt(1)
	v_sub_f32_e32 v0, v5, v0
	v_mul_f32_e32 v0, 0x3fb8aa3b, v0
	v_exp_f32_e32 v86, v0
	v_or_b32_e32 v0, 2, v16
	v_lshlrev_b32_e32 v7, 2, v0
	v_sub_u32_e32 v7, v104, v7
	ds_read2_b32 v[88:89], v7 offset0:127 offset1:128
	v_sub_u32_e32 v7, 62, v16
	v_mad_u64_u32 v[90:91], s[20:21], v7, s84, v[10:11]
	v_sub_u32_e32 v0, 63, v0
	s_waitcnt lgkmcnt(0)
	v_sub_f32_e32 v7, v5, v89
	v_mul_f32_e32 v7, 0x3fb8aa3b, v7
	v_exp_f32_e32 v92, v7
	v_or_b32_e32 v7, 4, v16
	v_lshlrev_b32_e32 v13, 2, v7
	v_sub_u32_e32 v13, v104, v13
	v_mad_u64_u32 v[94:95], s[20:21], v0, s84, v[10:11]
	v_sub_f32_e32 v0, v5, v88
	ds_read2_b32 v[88:89], v13 offset0:127 offset1:128
	v_mul_f32_e32 v0, 0x3fb8aa3b, v0
	v_exp_f32_e32 v87, v0
	v_or_b32_e32 v0, 3, v16
	v_sub_u32_e32 v0, 63, v0
	v_mad_u64_u32 v[96:97], s[20:21], v0, s84, v[10:11]
	s_waitcnt lgkmcnt(0)
	v_sub_f32_e32 v0, v5, v89
	v_mul_f32_e32 v0, 0x3fb8aa3b, v0
	v_exp_f32_e32 v93, v0
	v_sub_u32_e32 v0, 63, v7
	v_or_b32_e32 v7, 6, v16
	v_lshlrev_b32_e32 v13, 2, v7
	v_sub_u32_e32 v13, v104, v13
	ds_read_b32 v90, v90
	ds_read_b32 v85, v94
	ds_read_b32 v91, v96
	ds_read2_b32 v[96:97], v13 offset0:127 offset1:128
	v_mad_u64_u32 v[94:95], s[20:21], v0, s84, v[10:11]
	v_sub_f32_e32 v0, v5, v88
	v_mul_f32_e32 v0, 0x3fb8aa3b, v0
	v_exp_f32_e32 v88, v0
	v_or_b32_e32 v0, 5, v16
	v_sub_u32_e32 v0, 63, v0
	v_mad_u64_u32 v[98:99], s[20:21], v0, s84, v[10:11]
	s_waitcnt lgkmcnt(0)
	v_sub_f32_e32 v0, v5, v97
	v_mul_f32_e32 v0, 0x3fb8aa3b, v0
	v_exp_f32_e32 v126, v0
	v_sub_u32_e32 v0, 63, v7
	v_mad_u64_u32 v[128:129], s[20:21], v0, s84, v[10:11]
	v_sub_f32_e32 v0, v5, v96
	v_mul_f32_e32 v0, 0x3fb8aa3b, v0
	v_exp_f32_e32 v89, v0
	v_or_b32_e32 v0, 7, v14
	v_sub_u32_e32 v7, 63, v0
	v_lshlrev_b32_e32 v0, 2, v0
	v_sub_u32_e32 v0, v104, v0
	ds_read_b32 v94, v94
	ds_read_b32 v98, v98
	ds_read_b32 v0, v0 offset:508
	v_mad_u64_u32 v[14:15], s[20:21], v7, s84, v[10:11]
	ds_read_b32 v95, v128
	ds_read_b32 v99, v14
	v_ashrrev_i32_e32 v17, 31, v16
	s_waitcnt lgkmcnt(2)
; DI uint4 pack8(const float* f) { uint4 o; o.x = pk2(f[0], f[1]); o.y = pk2(f[2], f[3]); o.z = pk2(f[4], f[5]); o.w = pk2(f[6], f[7]); return o; }
; template <int D> DI void dn_out(float (&x)[64], lf_t Kl, lf_t Ql, lf_t Gn, bf16_t* DW, bf16_t* DQE, bf16_t* DKT, bf16_t* DUT, float* DEG, int item, int t) {
;     ...
;             for (int i = 0; i < 4; ++i) { const int idx = t + 256 * i, dk = idx & 127, pg = idx >> 7; float v[8];
; #pragma unroll
;                 for (int e = 0; e < 8; ++e) { const int pi = 8 * pg + e, n = D ? 63 - pi : pi; v[e] = Kl[n * 132 + dk] * __expf(glast - Gd[n]); }
;                 *(uint4*)(DKT + (((size_t)D * 1152 + item) * 128 + dk) * 64 + 8 * pg) = pack8(v); }
	v_sub_f32_e32 v0, v5, v0
	v_mul_f32_e32 v0, 0x3fb8aa3b, v0
	v_pk_mul_f32 v[14:15], v[84:85], v[86:87]
	v_exp_f32_e32 v127, v0
	v_lshl_add_u64 v[96:97], v[16:17], 1, v[8:9]
	v_pk_mul_f32 v[16:17], v[90:91], v[92:93]
	v_and_b32_sdwa v7, v14, v242 dst_sel:DWORD dst_unused:UNUSED_PAD src0_sel:WORD_1 src1_sel:DWORD
	v_add3_u32 v7, v14, v7, s71
	v_and_b32_sdwa v14, v16, v242 dst_sel:DWORD dst_unused:UNUSED_PAD src0_sel:WORD_1 src1_sel:DWORD
	v_and_b32_sdwa v13, v17, v242 dst_sel:DWORD dst_unused:UNUSED_PAD src0_sel:WORD_1 src1_sel:DWORD
	v_add3_u32 v14, v16, v14, s71
	v_and_b32_sdwa v0, v15, v242 dst_sel:DWORD dst_unused:UNUSED_PAD src0_sel:WORD_1 src1_sel:DWORD
	v_add3_u32 v13, v17, v13, s71
	v_and_b32_e32 v14, 0xffff0000, v14
	s_waitcnt lgkmcnt(1)
	v_pk_mul_f32 v[16:17], v[94:95], v[88:89]
	v_add3_u32 v0, v15, v0, s71
	v_and_b32_e32 v13, 0xffff0000, v13
	v_or_b32_sdwa v14, v14, v7 dst_sel:DWORD dst_unused:UNUSED_PAD src0_sel:DWORD src1_sel:WORD_1
	s_waitcnt lgkmcnt(0)
	v_pk_mul_f32 v[84:85], v[98:99], v[126:127]
	v_and_b32_sdwa v7, v16, v242 dst_sel:DWORD dst_unused:UNUSED_PAD src0_sel:WORD_1 src1_sel:DWORD
	v_or_b32_sdwa v15, v13, v0 dst_sel:DWORD dst_unused:UNUSED_PAD src0_sel:DWORD src1_sel:WORD_1
	v_add3_u32 v7, v16, v7, s71
	v_and_b32_sdwa v13, v85, v242 dst_sel:DWORD dst_unused:UNUSED_PAD src0_sel:WORD_1 src1_sel:DWORD
	v_and_b32_sdwa v16, v84, v242 dst_sel:DWORD dst_unused:UNUSED_PAD src0_sel:WORD_1 src1_sel:DWORD
	v_and_b32_sdwa v0, v17, v242 dst_sel:DWORD dst_unused:UNUSED_PAD src0_sel:WORD_1 src1_sel:DWORD
	v_add3_u32 v13, v85, v13, s71
	v_add3_u32 v16, v84, v16, s71
	v_add3_u32 v0, v17, v0, s71
	v_and_b32_e32 v13, 0xffff0000, v13
	v_and_b32_e32 v16, 0xffff0000, v16
	v_or_b32_sdwa v17, v13, v0 dst_sel:DWORD dst_unused:UNUSED_PAD src0_sel:DWORD src1_sel:WORD_1
	v_or_b32_sdwa v16, v16, v7 dst_sel:DWORD dst_unused:UNUSED_PAD src0_sel:DWORD src1_sel:WORD_1
	global_store_dwordx4 v[96:97], v[14:17], off
	v_cmp_eq_u32_e32 vcc, 0, v4
	s_nop 0
	v_and_b32_e32 v14, -8, v12
	v_lshlrev_b32_e32 v0, 2, v14
	v_sub_u32_e32 v0, v104, v0
	ds_read_b32 v0, v0 offset:508
	v_sub_u32_e32 v7, 63, v14
	v_mad_u64_u32 v[16:17], s[20:21], v7, s84, v[10:11]
	ds_read_b32 v16, v16
	s_waitcnt lgkmcnt(1)
	v_sub_f32_e32 v0, v5, v0
	v_mul_f32_e32 v0, 0x3fb8aa3b, v0
	v_exp_f32_e32 v84, v0
	v_or_b32_e32 v0, 2, v14
	v_lshlrev_b32_e32 v7, 2, v0
	v_sub_u32_e32 v7, v104, v7
	ds_read2_b32 v[86:87], v7 offset0:127 offset1:128
	v_sub_u32_e32 v7, 62, v14
	v_mad_u64_u32 v[88:89], s[20:21], v7, s84, v[10:11]
	v_sub_u32_e32 v0, 63, v0
	s_waitcnt lgkmcnt(0)
	v_sub_f32_e32 v7, v5, v87
	v_mul_f32_e32 v7, 0x3fb8aa3b, v7
	v_exp_f32_e32 v90, v7
	v_or_b32_e32 v7, 4, v14
	v_lshlrev_b32_e32 v13, 2, v7
	v_sub_u32_e32 v13, v104, v13
	v_mad_u64_u32 v[92:93], s[20:21], v0, s84, v[10:11]
	v_sub_f32_e32 v0, v5, v86
	ds_read2_b32 v[86:87], v13 offset0:127 offset1:128
	v_mul_f32_e32 v0, 0x3fb8aa3b, v0
	v_exp_f32_e32 v85, v0
	v_or_b32_e32 v0, 3, v14
	v_sub_u32_e32 v0, 63, v0
	v_mad_u64_u32 v[94:95], s[20:21], v0, s84, v[10:11]
	s_waitcnt lgkmcnt(0)
	v_sub_f32_e32 v0, v5, v87
	v_mul_f32_e32 v0, 0x3fb8aa3b, v0
	v_exp_f32_e32 v91, v0
	v_sub_u32_e32 v0, 63, v7
	v_or_b32_e32 v7, 6, v14
	v_lshlrev_b32_e32 v13, 2, v7
	v_sub_u32_e32 v13, v104, v13
	ds_read_b32 v88, v88
	ds_read_b32 v17, v92
	ds_read_b32 v89, v94
	ds_read2_b32 v[94:95], v13 offset0:127 offset1:128
	v_mad_u64_u32 v[92:93], s[20:21], v0, s84, v[10:11]
	v_sub_f32_e32 v0, v5, v86
	v_mul_f32_e32 v0, 0x3fb8aa3b, v0
	v_exp_f32_e32 v86, v0
	v_or_b32_e32 v0, 5, v14
	v_sub_u32_e32 v0, 63, v0
	v_mad_u64_u32 v[96:97], s[20:21], v0, s84, v[10:11]
	s_waitcnt lgkmcnt(0)
	v_sub_f32_e32 v0, v5, v95
	v_mul_f32_e32 v0, 0x3fb8aa3b, v0
	v_exp_f32_e32 v98, v0
	v_sub_u32_e32 v0, 63, v7
	v_mad_u64_u32 v[126:127], s[20:21], v0, s84, v[10:11]
	v_sub_f32_e32 v0, v5, v94
	v_mul_f32_e32 v0, 0x3fb8aa3b, v0
	v_exp_f32_e32 v87, v0
	v_or_b32_e32 v0, 7, v12
	v_sub_u32_e32 v7, 63, v0
	v_lshlrev_b32_e32 v0, 2, v0
	v_sub_u32_e32 v0, v104, v0
	ds_read_b32 v92, v92
	ds_read_b32 v96, v96
	ds_read_b32 v0, v0 offset:508
	v_mad_u64_u32 v[12:13], s[20:21], v7, s84, v[10:11]
	ds_read_b32 v93, v126
	ds_read_b32 v97, v12
	v_ashrrev_i32_e32 v15, 31, v14
	s_waitcnt lgkmcnt(2)
	v_sub_f32_e32 v0, v5, v0
	v_mul_f32_e32 v0, 0x3fb8aa3b, v0
	v_pk_mul_f32 v[12:13], v[16:17], v[84:85]
	v_exp_f32_e32 v99, v0
	v_lshl_add_u64 v[94:95], v[14:15], 1, v[8:9]
	v_pk_mul_f32 v[14:15], v[88:89], v[90:91]
	v_and_b32_sdwa v0, v13, v242 dst_sel:DWORD dst_unused:UNUSED_PAD src0_sel:WORD_1 src1_sel:DWORD
	v_and_b32_sdwa v7, v12, v242 dst_sel:DWORD dst_unused:UNUSED_PAD src0_sel:WORD_1 src1_sel:DWORD
	v_add3_u32 v7, v12, v7, s71
	v_add3_u32 v0, v13, v0, s71
	v_and_b32_sdwa v12, v15, v242 dst_sel:DWORD dst_unused:UNUSED_PAD src0_sel:WORD_1 src1_sel:DWORD
	v_and_b32_sdwa v13, v14, v242 dst_sel:DWORD dst_unused:UNUSED_PAD src0_sel:WORD_1 src1_sel:DWORD
	v_add3_u32 v12, v15, v12, s71
	v_add3_u32 v13, v14, v13, s71
	v_and_b32_e32 v12, 0xffff0000, v12
	v_and_b32_e32 v14, 0xffff0000, v13
	v_or_b32_sdwa v13, v12, v0 dst_sel:DWORD dst_unused:UNUSED_PAD src0_sel:DWORD src1_sel:WORD_1
	v_or_b32_sdwa v12, v14, v7 dst_sel:DWORD dst_unused:UNUSED_PAD src0_sel:DWORD src1_sel:WORD_1
	s_waitcnt lgkmcnt(1)
	v_pk_mul_f32 v[14:15], v[92:93], v[86:87]
	s_waitcnt lgkmcnt(0)
; DI uint4 pack8(const float* f) { uint4 o; o.x = pk2(f[0], f[1]); o.y = pk2(f[2], f[3]); o.z = pk2(f[4], f[5]); o.w = pk2(f[6], f[7]); return o; }
; template <int D> DI void dn_out(float (&x)[64], lf_t Kl, lf_t Ql, lf_t Gn, bf16_t* DW, bf16_t* DQE, bf16_t* DKT, bf16_t* DUT, float* DEG, int item, int t) {
;     ...
;             for (int i = 0; i < 4; ++i) { const int idx = t + 256 * i, dk = idx & 127, pg = idx >> 7; float v[8];
; #pragma unroll
;                 for (int e = 0; e < 8; ++e) { const int pi = 8 * pg + e, n = D ? 63 - pi : pi; v[e] = Kl[n * 132 + dk] * __expf(glast - Gd[n]); }
;                 *(uint4*)(DKT + (((size_t)D * 1152 + item) * 128 + dk) * 64 + 8 * pg) = pack8(v); }
;             if (t == 0) DEG[D * 1152 + item] = __expf(glast);
	v_pk_mul_f32 v[16:17], v[96:97], v[98:99]
	v_and_b32_sdwa v0, v15, v242 dst_sel:DWORD dst_unused:UNUSED_PAD src0_sel:WORD_1 src1_sel:DWORD
	v_and_b32_sdwa v7, v14, v242 dst_sel:DWORD dst_unused:UNUSED_PAD src0_sel:WORD_1 src1_sel:DWORD
	v_add3_u32 v7, v14, v7, s71
	v_add3_u32 v0, v15, v0, s71
	v_and_b32_sdwa v14, v17, v242 dst_sel:DWORD dst_unused:UNUSED_PAD src0_sel:WORD_1 src1_sel:DWORD
	v_and_b32_sdwa v15, v16, v242 dst_sel:DWORD dst_unused:UNUSED_PAD src0_sel:WORD_1 src1_sel:DWORD
	v_add3_u32 v14, v17, v14, s71
	v_add3_u32 v15, v16, v15, s71
	v_and_b32_e32 v14, 0xffff0000, v14
	v_and_b32_e32 v16, 0xffff0000, v15
	v_or_b32_sdwa v15, v14, v0 dst_sel:DWORD dst_unused:UNUSED_PAD src0_sel:DWORD src1_sel:WORD_1
	v_or_b32_sdwa v14, v16, v7 dst_sel:DWORD dst_unused:UNUSED_PAD src0_sel:DWORD src1_sel:WORD_1
	global_store_dwordx4 v[94:95], v[12:15], off
	s_nop 1
	v_and_b32_e32 v12, -8, v6
	v_lshlrev_b32_e32 v0, 2, v12
	v_sub_u32_e32 v0, v104, v0
	ds_read_b32 v0, v0 offset:508
	v_sub_u32_e32 v7, 63, v12
	v_mad_u64_u32 v[14:15], s[20:21], v7, s84, v[10:11]
	ds_read_b32 v14, v14
	s_waitcnt lgkmcnt(1)
	v_sub_f32_e32 v0, v5, v0
	v_mul_f32_e32 v0, 0x3fb8aa3b, v0
	v_exp_f32_e32 v16, v0
	v_or_b32_e32 v0, 2, v12
	v_lshlrev_b32_e32 v7, 2, v0
	v_sub_u32_e32 v7, v104, v7
	ds_read2_b32 v[84:85], v7 offset0:127 offset1:128
	v_sub_u32_e32 v7, 62, v12
	v_mad_u64_u32 v[86:87], s[20:21], v7, s84, v[10:11]
	v_sub_u32_e32 v0, 63, v0
	s_waitcnt lgkmcnt(0)
	v_sub_f32_e32 v7, v5, v85
	v_mul_f32_e32 v7, 0x3fb8aa3b, v7
	v_exp_f32_e32 v88, v7
	v_or_b32_e32 v7, 4, v12
	v_lshlrev_b32_e32 v13, 2, v7
	v_sub_u32_e32 v13, v104, v13
	v_mad_u64_u32 v[90:91], s[20:21], v0, s84, v[10:11]
	v_sub_f32_e32 v0, v5, v84
	ds_read2_b32 v[84:85], v13 offset0:127 offset1:128
	v_mul_f32_e32 v0, 0x3fb8aa3b, v0
	v_exp_f32_e32 v17, v0
	v_or_b32_e32 v0, 3, v12
	v_sub_u32_e32 v0, 63, v0
	v_mad_u64_u32 v[92:93], s[20:21], v0, s84, v[10:11]
	s_waitcnt lgkmcnt(0)
	v_sub_f32_e32 v0, v5, v85
	v_mul_f32_e32 v0, 0x3fb8aa3b, v0
	v_exp_f32_e32 v89, v0
	v_sub_u32_e32 v0, 63, v7
	v_or_b32_e32 v7, 6, v12
	v_lshlrev_b32_e32 v13, 2, v7
	v_sub_u32_e32 v13, v104, v13
	ds_read_b32 v86, v86
	ds_read_b32 v15, v90
	ds_read_b32 v87, v92
	ds_read2_b32 v[92:93], v13 offset0:127 offset1:128
	v_mad_u64_u32 v[90:91], s[20:21], v0, s84, v[10:11]
	v_sub_f32_e32 v0, v5, v84
	v_mul_f32_e32 v0, 0x3fb8aa3b, v0
	v_exp_f32_e32 v84, v0
	v_or_b32_e32 v0, 5, v12
	v_sub_u32_e32 v0, 63, v0
	v_mad_u64_u32 v[94:95], s[20:21], v0, s84, v[10:11]
	s_waitcnt lgkmcnt(0)
	v_sub_f32_e32 v0, v5, v93
	v_mul_f32_e32 v0, 0x3fb8aa3b, v0
	v_exp_f32_e32 v96, v0
	v_sub_u32_e32 v0, 63, v7
	v_mad_u64_u32 v[98:99], s[20:21], v0, s84, v[10:11]
	v_sub_f32_e32 v0, v5, v92
	v_mul_f32_e32 v0, 0x3fb8aa3b, v0
	v_exp_f32_e32 v85, v0
	v_or_b32_e32 v0, 7, v6
	v_sub_u32_e32 v6, 63, v0
	v_lshlrev_b32_e32 v0, 2, v0
	v_sub_u32_e32 v0, v104, v0
	ds_read_b32 v90, v90
	ds_read_b32 v94, v94
	ds_read_b32 v0, v0 offset:508
	v_mad_u64_u32 v[6:7], s[20:21], v6, s84, v[10:11]
	ds_read_b32 v91, v98
	ds_read_b32 v95, v6
	v_ashrrev_i32_e32 v13, 31, v12
	s_waitcnt lgkmcnt(2)
	v_sub_f32_e32 v0, v5, v0
	v_pk_mul_f32 v[6:7], v[14:15], v[16:17]
	v_mul_f32_e32 v0, 0x3fb8aa3b, v0
	v_lshl_add_u64 v[12:13], v[12:13], 1, v[8:9]
	v_pk_mul_f32 v[8:9], v[86:87], v[88:89]
	v_and_b32_sdwa v10, v6, v242 dst_sel:DWORD dst_unused:UNUSED_PAD src0_sel:WORD_1 src1_sel:DWORD
	v_exp_f32_e32 v97, v0
	v_and_b32_sdwa v0, v7, v242 dst_sel:DWORD dst_unused:UNUSED_PAD src0_sel:WORD_1 src1_sel:DWORD
	v_add3_u32 v6, v6, v10, s71
	v_and_b32_sdwa v10, v8, v242 dst_sel:DWORD dst_unused:UNUSED_PAD src0_sel:WORD_1 src1_sel:DWORD
	v_add3_u32 v0, v7, v0, s71
	v_and_b32_sdwa v7, v9, v242 dst_sel:DWORD dst_unused:UNUSED_PAD src0_sel:WORD_1 src1_sel:DWORD
	v_add3_u32 v8, v8, v10, s71
	v_add3_u32 v7, v9, v7, s71
	v_and_b32_e32 v8, 0xffff0000, v8
	v_and_b32_e32 v7, 0xffff0000, v7
	v_or_b32_sdwa v6, v8, v6 dst_sel:DWORD dst_unused:UNUSED_PAD src0_sel:DWORD src1_sel:WORD_1
	s_waitcnt lgkmcnt(1)
	v_pk_mul_f32 v[8:9], v[90:91], v[84:85]
	v_or_b32_sdwa v7, v7, v0 dst_sel:DWORD dst_unused:UNUSED_PAD src0_sel:DWORD src1_sel:WORD_1
	s_waitcnt lgkmcnt(0)
	v_pk_mul_f32 v[14:15], v[94:95], v[96:97]
	v_and_b32_sdwa v0, v9, v242 dst_sel:DWORD dst_unused:UNUSED_PAD src0_sel:WORD_1 src1_sel:DWORD
	v_and_b32_sdwa v10, v8, v242 dst_sel:DWORD dst_unused:UNUSED_PAD src0_sel:WORD_1 src1_sel:DWORD
	v_add3_u32 v8, v8, v10, s71
	v_add3_u32 v0, v9, v0, s71
	v_and_b32_sdwa v9, v15, v242 dst_sel:DWORD dst_unused:UNUSED_PAD src0_sel:WORD_1 src1_sel:DWORD
	v_and_b32_sdwa v10, v14, v242 dst_sel:DWORD dst_unused:UNUSED_PAD src0_sel:WORD_1 src1_sel:DWORD
	v_add3_u32 v9, v15, v9, s71
	v_add3_u32 v10, v14, v10, s71
	v_and_b32_e32 v9, 0xffff0000, v9
	v_and_b32_e32 v10, 0xffff0000, v10
	v_or_b32_sdwa v9, v9, v0 dst_sel:DWORD dst_unused:UNUSED_PAD src0_sel:DWORD src1_sel:WORD_1
	v_or_b32_sdwa v8, v10, v8 dst_sel:DWORD dst_unused:UNUSED_PAD src0_sel:DWORD src1_sel:WORD_1
	global_store_dwordx4 v[12:13], v[6:9], off
	s_and_saveexec_b64 s[20:21], vcc
	s_cbranch_execz .LBB0_661
	v_mul_f32_e32 v0, 0x3fb8aa3b, v5
	v_exp_f32_e32 v0, v0
	s_add_u32 s28, s66, s8
	s_addc_u32 s29, s67, s9
	v_mov_b32_e32 v4, 0x2be6b000
	global_store_dword v4, v0, s[28:29] offset:512

; DI unsigned f2bf(float f) { unsigned u = __float_as_uint(f); return (u + 0x7fffu + ((u >> 16) & 1u)) >> 16; }
; DI uint4 pack8(const float* f) { uint4 o; o.x = pk2(f[0], f[1]); o.y = pk2(f[2], f[3]); o.z = pk2(f[4], f[5]); o.w = pk2(f[6], f[7]); return o; }
; template <int D> DI void dn_out(float (&x)[64], lf_t Kl, lf_t Ql, lf_t Gn, bf16_t* DW, bf16_t* DQE, bf16_t* DKT, bf16_t* DUT, float* DEG, int item, int t) {
;     ...
;             if (t < 128) { bf16_t* uo = DUT + (((size_t)D * 1152 + item) * 128 + t) * 64;
; #pragma unroll
;                 for (int g8 = 0; g8 < 8; ++g8) *(uint4*)(uo + 8 * g8) = pack8(x + 8 * g8);
;             } else { bf16_t* wbase = DW + (((size_t)D * 1152 + item) * 64) * 128; unsigned woff = (unsigned)((t - 128) * 2);
; #pragma unroll
;                 for (int pi = 0; pi < 64; ++pi) { *(bf16_t*)((char*)wbase + woff) = (bf16_t)f2bf(x[pi]); woff += 256; asm volatile("" : "+v"(woff)); } }
.LBB0_662:
	s_and_b64 vcc, exec, s[20:21]
	s_cbranch_vccz .LBB0_475
	v_mov_b32_e32 v4, v107
	s_movk_i32 s4, 0x7f
	s_nop 0
	v_cmp_lt_i32_e32 vcc, s4, v4
	s_and_saveexec_b64 s[20:21], vcc
	s_xor_b64 s[20:21], exec, s[20:21]
	s_cbranch_execz .LBB0_665
	v_lshrrev_b32_e32 v6, 3, v4
	v_and_b32_e32 v0, 7, v4
	v_lshlrev_b32_e32 v6, 8, v6
	v_lshl_add_u32 v6, v0, 1, v6
	v_add_u32_e32 v6, 0xfffff010, v6
	s_add_u32 s42, s66, s12
	v_add_u32_e32 v0, -16, v6
	s_addc_u32 s43, s67, s13
	v_lshl_add_u64 v[8:9], s[42:43], 0, v[0:1]
	v_bfe_u32 v5, v2, 16, 1
	v_add_co_u32_e32 v8, vcc, 0x1f86a000, v8
	v_add3_u32 v2, v2, v5, s71
	s_nop 0
	v_addc_co_u32_e32 v9, vcc, 0, v9, vcc
	v_mov_b32_e32 v7, v1
	global_store_short_d16_hi v[8:9], v2, off
	v_bfe_u32 v0, v73, 16, 1
	v_lshl_add_u64 v[8:9], s[42:43], 0, v[6:7]
	v_add_co_u32_e32 v8, vcc, 0x1f86a000, v8
	v_add3_u32 v0, v73, v0, s71
	s_nop 0
	v_addc_co_u32_e32 v9, vcc, 0, v9, vcc
	global_store_short_d16_hi v[8:9], v0, off
	v_add_u32_e32 v0, 16, v6
	v_bfe_u32 v2, v72, 16, 1
	v_lshl_add_u64 v[6:7], s[42:43], 0, v[0:1]
	v_add_co_u32_e32 v6, vcc, 0x1f86a000, v6
	v_add3_u32 v2, v72, v2, s71
	s_nop 0
	v_addc_co_u32_e32 v7, vcc, 0, v7, vcc
	v_add_u32_e32 v0, 16, v0
	global_store_short_d16_hi v[6:7], v2, off
	v_bfe_u32 v2, v70, 16, 1
	v_lshl_add_u64 v[6:7], s[42:43], 0, v[0:1]
	v_add_co_u32_e32 v6, vcc, 0x1f86a000, v6
	v_add3_u32 v2, v70, v2, s71
	s_nop 0
	v_addc_co_u32_e32 v7, vcc, 0, v7, vcc
	v_add_u32_e32 v0, 16, v0
	global_store_short_d16_hi v[6:7], v2, off
	v_bfe_u32 v2, v71, 16, 1
	v_lshl_add_u64 v[6:7], s[42:43], 0, v[0:1]
	v_add_co_u32_e32 v6, vcc, 0x1f86a000, v6
	v_add3_u32 v2, v71, v2, s71
	s_nop 0
	v_addc_co_u32_e32 v7, vcc, 0, v7, vcc
	v_add_u32_e32 v0, 16, v0
	global_store_short_d16_hi v[6:7], v2, off
	v_bfe_u32 v2, v67, 16, 1
	v_lshl_add_u64 v[6:7], s[42:43], 0, v[0:1]
	v_add_co_u32_e32 v6, vcc, 0x1f86a000, v6
	v_add3_u32 v2, v67, v2, s71
	s_nop 0
	v_addc_co_u32_e32 v7, vcc, 0, v7, vcc
	v_add_u32_e32 v0, 16, v0
	global_store_short_d16_hi v[6:7], v2, off
	v_bfe_u32 v2, v66, 16, 1
	v_lshl_add_u64 v[6:7], s[42:43], 0, v[0:1]
	v_add_co_u32_e32 v6, vcc, 0x1f86a000, v6
	v_add3_u32 v2, v66, v2, s71
	s_nop 0
	v_addc_co_u32_e32 v7, vcc, 0, v7, vcc
	v_add_u32_e32 v0, 16, v0
	global_store_short_d16_hi v[6:7], v2, off
	v_bfe_u32 v2, v56, 16, 1
	v_lshl_add_u64 v[6:7], s[42:43], 0, v[0:1]
	v_add_co_u32_e32 v6, vcc, 0x1f86a000, v6
	v_add3_u32 v2, v56, v2, s71
	s_nop 0
	v_addc_co_u32_e32 v7, vcc, 0, v7, vcc
	v_add_u32_e32 v0, 16, v0
	global_store_short_d16_hi v[6:7], v2, off
	v_bfe_u32 v2, v62, 16, 1
	v_lshl_add_u64 v[6:7], s[42:43], 0, v[0:1]
	v_add_co_u32_e32 v6, vcc, 0x1f86a000, v6
	v_add3_u32 v2, v62, v2, s71
	s_nop 0
	v_addc_co_u32_e32 v7, vcc, 0, v7, vcc
	v_add_u32_e32 v0, 16, v0
	global_store_short_d16_hi v[6:7], v2, off
	v_bfe_u32 v2, v57, 16, 1
	v_lshl_add_u64 v[6:7], s[42:43], 0, v[0:1]
	v_add_co_u32_e32 v6, vcc, 0x1f86a000, v6
	v_add3_u32 v2, v57, v2, s71
	s_nop 0
	v_addc_co_u32_e32 v7, vcc, 0, v7, vcc
	v_add_u32_e32 v0, 16, v0
	global_store_short_d16_hi v[6:7], v2, off
	v_bfe_u32 v2, v51, 16, 1
	v_lshl_add_u64 v[6:7], s[42:43], 0, v[0:1]
	v_add_co_u32_e32 v6, vcc, 0x1f86a000, v6
	v_add3_u32 v2, v51, v2, s71
	s_nop 0
	v_addc_co_u32_e32 v7, vcc, 0, v7, vcc
	global_store_short_d16_hi v[6:7], v2, off
	v_add_u32_e32 v0, 16, v0
	v_bfe_u32 v2, v3, 16, 1
	v_add3_u32 v5, v3, v2, s71
	v_lshl_add_u64 v[2:3], s[42:43], 0, v[0:1]
	v_add_co_u32_e32 v2, vcc, 0x1f86a000, v2
	v_add_u32_e32 v0, 16, v0
	s_nop 0
	v_addc_co_u32_e32 v3, vcc, 0, v3, vcc
	global_store_short_d16_hi v[2:3], v5, off
	v_bfe_u32 v2, v60, 16, 1
	v_add3_u32 v5, v60, v2, s71
	v_lshl_add_u64 v[2:3], s[42:43], 0, v[0:1]
	v_add_co_u32_e32 v2, vcc, 0x1f86a000, v2
	v_add_u32_e32 v0, 16, v0
	s_nop 0
	v_addc_co_u32_e32 v3, vcc, 0, v3, vcc
	global_store_short_d16_hi v[2:3], v5, off
	v_bfe_u32 v2, v59, 16, 1
	v_add3_u32 v5, v59, v2, s71
	v_lshl_add_u64 v[2:3], s[42:43], 0, v[0:1]
	v_add_co_u32_e32 v2, vcc, 0x1f86a000, v2
	v_add_u32_e32 v0, 16, v0
	s_nop 0
	v_addc_co_u32_e32 v3, vcc, 0, v3, vcc
	global_store_short_d16_hi v[2:3], v5, off
	v_bfe_u32 v2, v58, 16, 1
	v_add3_u32 v5, v58, v2, s71
	v_lshl_add_u64 v[2:3], s[42:43], 0, v[0:1]
	v_add_co_u32_e32 v2, vcc, 0x1f86a000, v2
	v_add_u32_e32 v0, 16, v0
	s_nop 0
	v_addc_co_u32_e32 v3, vcc, 0, v3, vcc
	global_store_short_d16_hi v[2:3], v5, off
	v_bfe_u32 v2, v50, 16, 1
	v_add3_u32 v5, v50, v2, s71
	v_lshl_add_u64 v[2:3], s[42:43], 0, v[0:1]
	v_add_co_u32_e32 v2, vcc, 0x1f86a000, v2
	v_add_u32_e32 v0, 0xf10, v0
	s_nop 0
	v_addc_co_u32_e32 v3, vcc, 0, v3, vcc
	global_store_short_d16_hi v[2:3], v5, off
	v_bfe_u32 v2, v55, 16, 1
	v_add3_u32 v5, v55, v2, s71
	v_lshl_add_u64 v[2:3], s[42:43], 0, v[0:1]
	v_add_co_u32_e32 v2, vcc, 0x1f86a000, v2
	v_add_u32_e32 v0, 16, v0
	s_nop 0
	v_addc_co_u32_e32 v3, vcc, 0, v3, vcc
	global_store_short_d16_hi v[2:3], v5, off
	v_bfe_u32 v2, v54, 16, 1
	v_add3_u32 v5, v54, v2, s71
	v_lshl_add_u64 v[2:3], s[42:43], 0, v[0:1]
	v_add_co_u32_e32 v2, vcc, 0x1f86a000, v2
	v_add_u32_e32 v0, 16, v0
	s_nop 0
	v_addc_co_u32_e32 v3, vcc, 0, v3, vcc
	global_store_short_d16_hi v[2:3], v5, off
	v_bfe_u32 v2, v53, 16, 1
	v_add3_u32 v5, v53, v2, s71
	v_lshl_add_u64 v[2:3], s[42:43], 0, v[0:1]
	v_add_co_u32_e32 v2, vcc, 0x1f86a000, v2
	v_add_u32_e32 v0, 16, v0
	s_nop 0
	v_addc_co_u32_e32 v3, vcc, 0, v3, vcc
	global_store_short_d16_hi v[2:3], v5, off
	v_bfe_u32 v2, v52, 16, 1
	v_add3_u32 v5, v52, v2, s71
	v_lshl_add_u64 v[2:3], s[42:43], 0, v[0:1]
	v_add_co_u32_e32 v2, vcc, 0x1f86a000, v2
	v_add_u32_e32 v0, 16, v0
	s_nop 0
	v_addc_co_u32_e32 v3, vcc, 0, v3, vcc
	global_store_short_d16_hi v[2:3], v5, off
; DI unsigned f2bf(float f) { unsigned u = __float_as_uint(f); return (u + 0x7fffu + ((u >> 16) & 1u)) >> 16; }
; template <int D> DI void dn_out(float (&x)[64], lf_t Kl, lf_t Ql, lf_t Gn, bf16_t* DW, bf16_t* DQE, bf16_t* DKT, bf16_t* DUT, float* DEG, int item, int t) {
;     ...
;             } else { bf16_t* wbase = DW + (((size_t)D * 1152 + item) * 64) * 128; unsigned woff = (unsigned)((t - 128) * 2);
; #pragma unroll
;                 for (int pi = 0; pi < 64; ++pi) { *(bf16_t*)((char*)wbase + woff) = (bf16_t)f2bf(x[pi]); woff += 256; asm volatile("" : "+v"(woff)); } }
	v_bfe_u32 v2, v49, 16, 1
	v_add3_u32 v5, v49, v2, s71
	v_lshl_add_u64 v[2:3], s[42:43], 0, v[0:1]
	v_add_co_u32_e32 v2, vcc, 0x1f86a000, v2
	v_add_u32_e32 v0, 16, v0
	s_nop 0
	v_addc_co_u32_e32 v3, vcc, 0, v3, vcc
	global_store_short_d16_hi v[2:3], v5, off
	v_bfe_u32 v2, v48, 16, 1
	v_add3_u32 v5, v48, v2, s71
	v_lshl_add_u64 v[2:3], s[42:43], 0, v[0:1]
	v_add_co_u32_e32 v2, vcc, 0x1f86a000, v2
	v_add_u32_e32 v0, 16, v0
	s_nop 0
	v_addc_co_u32_e32 v3, vcc, 0, v3, vcc
	global_store_short_d16_hi v[2:3], v5, off
	v_bfe_u32 v2, v47, 16, 1
	v_add3_u32 v5, v47, v2, s71
	v_lshl_add_u64 v[2:3], s[42:43], 0, v[0:1]
	v_add_co_u32_e32 v2, vcc, 0x1f86a000, v2
	v_add_u32_e32 v0, 16, v0
	s_nop 0
	v_addc_co_u32_e32 v3, vcc, 0, v3, vcc
	global_store_short_d16_hi v[2:3], v5, off
	v_bfe_u32 v2, v46, 16, 1
	v_add3_u32 v5, v46, v2, s71
	v_lshl_add_u64 v[2:3], s[42:43], 0, v[0:1]
	v_add_co_u32_e32 v2, vcc, 0x1f86a000, v2
	v_add_u32_e32 v0, 16, v0
	s_nop 0
	v_addc_co_u32_e32 v3, vcc, 0, v3, vcc
	global_store_short_d16_hi v[2:3], v5, off
	v_bfe_u32 v2, v45, 16, 1
	v_add3_u32 v5, v45, v2, s71
	v_lshl_add_u64 v[2:3], s[42:43], 0, v[0:1]
	v_add_co_u32_e32 v2, vcc, 0x1f86a000, v2
	v_add_u32_e32 v0, 16, v0
	s_nop 0
	v_addc_co_u32_e32 v3, vcc, 0, v3, vcc
	global_store_short_d16_hi v[2:3], v5, off
	v_bfe_u32 v2, v44, 16, 1
	v_add3_u32 v5, v44, v2, s71
	v_lshl_add_u64 v[2:3], s[42:43], 0, v[0:1]
	v_add_co_u32_e32 v2, vcc, 0x1f86a000, v2
	v_add_u32_e32 v0, 16, v0
	s_nop 0
	v_addc_co_u32_e32 v3, vcc, 0, v3, vcc
	global_store_short_d16_hi v[2:3], v5, off
	v_bfe_u32 v2, v43, 16, 1
	v_add3_u32 v5, v43, v2, s71
	v_lshl_add_u64 v[2:3], s[42:43], 0, v[0:1]
	v_add_co_u32_e32 v2, vcc, 0x1f86a000, v2
	v_add_u32_e32 v0, 16, v0
	s_nop 0
	v_addc_co_u32_e32 v3, vcc, 0, v3, vcc
	global_store_short_d16_hi v[2:3], v5, off
	v_bfe_u32 v2, v42, 16, 1
	v_add3_u32 v5, v42, v2, s71
	v_lshl_add_u64 v[2:3], s[42:43], 0, v[0:1]
	v_add_co_u32_e32 v2, vcc, 0x1f86a000, v2
	v_add_u32_e32 v0, 16, v0
	s_nop 0
	v_addc_co_u32_e32 v3, vcc, 0, v3, vcc
	global_store_short_d16_hi v[2:3], v5, off
	v_bfe_u32 v2, v41, 16, 1
	v_add3_u32 v5, v41, v2, s71
	v_lshl_add_u64 v[2:3], s[42:43], 0, v[0:1]
	v_add_co_u32_e32 v2, vcc, 0x1f86a000, v2
	v_add_u32_e32 v0, 16, v0
	s_nop 0
	v_addc_co_u32_e32 v3, vcc, 0, v3, vcc
	global_store_short_d16_hi v[2:3], v5, off
	v_bfe_u32 v2, v40, 16, 1
	v_add3_u32 v5, v40, v2, s71
	v_lshl_add_u64 v[2:3], s[42:43], 0, v[0:1]
	v_add_co_u32_e32 v2, vcc, 0x1f86a000, v2
	v_add_u32_e32 v0, 16, v0
	s_nop 0
	v_addc_co_u32_e32 v3, vcc, 0, v3, vcc
	global_store_short_d16_hi v[2:3], v5, off
	v_bfe_u32 v2, v39, 16, 1
	v_add3_u32 v5, v39, v2, s71
	v_lshl_add_u64 v[2:3], s[42:43], 0, v[0:1]
	v_add_co_u32_e32 v2, vcc, 0x1f86a000, v2
	v_add_u32_e32 v0, 16, v0
	s_nop 0
	v_addc_co_u32_e32 v3, vcc, 0, v3, vcc
	global_store_short_d16_hi v[2:3], v5, off
	v_bfe_u32 v2, v38, 16, 1
	v_add3_u32 v5, v38, v2, s71
	v_lshl_add_u64 v[2:3], s[42:43], 0, v[0:1]
	v_add_co_u32_e32 v2, vcc, 0x1f86a000, v2
	v_add_u32_e32 v0, 0xf10, v0
	s_nop 0
	v_addc_co_u32_e32 v3, vcc, 0, v3, vcc
	global_store_short_d16_hi v[2:3], v5, off
	v_bfe_u32 v2, v37, 16, 1
	v_add3_u32 v5, v37, v2, s71
	v_lshl_add_u64 v[2:3], s[42:43], 0, v[0:1]
	v_add_co_u32_e32 v2, vcc, 0x1f86a000, v2
	v_add_u32_e32 v0, 16, v0
	s_nop 0
	v_addc_co_u32_e32 v3, vcc, 0, v3, vcc
	global_store_short_d16_hi v[2:3], v5, off
	v_bfe_u32 v2, v36, 16, 1
	v_add3_u32 v5, v36, v2, s71
	v_lshl_add_u64 v[2:3], s[42:43], 0, v[0:1]
	v_add_co_u32_e32 v2, vcc, 0x1f86a000, v2
	v_add_u32_e32 v0, 16, v0
	s_nop 0
	v_addc_co_u32_e32 v3, vcc, 0, v3, vcc
	global_store_short_d16_hi v[2:3], v5, off
	v_bfe_u32 v2, v35, 16, 1
	v_add3_u32 v5, v35, v2, s71
	v_lshl_add_u64 v[2:3], s[42:43], 0, v[0:1]
	v_add_co_u32_e32 v2, vcc, 0x1f86a000, v2
	v_add_u32_e32 v0, 16, v0
	s_nop 0
	v_addc_co_u32_e32 v3, vcc, 0, v3, vcc
	global_store_short_d16_hi v[2:3], v5, off
	v_bfe_u32 v2, v34, 16, 1
	v_add3_u32 v5, v34, v2, s71
	v_lshl_add_u64 v[2:3], s[42:43], 0, v[0:1]
	v_add_co_u32_e32 v2, vcc, 0x1f86a000, v2
	v_add_u32_e32 v0, 16, v0
	s_nop 0
	v_addc_co_u32_e32 v3, vcc, 0, v3, vcc
	global_store_short_d16_hi v[2:3], v5, off
	v_bfe_u32 v2, v33, 16, 1
	v_add3_u32 v5, v33, v2, s71
	v_lshl_add_u64 v[2:3], s[42:43], 0, v[0:1]
	v_add_co_u32_e32 v2, vcc, 0x1f86a000, v2
	v_add_u32_e32 v0, 16, v0
	s_nop 0
	v_addc_co_u32_e32 v3, vcc, 0, v3, vcc
	global_store_short_d16_hi v[2:3], v5, off
	v_bfe_u32 v2, v32, 16, 1
	v_add3_u32 v5, v32, v2, s71
	v_lshl_add_u64 v[2:3], s[42:43], 0, v[0:1]
	v_add_co_u32_e32 v2, vcc, 0x1f86a000, v2
	v_add_u32_e32 v0, 16, v0
	s_nop 0
	v_addc_co_u32_e32 v3, vcc, 0, v3, vcc
	global_store_short_d16_hi v[2:3], v5, off
	v_bfe_u32 v2, v31, 16, 1
	v_add3_u32 v5, v31, v2, s71
	v_lshl_add_u64 v[2:3], s[42:43], 0, v[0:1]
	v_add_co_u32_e32 v2, vcc, 0x1f86a000, v2
	v_add_u32_e32 v0, 16, v0
	s_nop 0
	v_addc_co_u32_e32 v3, vcc, 0, v3, vcc
	global_store_short_d16_hi v[2:3], v5, off
	v_bfe_u32 v2, v30, 16, 1
	v_add3_u32 v5, v30, v2, s71
	v_lshl_add_u64 v[2:3], s[42:43], 0, v[0:1]
	v_add_co_u32_e32 v2, vcc, 0x1f86a000, v2
	v_add_u32_e32 v0, 16, v0
	s_nop 0
	v_addc_co_u32_e32 v3, vcc, 0, v3, vcc
	global_store_short_d16_hi v[2:3], v5, off
	v_bfe_u32 v2, v29, 16, 1
	v_add3_u32 v5, v29, v2, s71
	v_lshl_add_u64 v[2:3], s[42:43], 0, v[0:1]
	v_add_co_u32_e32 v2, vcc, 0x1f86a000, v2
	v_add_u32_e32 v0, 16, v0
	s_nop 0
	v_addc_co_u32_e32 v3, vcc, 0, v3, vcc
	global_store_short_d16_hi v[2:3], v5, off
	v_bfe_u32 v2, v28, 16, 1
	v_add3_u32 v5, v28, v2, s71
	v_lshl_add_u64 v[2:3], s[42:43], 0, v[0:1]
	v_add_co_u32_e32 v2, vcc, 0x1f86a000, v2
	v_add_u32_e32 v0, 16, v0
	s_nop 0
	v_addc_co_u32_e32 v3, vcc, 0, v3, vcc
; DI unsigned f2bf(float f) { unsigned u = __float_as_uint(f); return (u + 0x7fffu + ((u >> 16) & 1u)) >> 16; }
; template <int D> DI void dn_out(float (&x)[64], lf_t Kl, lf_t Ql, lf_t Gn, bf16_t* DW, bf16_t* DQE, bf16_t* DKT, bf16_t* DUT, float* DEG, int item, int t) {
;     ...
;             } else { bf16_t* wbase = DW + (((size_t)D * 1152 + item) * 64) * 128; unsigned woff = (unsigned)((t - 128) * 2);
; #pragma unroll
;                 for (int pi = 0; pi < 64; ++pi) { *(bf16_t*)((char*)wbase + woff) = (bf16_t)f2bf(x[pi]); woff += 256; asm volatile("" : "+v"(woff)); } }
	global_store_short_d16_hi v[2:3], v5, off
	v_bfe_u32 v2, v27, 16, 1
	v_add3_u32 v5, v27, v2, s71
	v_lshl_add_u64 v[2:3], s[42:43], 0, v[0:1]
	v_add_co_u32_e32 v2, vcc, 0x1f86a000, v2
	v_add_u32_e32 v0, 16, v0
	s_nop 0
	v_addc_co_u32_e32 v3, vcc, 0, v3, vcc
	global_store_short_d16_hi v[2:3], v5, off
	v_bfe_u32 v2, v26, 16, 1
	v_add3_u32 v5, v26, v2, s71
	v_lshl_add_u64 v[2:3], s[42:43], 0, v[0:1]
	v_add_co_u32_e32 v2, vcc, 0x1f86a000, v2
	v_add_u32_e32 v0, 16, v0
	s_nop 0
	v_addc_co_u32_e32 v3, vcc, 0, v3, vcc
	global_store_short_d16_hi v[2:3], v5, off
	v_bfe_u32 v2, v25, 16, 1
	v_add3_u32 v5, v25, v2, s71
	v_lshl_add_u64 v[2:3], s[42:43], 0, v[0:1]
	v_add_co_u32_e32 v2, vcc, 0x1f86a000, v2
	v_add_u32_e32 v0, 16, v0
	s_nop 0
	v_addc_co_u32_e32 v3, vcc, 0, v3, vcc
	global_store_short_d16_hi v[2:3], v5, off
	v_bfe_u32 v2, v24, 16, 1
	v_add3_u32 v5, v24, v2, s71
	v_lshl_add_u64 v[2:3], s[42:43], 0, v[0:1]
	v_add_co_u32_e32 v2, vcc, 0x1f86a000, v2
	v_add_u32_e32 v0, 16, v0
	s_nop 0
	v_addc_co_u32_e32 v3, vcc, 0, v3, vcc
	global_store_short_d16_hi v[2:3], v5, off
	v_bfe_u32 v2, v23, 16, 1
	v_add3_u32 v5, v23, v2, s71
	v_lshl_add_u64 v[2:3], s[42:43], 0, v[0:1]
	v_add_co_u32_e32 v2, vcc, 0x1f86a000, v2
	v_add_u32_e32 v0, 16, v0
	s_nop 0
	v_addc_co_u32_e32 v3, vcc, 0, v3, vcc
	global_store_short_d16_hi v[2:3], v5, off
	v_bfe_u32 v2, v22, 16, 1
	v_add3_u32 v5, v22, v2, s71
	v_lshl_add_u64 v[2:3], s[42:43], 0, v[0:1]
	v_add_co_u32_e32 v2, vcc, 0x1f86a000, v2
	v_add_u32_e32 v0, 0xf10, v0
	s_nop 0
	v_addc_co_u32_e32 v3, vcc, 0, v3, vcc
	global_store_short_d16_hi v[2:3], v5, off
	v_bfe_u32 v2, v65, 16, 1
	v_add3_u32 v5, v65, v2, s71
	v_lshl_add_u64 v[2:3], s[42:43], 0, v[0:1]
	v_add_co_u32_e32 v2, vcc, 0x1f86a000, v2
	v_add_u32_e32 v0, 16, v0
	s_nop 0
	v_addc_co_u32_e32 v3, vcc, 0, v3, vcc
	global_store_short_d16_hi v[2:3], v5, off
	v_bfe_u32 v2, v64, 16, 1
	v_add3_u32 v5, v64, v2, s71
	v_lshl_add_u64 v[2:3], s[42:43], 0, v[0:1]
	v_add_co_u32_e32 v2, vcc, 0x1f86a000, v2
	v_add_u32_e32 v0, 16, v0
	s_nop 0
	v_addc_co_u32_e32 v3, vcc, 0, v3, vcc
	global_store_short_d16_hi v[2:3], v5, off
	v_bfe_u32 v2, v63, 16, 1
	v_add3_u32 v5, v63, v2, s71
	v_lshl_add_u64 v[2:3], s[42:43], 0, v[0:1]
	v_add_co_u32_e32 v2, vcc, 0x1f86a000, v2
	v_add_u32_e32 v0, 16, v0
	s_nop 0
	v_addc_co_u32_e32 v3, vcc, 0, v3, vcc
	global_store_short_d16_hi v[2:3], v5, off
	v_bfe_u32 v2, v61, 16, 1
	v_add3_u32 v5, v61, v2, s71
	v_lshl_add_u64 v[2:3], s[42:43], 0, v[0:1]
	v_add_co_u32_e32 v2, vcc, 0x1f86a000, v2
	v_add_u32_e32 v0, 16, v0
	s_nop 0
	v_addc_co_u32_e32 v3, vcc, 0, v3, vcc
	global_store_short_d16_hi v[2:3], v5, off
	v_bfe_u32 v2, v76, 16, 1
	v_add3_u32 v5, v76, v2, s71
	v_lshl_add_u64 v[2:3], s[42:43], 0, v[0:1]
	v_add_co_u32_e32 v2, vcc, 0x1f86a000, v2
	v_add_u32_e32 v0, 16, v0
	s_nop 0
	v_addc_co_u32_e32 v3, vcc, 0, v3, vcc
	global_store_short_d16_hi v[2:3], v5, off
	v_bfe_u32 v2, v75, 16, 1
	v_add3_u32 v5, v75, v2, s71
	v_lshl_add_u64 v[2:3], s[42:43], 0, v[0:1]
	v_add_co_u32_e32 v2, vcc, 0x1f86a000, v2
	v_add_u32_e32 v0, 16, v0
	s_nop 0
	v_addc_co_u32_e32 v3, vcc, 0, v3, vcc
	global_store_short_d16_hi v[2:3], v5, off
	v_bfe_u32 v2, v74, 16, 1
	v_add3_u32 v5, v74, v2, s71
	v_lshl_add_u64 v[2:3], s[42:43], 0, v[0:1]
	v_add_co_u32_e32 v2, vcc, 0x1f86a000, v2
	v_add_u32_e32 v0, 16, v0
	s_nop 0
	v_addc_co_u32_e32 v3, vcc, 0, v3, vcc
	global_store_short_d16_hi v[2:3], v5, off
	v_bfe_u32 v2, v11, 16, 1
	v_add3_u32 v5, v11, v2, s71
	v_lshl_add_u64 v[2:3], s[42:43], 0, v[0:1]
	v_add_co_u32_e32 v2, vcc, 0x1f86a000, v2
	v_add_u32_e32 v0, 16, v0
	s_nop 0
	v_addc_co_u32_e32 v3, vcc, 0, v3, vcc
	global_store_short_d16_hi v[2:3], v5, off
	v_bfe_u32 v2, v80, 16, 1
	v_add3_u32 v5, v80, v2, s71
	v_lshl_add_u64 v[2:3], s[42:43], 0, v[0:1]
	v_add_co_u32_e32 v2, vcc, 0x1f86a000, v2
	v_add_u32_e32 v0, 16, v0
	s_nop 0
	v_addc_co_u32_e32 v3, vcc, 0, v3, vcc
	global_store_short_d16_hi v[2:3], v5, off
	v_bfe_u32 v2, v79, 16, 1
	v_add3_u32 v5, v79, v2, s71
	v_lshl_add_u64 v[2:3], s[42:43], 0, v[0:1]
	v_add_co_u32_e32 v2, vcc, 0x1f86a000, v2
	v_add_u32_e32 v0, 16, v0
	s_nop 0
	v_addc_co_u32_e32 v3, vcc, 0, v3, vcc
	global_store_short_d16_hi v[2:3], v5, off
	v_bfe_u32 v2, v78, 16, 1
	v_add3_u32 v5, v78, v2, s71
	v_lshl_add_u64 v[2:3], s[42:43], 0, v[0:1]
	v_add_co_u32_e32 v2, vcc, 0x1f86a000, v2
	v_add_u32_e32 v0, 16, v0
	s_nop 0
	v_addc_co_u32_e32 v3, vcc, 0, v3, vcc
	global_store_short_d16_hi v[2:3], v5, off
	v_bfe_u32 v2, v77, 16, 1
	v_add3_u32 v5, v77, v2, s71
	v_lshl_add_u64 v[2:3], s[42:43], 0, v[0:1]
	v_add_co_u32_e32 v2, vcc, 0x1f86a000, v2
	v_add_u32_e32 v0, 16, v0
	s_nop 0
	v_addc_co_u32_e32 v3, vcc, 0, v3, vcc
	global_store_short_d16_hi v[2:3], v5, off
	v_bfe_u32 v2, v82, 16, 1
	v_add3_u32 v5, v82, v2, s71
	v_lshl_add_u64 v[2:3], s[42:43], 0, v[0:1]
	v_add_co_u32_e32 v2, vcc, 0x1f86a000, v2
	v_add_u32_e32 v0, 16, v0
	s_nop 0
	v_addc_co_u32_e32 v3, vcc, 0, v3, vcc
	global_store_short_d16_hi v[2:3], v5, off
	v_bfe_u32 v2, v81, 16, 1
	v_add3_u32 v5, v81, v2, s71
	v_lshl_add_u64 v[2:3], s[42:43], 0, v[0:1]
	v_add_co_u32_e32 v2, vcc, 0x1f86a000, v2
	v_add_u32_e32 v0, 16, v0
	s_nop 0
	v_addc_co_u32_e32 v3, vcc, 0, v3, vcc
	global_store_short_d16_hi v[2:3], v5, off
	v_bfe_u32 v2, v69, 16, 1
	v_add3_u32 v5, v69, v2, s71
	v_lshl_add_u64 v[2:3], s[42:43], 0, v[0:1]
	v_add_co_u32_e32 v2, vcc, 0x1f86a000, v2
	v_add_u32_e32 v0, 16, v0
	s_nop 0
	v_addc_co_u32_e32 v3, vcc, 0, v3, vcc
	global_store_short_d16_hi v[2:3], v5, off
	v_bfe_u32 v2, v68, 16, 1
	v_add3_u32 v5, v68, v2, s71
	v_lshl_add_u64 v[2:3], s[42:43], 0, v[0:1]
	v_add_co_u32_e32 v2, vcc, 0x1f86a000, v2
	v_add_u32_e32 v0, 0xf10, v0
	s_nop 0
	v_addc_co_u32_e32 v3, vcc, 0, v3, vcc
	global_store_short_d16_hi v[2:3], v5, off

; DI unsigned pk2(float lo, float hi) { return f2bf(lo) | (f2bf(hi) << 16); }
; template <int D> DI void dn_out(float (&x)[64], lf_t Kl, lf_t Ql, lf_t Gn, bf16_t* DW, bf16_t* DQE, bf16_t* DKT, bf16_t* DUT, float* DEG, int item, int t) {
;     ...
;             for (int i = 0; i < 4; ++i) { const int idx = t + 256 * i, pi = idx >> 4, seg = idx & 15, n = D ? 63 - pi : pi; const float e = __expf(Gd[n]);
;                 const float4 a0 = *(const float4*)(Ql + n * 132 + seg * 8), a1 = *(const float4*)(Ql + n * 132 + seg * 8 + 4);
;                 uint4 o; o.x = pk2(a0.x * e, a0.y * e); o.y = pk2(a0.z * e, a0.w * e); o.z = pk2(a1.x * e, a1.y * e); o.w = pk2(a1.z * e, a1.w * e);
;                 *(uint4*)(DQE + (((size_t)D * 1152 + item) * 64 + pi) * 128 + seg * 8) = o; }
.LBB0_667:
	s_or_b64 exec, exec, s[20:21]
	v_ashrrev_i32_e32 v12, 4, v4
	v_lshl_add_u32 v0, v12, 2, v104
	ds_read_b32 v2, v0
	v_lshlrev_b32_e32 v0, 5, v4
	v_and_b32_e32 v0, 0x1e0, v0
	v_add_u32_e32 v0, v103, v0
	v_mad_u64_u32 v[10:11], s[20:21], v12, s84, v[0:1]
	ds_read_b128 v[6:9], v10
	s_waitcnt lgkmcnt(1)
	v_mul_f32_e32 v2, 0x3fb8aa3b, v2
	v_ashrrev_i32_e32 v13, 31, v12
	v_exp_f32_e32 v2, v2
	v_lshlrev_b32_e32 v3, 8, v4
	v_and_b32_e32 v14, 15, v12
	v_lshrrev_b32_e32 v15, 4, v12
	v_lshlrev_b32_e32 v14, 4, v14
	v_lshl_add_u32 v14, v15, 12, v14
	v_mov_b32_e32 v15, 0
	v_and_b32_e32 v13, 0xf00, v3
	s_add_u32 s20, s66, s12
	v_or_b32_e32 v14, v14, v13
	s_addc_u32 s21, s67, s13
	v_lshl_add_u64 v[22:23], s[20:21], 0, v[14:15]
	ds_read_b128 v[14:17], v10 offset:16
	s_waitcnt lgkmcnt(1)
	v_mov_b32_e32 v10, v6
	v_mov_b32_e32 v11, v8
	v_pk_mul_f32 v[10:11], v[10:11], v[2:3] op_sel_hi:[1,0]
	v_mov_b32_e32 v8, v7
	v_pk_mul_f32 v[6:7], v[8:9], v[2:3] op_sel_hi:[1,0]
	v_and_b32_sdwa v8, v10, v242 dst_sel:DWORD dst_unused:UNUSED_PAD src0_sel:WORD_1 src1_sel:DWORD
	v_add3_u32 v8, v10, v8, s71
	v_and_b32_sdwa v10, v6, v242 dst_sel:DWORD dst_unused:UNUSED_PAD src0_sel:WORD_1 src1_sel:DWORD
	v_add3_u32 v6, v6, v10, s71
	v_and_b32_sdwa v3, v11, v242 dst_sel:DWORD dst_unused:UNUSED_PAD src0_sel:WORD_1 src1_sel:DWORD
	v_and_b32_sdwa v9, v7, v242 dst_sel:DWORD dst_unused:UNUSED_PAD src0_sel:WORD_1 src1_sel:DWORD
	v_and_b32_e32 v6, 0xffff0000, v6
	v_add3_u32 v3, v11, v3, s71
	v_add3_u32 v7, v7, v9, s71
	v_or_b32_sdwa v6, v6, v8 dst_sel:DWORD dst_unused:UNUSED_PAD src0_sel:DWORD src1_sel:WORD_1
	s_waitcnt lgkmcnt(0)
	v_mov_b32_e32 v8, v14
	v_mov_b32_e32 v9, v16
	v_and_b32_e32 v7, 0xffff0000, v7
	v_pk_mul_f32 v[8:9], v[2:3], v[8:9] op_sel_hi:[0,1]
	v_mov_b32_e32 v16, v15
	v_or_b32_sdwa v7, v7, v3 dst_sel:DWORD dst_unused:UNUSED_PAD src0_sel:DWORD src1_sel:WORD_1
	v_pk_mul_f32 v[2:3], v[2:3], v[16:17] op_sel_hi:[0,1]
	v_and_b32_sdwa v11, v8, v242 dst_sel:DWORD dst_unused:UNUSED_PAD src0_sel:WORD_1 src1_sel:DWORD
	v_add3_u32 v8, v8, v11, s71
	v_and_b32_sdwa v11, v2, v242 dst_sel:DWORD dst_unused:UNUSED_PAD src0_sel:WORD_1 src1_sel:DWORD
	v_add3_u32 v2, v2, v11, s71
	v_and_b32_sdwa v10, v9, v242 dst_sel:DWORD dst_unused:UNUSED_PAD src0_sel:WORD_1 src1_sel:DWORD
	v_and_b32_e32 v2, 0xffff0000, v2
	v_add3_u32 v9, v9, v10, s71
	v_and_b32_sdwa v10, v3, v242 dst_sel:DWORD dst_unused:UNUSED_PAD src0_sel:WORD_1 src1_sel:DWORD
	v_or_b32_sdwa v8, v2, v8 dst_sel:DWORD dst_unused:UNUSED_PAD src0_sel:DWORD src1_sel:WORD_1
	v_add_u32_e32 v2, 0x100, v4
	v_add3_u32 v3, v3, v10, s71
	v_ashrrev_i32_e32 v10, 4, v2
	v_lshl_add_u32 v2, v10, 2, v104
	ds_read_b32 v14, v2
	s_mov_b32 s4, 0x21c6a000
	v_and_b32_e32 v3, 0xffff0000, v3
	v_add_co_u32_e32 v2, vcc, s4, v22
	v_or_b32_sdwa v9, v3, v9 dst_sel:DWORD dst_unused:UNUSED_PAD src0_sel:DWORD src1_sel:WORD_1
	s_nop 0
	v_addc_co_u32_e32 v3, vcc, 0, v23, vcc
	global_store_dwordx4 v[2:3], v[6:9], off
	s_waitcnt lgkmcnt(0)
	v_mul_f32_e32 v2, 0x3fb8aa3b, v14
	v_mad_u64_u32 v[14:15], s[28:29], v10, s84, v[0:1]
	ds_read_b128 v[6:9], v14
	v_ashrrev_i32_e32 v11, 31, v10
	v_exp_f32_e32 v2, v2
	v_and_b32_e32 v16, 15, v10
	v_lshrrev_b32_e32 v17, 4, v10
	v_lshlrev_b32_e32 v16, 4, v16
	v_lshl_add_u32 v16, v17, 12, v16
	v_mov_b32_e32 v17, 0
	v_or_b32_e32 v16, v16, v13
	v_lshl_add_u64 v[26:27], s[20:21], 0, v[16:17]
	ds_read_b128 v[14:17], v14 offset:16
	s_waitcnt lgkmcnt(1)
	v_mov_b32_e32 v23, v8
	v_mov_b32_e32 v8, v7
	v_mov_b32_e32 v22, v6
	v_pk_mul_f32 v[6:7], v[8:9], v[2:3] op_sel_hi:[1,0]
	v_pk_mul_f32 v[22:23], v[22:23], v[2:3] op_sel_hi:[1,0]
	v_and_b32_sdwa v9, v7, v242 dst_sel:DWORD dst_unused:UNUSED_PAD src0_sel:WORD_1 src1_sel:DWORD
	v_and_b32_sdwa v11, v6, v242 dst_sel:DWORD dst_unused:UNUSED_PAD src0_sel:WORD_1 src1_sel:DWORD
	v_and_b32_sdwa v3, v23, v242 dst_sel:DWORD dst_unused:UNUSED_PAD src0_sel:WORD_1 src1_sel:DWORD
	v_and_b32_sdwa v8, v22, v242 dst_sel:DWORD dst_unused:UNUSED_PAD src0_sel:WORD_1 src1_sel:DWORD
	v_add3_u32 v7, v7, v9, s71
	v_add3_u32 v6, v6, v11, s71
	v_add3_u32 v8, v22, v8, s71
	v_add3_u32 v3, v23, v3, s71
	v_and_b32_e32 v7, 0xffff0000, v7
	v_and_b32_e32 v6, 0xffff0000, v6
	v_or_b32_sdwa v23, v7, v3 dst_sel:DWORD dst_unused:UNUSED_PAD src0_sel:DWORD src1_sel:WORD_1
	v_or_b32_sdwa v22, v6, v8 dst_sel:DWORD dst_unused:UNUSED_PAD src0_sel:DWORD src1_sel:WORD_1
	s_waitcnt lgkmcnt(0)
	v_mov_b32_e32 v6, v14
	v_mov_b32_e32 v7, v16
	v_pk_mul_f32 v[6:7], v[2:3], v[6:7] op_sel_hi:[0,1]
	v_mov_b32_e32 v16, v15
	v_pk_mul_f32 v[2:3], v[2:3], v[16:17] op_sel_hi:[0,1]
	v_and_b32_sdwa v9, v6, v242 dst_sel:DWORD dst_unused:UNUSED_PAD src0_sel:WORD_1 src1_sel:DWORD
	v_add3_u32 v6, v6, v9, s71
	v_and_b32_sdwa v9, v2, v242 dst_sel:DWORD dst_unused:UNUSED_PAD src0_sel:WORD_1 src1_sel:DWORD
	v_add3_u32 v2, v2, v9, s71
	v_and_b32_e32 v2, 0xffff0000, v2
	v_or_b32_sdwa v24, v2, v6 dst_sel:DWORD dst_unused:UNUSED_PAD src0_sel:DWORD src1_sel:WORD_1
	v_add_u32_e32 v2, 0x200, v4
	v_and_b32_sdwa v8, v7, v242 dst_sel:DWORD dst_unused:UNUSED_PAD src0_sel:WORD_1 src1_sel:DWORD
	v_ashrrev_i32_e32 v6, 4, v2
	v_add3_u32 v7, v7, v8, s71
	v_and_b32_sdwa v8, v3, v242 dst_sel:DWORD dst_unused:UNUSED_PAD src0_sel:WORD_1 src1_sel:DWORD
	v_lshl_add_u32 v2, v6, 2, v104
	v_add3_u32 v3, v3, v8, s71
	ds_read_b32 v8, v2
	v_and_b32_e32 v3, 0xffff0000, v3
	v_add_co_u32_e32 v2, vcc, s4, v26
	v_or_b32_sdwa v25, v3, v7 dst_sel:DWORD dst_unused:UNUSED_PAD src0_sel:DWORD src1_sel:WORD_1
	s_nop 0
	v_addc_co_u32_e32 v3, vcc, 0, v27, vcc
	global_store_dwordx4 v[2:3], v[22:25], off
	s_waitcnt lgkmcnt(0)
; DI unsigned pk2(float lo, float hi) { return f2bf(lo) | (f2bf(hi) << 16); }
; DI uint4 pack8(const float* f) { uint4 o; o.x = pk2(f[0], f[1]); o.y = pk2(f[2], f[3]); o.z = pk2(f[4], f[5]); o.w = pk2(f[6], f[7]); return o; }
; template <int D> DI void dn_out(float (&x)[64], lf_t Kl, lf_t Ql, lf_t Gn, bf16_t* DW, bf16_t* DQE, bf16_t* DKT, bf16_t* DUT, float* DEG, int item, int t) {
;     ...
;             for (int i = 0; i < 4; ++i) { const int idx = t + 256 * i, pi = idx >> 4, seg = idx & 15, n = D ? 63 - pi : pi; const float e = __expf(Gd[n]);
;                 const float4 a0 = *(const float4*)(Ql + n * 132 + seg * 8), a1 = *(const float4*)(Ql + n * 132 + seg * 8 + 4);
;                 uint4 o; o.x = pk2(a0.x * e, a0.y * e); o.y = pk2(a0.z * e, a0.w * e); o.z = pk2(a1.x * e, a1.y * e); o.w = pk2(a1.z * e, a1.w * e);
;                 *(uint4*)(DQE + (((size_t)D * 1152 + item) * 64 + pi) * 128 + seg * 8) = o; }
; #pragma unroll
;             for (int i = 0; i < 4; ++i) { const int idx = t + 256 * i, dk = idx & 127, pg = idx >> 7; float v[8];
; #pragma unroll
;                 for (int e = 0; e < 8; ++e) { const int pi = 8 * pg + e, n = D ? 63 - pi : pi; v[e] = Kl[n * 132 + dk] * __expf(glast - Gd[n]); }
;                 *(uint4*)(DKT + (((size_t)D * 1152 + item) * 128 + dk) * 64 + 8 * pg) = pack8(v); }
	v_mul_f32_e32 v2, 0x3fb8aa3b, v8
	v_mad_u64_u32 v[8:9], s[28:29], v6, s84, v[0:1]
	ds_read_b128 v[14:17], v8
	v_ashrrev_i32_e32 v7, 31, v6
	v_exp_f32_e32 v2, v2
	v_and_b32_e32 v22, 15, v6
	v_lshrrev_b32_e32 v23, 4, v6
	v_lshlrev_b32_e32 v22, 4, v22
	v_lshl_add_u32 v22, v23, 12, v22
	v_mov_b32_e32 v23, 0
	v_or_b32_e32 v22, v22, v13
	v_lshl_add_u64 v[26:27], s[20:21], 0, v[22:23]
	ds_read_b128 v[22:25], v8 offset:16
	s_waitcnt lgkmcnt(1)
	v_mov_b32_e32 v8, v14
	v_mov_b32_e32 v9, v16
	v_pk_mul_f32 v[8:9], v[8:9], v[2:3] op_sel_hi:[1,0]
	v_mov_b32_e32 v16, v15
	v_pk_mul_f32 v[14:15], v[16:17], v[2:3] op_sel_hi:[1,0]
	v_and_b32_sdwa v3, v9, v242 dst_sel:DWORD dst_unused:UNUSED_PAD src0_sel:WORD_1 src1_sel:DWORD
	v_and_b32_sdwa v7, v8, v242 dst_sel:DWORD dst_unused:UNUSED_PAD src0_sel:WORD_1 src1_sel:DWORD
	v_add3_u32 v7, v8, v7, s71
	v_add3_u32 v3, v9, v3, s71
	v_and_b32_sdwa v8, v15, v242 dst_sel:DWORD dst_unused:UNUSED_PAD src0_sel:WORD_1 src1_sel:DWORD
	v_and_b32_sdwa v9, v14, v242 dst_sel:DWORD dst_unused:UNUSED_PAD src0_sel:WORD_1 src1_sel:DWORD
	v_add3_u32 v8, v15, v8, s71
	v_add3_u32 v9, v14, v9, s71
	v_and_b32_e32 v8, 0xffff0000, v8
	v_and_b32_e32 v9, 0xffff0000, v9
	v_or_b32_sdwa v15, v8, v3 dst_sel:DWORD dst_unused:UNUSED_PAD src0_sel:DWORD src1_sel:WORD_1
	v_or_b32_sdwa v14, v9, v7 dst_sel:DWORD dst_unused:UNUSED_PAD src0_sel:DWORD src1_sel:WORD_1
	s_waitcnt lgkmcnt(0)
	v_mov_b32_e32 v8, v22
	v_mov_b32_e32 v9, v24
	v_pk_mul_f32 v[8:9], v[2:3], v[8:9] op_sel_hi:[0,1]
	v_mov_b32_e32 v24, v23
	v_pk_mul_f32 v[2:3], v[2:3], v[24:25] op_sel_hi:[0,1]
	v_and_b32_sdwa v11, v8, v242 dst_sel:DWORD dst_unused:UNUSED_PAD src0_sel:WORD_1 src1_sel:DWORD
	v_add3_u32 v8, v8, v11, s71
	v_and_b32_sdwa v11, v2, v242 dst_sel:DWORD dst_unused:UNUSED_PAD src0_sel:WORD_1 src1_sel:DWORD
	v_and_b32_sdwa v7, v9, v242 dst_sel:DWORD dst_unused:UNUSED_PAD src0_sel:WORD_1 src1_sel:DWORD
	v_add3_u32 v2, v2, v11, s71
	v_add3_u32 v7, v9, v7, s71
	v_and_b32_sdwa v9, v3, v242 dst_sel:DWORD dst_unused:UNUSED_PAD src0_sel:WORD_1 src1_sel:DWORD
	v_and_b32_e32 v2, 0xffff0000, v2
	v_add3_u32 v3, v3, v9, s71
	v_or_b32_sdwa v16, v2, v8 dst_sel:DWORD dst_unused:UNUSED_PAD src0_sel:DWORD src1_sel:WORD_1
	v_add_u32_e32 v2, 0x300, v4
	v_and_b32_e32 v3, 0xffff0000, v3
	v_ashrrev_i32_e32 v2, 4, v2
	v_or_b32_sdwa v17, v3, v7 dst_sel:DWORD dst_unused:UNUSED_PAD src0_sel:DWORD src1_sel:WORD_1
	v_lshl_add_u32 v3, v2, 2, v104
	ds_read_b32 v7, v3
	v_add_co_u32_e32 v8, vcc, s4, v26
	v_mad_u64_u32 v[22:23], s[28:29], v2, s84, v[0:1]
	s_nop 0
	v_addc_co_u32_e32 v9, vcc, 0, v27, vcc
	global_store_dwordx4 v[8:9], v[14:17], off
	ds_read_b128 v[14:17], v22
	v_ashrrev_i32_e32 v3, 31, v2
	s_waitcnt lgkmcnt(1)
	v_mul_f32_e32 v7, 0x3fb8aa3b, v7
	v_exp_f32_e32 v8, v7
	v_and_b32_e32 v24, 15, v2
	v_lshrrev_b32_e32 v25, 4, v2
	v_lshlrev_b32_e32 v24, 4, v24
	v_lshl_add_u32 v24, v25, 12, v24
	v_mov_b32_e32 v25, 0
	v_or_b32_e32 v24, v24, v13
	v_lshl_add_u64 v[26:27], s[20:21], 0, v[24:25]
	ds_read_b128 v[22:25], v22 offset:16
	s_waitcnt lgkmcnt(1)
	v_mov_b32_e32 v29, v16
	v_mov_b32_e32 v16, v15
	v_mov_b32_e32 v28, v14
	v_pk_mul_f32 v[14:15], v[16:17], v[8:9] op_sel_hi:[1,0]
	v_pk_mul_f32 v[28:29], v[28:29], v[8:9] op_sel_hi:[1,0]
	v_and_b32_sdwa v9, v14, v242 dst_sel:DWORD dst_unused:UNUSED_PAD src0_sel:WORD_1 src1_sel:DWORD
	v_and_b32_sdwa v3, v28, v242 dst_sel:DWORD dst_unused:UNUSED_PAD src0_sel:WORD_1 src1_sel:DWORD
	v_add3_u32 v9, v14, v9, s71
	v_add3_u32 v3, v28, v3, s71
	v_and_b32_sdwa v7, v15, v242 dst_sel:DWORD dst_unused:UNUSED_PAD src0_sel:WORD_1 src1_sel:DWORD
	v_and_b32_e32 v9, 0xffff0000, v9
	s_waitcnt lgkmcnt(0)
	v_mov_b32_e32 v16, v22
	v_mov_b32_e32 v17, v24
	v_mov_b32_e32 v24, v23
	v_and_b32_sdwa v0, v29, v242 dst_sel:DWORD dst_unused:UNUSED_PAD src0_sel:WORD_1 src1_sel:DWORD
	v_add3_u32 v7, v15, v7, s71
	v_or_b32_sdwa v14, v9, v3 dst_sel:DWORD dst_unused:UNUSED_PAD src0_sel:DWORD src1_sel:WORD_1
	v_pk_mul_f32 v[16:17], v[8:9], v[16:17] op_sel_hi:[0,1]
	v_pk_mul_f32 v[8:9], v[8:9], v[24:25] op_sel_hi:[0,1]
	v_add3_u32 v0, v29, v0, s71
	v_and_b32_e32 v7, 0xffff0000, v7
	v_and_b32_sdwa v11, v8, v242 dst_sel:DWORD dst_unused:UNUSED_PAD src0_sel:WORD_1 src1_sel:DWORD
	v_or_b32_sdwa v15, v7, v0 dst_sel:DWORD dst_unused:UNUSED_PAD src0_sel:DWORD src1_sel:WORD_1
	v_and_b32_sdwa v3, v16, v242 dst_sel:DWORD dst_unused:UNUSED_PAD src0_sel:WORD_1 src1_sel:DWORD
	v_and_b32_sdwa v7, v9, v242 dst_sel:DWORD dst_unused:UNUSED_PAD src0_sel:WORD_1 src1_sel:DWORD
	v_add3_u32 v8, v8, v11, s71
	v_and_b32_sdwa v0, v17, v242 dst_sel:DWORD dst_unused:UNUSED_PAD src0_sel:WORD_1 src1_sel:DWORD
	v_add3_u32 v3, v16, v3, s71
	v_add3_u32 v7, v9, v7, s71
	v_and_b32_e32 v8, 0xffff0000, v8
	ds_read_b32 v5, v104 offset:252
	v_add3_u32 v0, v17, v0, s71
	v_and_b32_e32 v7, 0xffff0000, v7
	v_or_b32_sdwa v16, v8, v3 dst_sel:DWORD dst_unused:UNUSED_PAD src0_sel:DWORD src1_sel:WORD_1
	v_add_co_u32_e32 v8, vcc, s4, v26
	v_or_b32_sdwa v17, v7, v0 dst_sel:DWORD dst_unused:UNUSED_PAD src0_sel:DWORD src1_sel:WORD_1
	s_nop 0
	v_addc_co_u32_e32 v9, vcc, 0, v27, vcc
	global_store_dwordx4 v[8:9], v[14:17], off
	v_and_b32_e32 v0, 0x7f, v4
	v_lshl_add_u32 v8, v0, 2, v100
	v_and_b32_e32 v14, -8, v12
	v_lshl_add_u32 v3, v14, 2, v104
	v_mad_u64_u32 v[16:17], s[28:29], v14, s84, v[8:9]
	ds_read2_b32 v[22:23], v3 offset1:1
	ds_read2_b32 v[24:25], v16 offset1:132
	ds_read2_b32 v[26:27], v3 offset0:2 offset1:3
	ds_read2_b32 v[28:29], v3 offset0:4 offset1:5
	ds_read_b32 v3, v3 offset:24
	s_waitcnt lgkmcnt(4)
	v_sub_f32_e32 v7, v5, v22
	v_mul_f32_e32 v7, 0x3fb8aa3b, v7
	v_exp_f32_e32 v22, v7
	v_sub_f32_e32 v7, v5, v23
	v_mul_f32_e32 v7, 0x3fb8aa3b, v7
	v_exp_f32_e32 v30, v7
	v_add_u32_e32 v7, 0x400, v16
	ds_read2_b32 v[32:33], v7 offset0:8 offset1:140
	s_waitcnt lgkmcnt(3)
; DI uint4 pack8(const float* f) { uint4 o; o.x = pk2(f[0], f[1]); o.y = pk2(f[2], f[3]); o.z = pk2(f[4], f[5]); o.w = pk2(f[6], f[7]); return o; }
; template <int D> DI void dn_out(float (&x)[64], lf_t Kl, lf_t Ql, lf_t Gn, bf16_t* DW, bf16_t* DQE, bf16_t* DKT, bf16_t* DUT, float* DEG, int item, int t) {
;     ...
;             for (int i = 0; i < 4; ++i) { const int idx = t + 256 * i, dk = idx & 127, pg = idx >> 7; float v[8];
; #pragma unroll
;                 for (int e = 0; e < 8; ++e) { const int pi = 8 * pg + e, n = D ? 63 - pi : pi; v[e] = Kl[n * 132 + dk] * __expf(glast - Gd[n]); }
;                 *(uint4*)(DKT + (((size_t)D * 1152 + item) * 128 + dk) * 64 + 8 * pg) = pack8(v); }
	v_sub_f32_e32 v7, v5, v26
	v_mul_f32_e32 v7, 0x3fb8aa3b, v7
	v_exp_f32_e32 v23, v7
	v_sub_f32_e32 v7, v5, v27
	v_mul_f32_e32 v7, 0x3fb8aa3b, v7
	v_exp_f32_e32 v31, v7
	v_add_u32_e32 v7, 0x800, v16
	ds_read2_b32 v[26:27], v7 offset0:16 offset1:148
	s_waitcnt lgkmcnt(3)
	v_sub_f32_e32 v7, v5, v28
	v_mul_f32_e32 v7, 0x3fb8aa3b, v7
	v_exp_f32_e32 v28, v7
	v_sub_f32_e32 v7, v5, v29
	v_mul_f32_e32 v7, 0x3fb8aa3b, v7
	v_exp_f32_e32 v34, v7
	v_or_b32_e32 v7, 7, v12
	v_lshl_add_u32 v9, v7, 2, v104
	ds_read_b32 v9, v9
	s_waitcnt lgkmcnt(3)
	v_sub_f32_e32 v3, v5, v3
	v_mul_f32_e32 v3, 0x3fb8aa3b, v3
	v_exp_f32_e32 v29, v3
	v_ashrrev_i32_e32 v15, 31, v14
	s_waitcnt lgkmcnt(0)
	v_mad_u64_u32 v[12:13], s[28:29], v7, s84, v[8:9]
	v_sub_f32_e32 v3, v5, v9
	v_lshlrev_b32_e32 v0, 7, v0
	ds_read_b32 v17, v16 offset:3168
	ds_read_b32 v37, v12
	v_mul_f32_e32 v3, 0x3fb8aa3b, v3
	v_lshl_add_u64 v[12:13], v[14:15], 1, v[0:1]
	v_exp_f32_e32 v35, v3
	v_lshl_add_u64 v[38:39], s[20:21], 0, v[12:13]
	v_mov_b32_e32 v13, v32
	v_mov_b32_e32 v32, v25
	v_mov_b32_e32 v12, v24
	v_pk_mul_f32 v[14:15], v[32:33], v[30:31]
	v_pk_mul_f32 v[12:13], v[12:13], v[22:23]
	v_and_b32_sdwa v9, v15, v242 dst_sel:DWORD dst_unused:UNUSED_PAD src0_sel:WORD_1 src1_sel:DWORD
	v_and_b32_sdwa v11, v14, v242 dst_sel:DWORD dst_unused:UNUSED_PAD src0_sel:WORD_1 src1_sel:DWORD
	v_and_b32_sdwa v3, v13, v242 dst_sel:DWORD dst_unused:UNUSED_PAD src0_sel:WORD_1 src1_sel:DWORD
	v_and_b32_sdwa v7, v12, v242 dst_sel:DWORD dst_unused:UNUSED_PAD src0_sel:WORD_1 src1_sel:DWORD
	v_add3_u32 v9, v15, v9, s71
	v_add3_u32 v11, v14, v11, s71
	v_mov_b32_e32 v16, v26
	v_mov_b32_e32 v36, v27
	v_add3_u32 v7, v12, v7, s71
	v_add3_u32 v3, v13, v3, s71
	v_and_b32_e32 v9, 0xffff0000, v9
	v_and_b32_e32 v11, 0xffff0000, v11
	s_waitcnt lgkmcnt(1)
	v_pk_mul_f32 v[14:15], v[16:17], v[28:29]
	s_waitcnt lgkmcnt(0)
	v_pk_mul_f32 v[16:17], v[36:37], v[34:35]
	v_or_b32_sdwa v13, v9, v3 dst_sel:DWORD dst_unused:UNUSED_PAD src0_sel:DWORD src1_sel:WORD_1
	v_or_b32_sdwa v12, v11, v7 dst_sel:DWORD dst_unused:UNUSED_PAD src0_sel:DWORD src1_sel:WORD_1
	v_and_b32_sdwa v9, v17, v242 dst_sel:DWORD dst_unused:UNUSED_PAD src0_sel:WORD_1 src1_sel:DWORD
	v_and_b32_sdwa v11, v16, v242 dst_sel:DWORD dst_unused:UNUSED_PAD src0_sel:WORD_1 src1_sel:DWORD
	v_and_b32_sdwa v3, v15, v242 dst_sel:DWORD dst_unused:UNUSED_PAD src0_sel:WORD_1 src1_sel:DWORD
	v_and_b32_sdwa v7, v14, v242 dst_sel:DWORD dst_unused:UNUSED_PAD src0_sel:WORD_1 src1_sel:DWORD
	v_add3_u32 v9, v17, v9, s71
	v_add3_u32 v11, v16, v11, s71
	s_mov_b32 s4, 0x2406a000
	v_add3_u32 v7, v14, v7, s71
	v_add3_u32 v3, v15, v3, s71
	v_and_b32_e32 v9, 0xffff0000, v9
	v_and_b32_e32 v11, 0xffff0000, v11
	v_add_co_u32_e32 v16, vcc, s4, v38
	v_or_b32_sdwa v15, v9, v3 dst_sel:DWORD dst_unused:UNUSED_PAD src0_sel:DWORD src1_sel:WORD_1
	v_or_b32_sdwa v14, v11, v7 dst_sel:DWORD dst_unused:UNUSED_PAD src0_sel:DWORD src1_sel:WORD_1
	v_addc_co_u32_e32 v17, vcc, 0, v39, vcc
	global_store_dwordx4 v[16:17], v[12:15], off
	s_nop 1
	v_and_b32_e32 v12, -8, v10
	v_lshl_add_u32 v3, v12, 2, v104
	v_mad_u64_u32 v[14:15], s[28:29], v12, s84, v[8:9]
	ds_read2_b32 v[16:17], v3 offset1:1
	ds_read2_b32 v[22:23], v14 offset1:132
	ds_read2_b32 v[24:25], v3 offset0:2 offset1:3
	ds_read2_b32 v[26:27], v3 offset0:4 offset1:5
	ds_read_b32 v3, v3 offset:24
	s_waitcnt lgkmcnt(4)
	v_sub_f32_e32 v7, v5, v16
	v_mul_f32_e32 v7, 0x3fb8aa3b, v7
	v_exp_f32_e32 v16, v7
	v_sub_f32_e32 v7, v5, v17
	v_mul_f32_e32 v7, 0x3fb8aa3b, v7
	v_exp_f32_e32 v28, v7
	v_add_u32_e32 v7, 0x400, v14
	ds_read2_b32 v[30:31], v7 offset0:8 offset1:140
	s_waitcnt lgkmcnt(3)
	v_sub_f32_e32 v7, v5, v24
	v_mul_f32_e32 v7, 0x3fb8aa3b, v7
	v_exp_f32_e32 v17, v7
	v_sub_f32_e32 v7, v5, v25
	v_mul_f32_e32 v7, 0x3fb8aa3b, v7
	v_exp_f32_e32 v29, v7
	v_add_u32_e32 v7, 0x800, v14
	ds_read2_b32 v[24:25], v7 offset0:16 offset1:148
	s_waitcnt lgkmcnt(3)
	v_sub_f32_e32 v7, v5, v26
	v_mul_f32_e32 v7, 0x3fb8aa3b, v7
	v_exp_f32_e32 v26, v7
	v_sub_f32_e32 v7, v5, v27
	v_mul_f32_e32 v7, 0x3fb8aa3b, v7
	v_exp_f32_e32 v32, v7
	v_or_b32_e32 v7, 7, v10
	v_lshl_add_u32 v9, v7, 2, v104
	ds_read_b32 v9, v9
	s_waitcnt lgkmcnt(3)
	v_sub_f32_e32 v3, v5, v3
	v_ashrrev_i32_e32 v13, 31, v12
	ds_read_b32 v15, v14 offset:3168
	v_mul_f32_e32 v3, 0x3fb8aa3b, v3
	s_waitcnt lgkmcnt(1)
	v_mad_u64_u32 v[10:11], s[28:29], v7, s84, v[8:9]
	ds_read_b32 v35, v10
	v_lshl_add_u64 v[10:11], v[12:13], 1, v[0:1]
	v_exp_f32_e32 v27, v3
	v_sub_f32_e32 v3, v5, v9
	v_lshl_add_u64 v[36:37], s[20:21], 0, v[10:11]
	v_mov_b32_e32 v10, v22
	v_mov_b32_e32 v11, v30
	v_mul_f32_e32 v3, 0x3fb8aa3b, v3
	v_pk_mul_f32 v[10:11], v[10:11], v[16:17]
	v_mov_b32_e32 v30, v23
	v_exp_f32_e32 v33, v3
	v_pk_mul_f32 v[12:13], v[30:31], v[28:29]
	v_and_b32_sdwa v7, v10, v242 dst_sel:DWORD dst_unused:UNUSED_PAD src0_sel:WORD_1 src1_sel:DWORD
	v_add3_u32 v7, v10, v7, s71
	v_and_b32_sdwa v10, v12, v242 dst_sel:DWORD dst_unused:UNUSED_PAD src0_sel:WORD_1 src1_sel:DWORD
	v_and_b32_sdwa v9, v13, v242 dst_sel:DWORD dst_unused:UNUSED_PAD src0_sel:WORD_1 src1_sel:DWORD
	v_add3_u32 v10, v12, v10, s71
	v_mov_b32_e32 v14, v24
	v_and_b32_sdwa v3, v11, v242 dst_sel:DWORD dst_unused:UNUSED_PAD src0_sel:WORD_1 src1_sel:DWORD
	v_add3_u32 v9, v13, v9, s71
	v_and_b32_e32 v10, 0xffff0000, v10
	s_waitcnt lgkmcnt(1)
	v_pk_mul_f32 v[12:13], v[14:15], v[26:27]
	v_mov_b32_e32 v34, v25
	v_add3_u32 v3, v11, v3, s71
	v_and_b32_e32 v9, 0xffff0000, v9
	v_or_b32_sdwa v10, v10, v7 dst_sel:DWORD dst_unused:UNUSED_PAD src0_sel:DWORD src1_sel:WORD_1
	s_waitcnt lgkmcnt(0)
; DI uint4 pack8(const float* f) { uint4 o; o.x = pk2(f[0], f[1]); o.y = pk2(f[2], f[3]); o.z = pk2(f[4], f[5]); o.w = pk2(f[6], f[7]); return o; }
; template <int D> DI void dn_out(float (&x)[64], lf_t Kl, lf_t Ql, lf_t Gn, bf16_t* DW, bf16_t* DQE, bf16_t* DKT, bf16_t* DUT, float* DEG, int item, int t) {
;     ...
;             for (int i = 0; i < 4; ++i) { const int idx = t + 256 * i, dk = idx & 127, pg = idx >> 7; float v[8];
; #pragma unroll
;                 for (int e = 0; e < 8; ++e) { const int pi = 8 * pg + e, n = D ? 63 - pi : pi; v[e] = Kl[n * 132 + dk] * __expf(glast - Gd[n]); }
;                 *(uint4*)(DKT + (((size_t)D * 1152 + item) * 128 + dk) * 64 + 8 * pg) = pack8(v); }
	v_pk_mul_f32 v[14:15], v[34:35], v[32:33]
	v_and_b32_sdwa v7, v12, v242 dst_sel:DWORD dst_unused:UNUSED_PAD src0_sel:WORD_1 src1_sel:DWORD
	v_or_b32_sdwa v11, v9, v3 dst_sel:DWORD dst_unused:UNUSED_PAD src0_sel:DWORD src1_sel:WORD_1
	v_add3_u32 v7, v12, v7, s71
	v_and_b32_sdwa v9, v15, v242 dst_sel:DWORD dst_unused:UNUSED_PAD src0_sel:WORD_1 src1_sel:DWORD
	v_and_b32_sdwa v12, v14, v242 dst_sel:DWORD dst_unused:UNUSED_PAD src0_sel:WORD_1 src1_sel:DWORD
	v_and_b32_sdwa v3, v13, v242 dst_sel:DWORD dst_unused:UNUSED_PAD src0_sel:WORD_1 src1_sel:DWORD
	v_add3_u32 v9, v15, v9, s71
	v_add3_u32 v12, v14, v12, s71
	v_add3_u32 v3, v13, v3, s71
	v_and_b32_e32 v9, 0xffff0000, v9
	v_and_b32_e32 v12, 0xffff0000, v12
	v_add_co_u32_e32 v14, vcc, s4, v36
	v_or_b32_sdwa v13, v9, v3 dst_sel:DWORD dst_unused:UNUSED_PAD src0_sel:DWORD src1_sel:WORD_1
	v_or_b32_sdwa v12, v12, v7 dst_sel:DWORD dst_unused:UNUSED_PAD src0_sel:DWORD src1_sel:WORD_1
	v_addc_co_u32_e32 v15, vcc, 0, v37, vcc
	global_store_dwordx4 v[14:15], v[10:13], off
	s_nop 1
	v_and_b32_e32 v10, -8, v6
	v_lshl_add_u32 v3, v10, 2, v104
	v_mad_u64_u32 v[12:13], s[28:29], v10, s84, v[8:9]
	ds_read2_b32 v[14:15], v3 offset1:1
	ds_read2_b32 v[16:17], v12 offset1:132
	ds_read2_b32 v[22:23], v3 offset0:2 offset1:3
	ds_read2_b32 v[24:25], v3 offset0:4 offset1:5
	ds_read_b32 v3, v3 offset:24
	s_waitcnt lgkmcnt(4)
	v_sub_f32_e32 v7, v5, v14
	v_mul_f32_e32 v7, 0x3fb8aa3b, v7
	v_exp_f32_e32 v14, v7
	v_sub_f32_e32 v7, v5, v15
	v_mul_f32_e32 v7, 0x3fb8aa3b, v7
	v_exp_f32_e32 v26, v7
	v_add_u32_e32 v7, 0x400, v12
	ds_read2_b32 v[28:29], v7 offset0:8 offset1:140
	s_waitcnt lgkmcnt(3)
	v_sub_f32_e32 v7, v5, v22
	v_mul_f32_e32 v7, 0x3fb8aa3b, v7
	v_exp_f32_e32 v15, v7
	v_sub_f32_e32 v7, v5, v23
	v_or_b32_e32 v6, 7, v6
	v_mul_f32_e32 v7, 0x3fb8aa3b, v7
	v_lshl_add_u32 v9, v6, 2, v104
	v_exp_f32_e32 v27, v7
	v_add_u32_e32 v7, 0x800, v12
	ds_read_b32 v9, v9
	ds_read2_b32 v[22:23], v7 offset0:16 offset1:148
	s_waitcnt lgkmcnt(4)
	v_sub_f32_e32 v7, v5, v24
	v_ashrrev_i32_e32 v11, 31, v10
	v_mul_f32_e32 v7, 0x3fb8aa3b, v7
	v_lshl_add_u64 v[10:11], v[10:11], 1, v[0:1]
	v_exp_f32_e32 v24, v7
	v_sub_f32_e32 v7, v5, v25
	s_waitcnt lgkmcnt(3)
	v_sub_f32_e32 v3, v5, v3
	v_lshl_add_u64 v[32:33], s[20:21], 0, v[10:11]
	v_mov_b32_e32 v10, v16
	s_waitcnt lgkmcnt(2)
	v_mov_b32_e32 v11, v28
	v_mul_f32_e32 v7, 0x3fb8aa3b, v7
	v_mul_f32_e32 v3, 0x3fb8aa3b, v3
	v_pk_mul_f32 v[10:11], v[10:11], v[14:15]
	v_mov_b32_e32 v28, v17
	v_exp_f32_e32 v30, v7
	ds_read_b32 v7, v12 offset:3168
	v_exp_f32_e32 v25, v3
	s_waitcnt lgkmcnt(2)
	v_mad_u64_u32 v[12:13], s[28:29], v6, s84, v[8:9]
	v_sub_f32_e32 v3, v5, v9
	v_pk_mul_f32 v[14:15], v[28:29], v[26:27]
	v_and_b32_sdwa v6, v10, v242 dst_sel:DWORD dst_unused:UNUSED_PAD src0_sel:WORD_1 src1_sel:DWORD
	ds_read_b32 v13, v12
	v_mul_f32_e32 v3, 0x3fb8aa3b, v3
	v_add3_u32 v6, v10, v6, s71
	v_and_b32_sdwa v10, v14, v242 dst_sel:DWORD dst_unused:UNUSED_PAD src0_sel:WORD_1 src1_sel:DWORD
	v_exp_f32_e32 v31, v3
	v_add3_u32 v10, v14, v10, s71
	v_and_b32_sdwa v9, v15, v242 dst_sel:DWORD dst_unused:UNUSED_PAD src0_sel:WORD_1 src1_sel:DWORD
	v_and_b32_e32 v10, 0xffff0000, v10
	v_and_b32_sdwa v3, v11, v242 dst_sel:DWORD dst_unused:UNUSED_PAD src0_sel:WORD_1 src1_sel:DWORD
	v_add3_u32 v9, v15, v9, s71
	v_or_b32_sdwa v10, v10, v6 dst_sel:DWORD dst_unused:UNUSED_PAD src0_sel:DWORD src1_sel:WORD_1
	s_waitcnt lgkmcnt(2)
	v_mov_b32_e32 v6, v22
	v_add3_u32 v3, v11, v3, s71
	v_and_b32_e32 v9, 0xffff0000, v9
	s_waitcnt lgkmcnt(1)
	v_pk_mul_f32 v[6:7], v[6:7], v[24:25]
	v_mov_b32_e32 v12, v23
	v_or_b32_sdwa v11, v9, v3 dst_sel:DWORD dst_unused:UNUSED_PAD src0_sel:DWORD src1_sel:WORD_1
	s_waitcnt lgkmcnt(0)
; DI uint4 pack8(const float* f) { uint4 o; o.x = pk2(f[0], f[1]); o.y = pk2(f[2], f[3]); o.z = pk2(f[4], f[5]); o.w = pk2(f[6], f[7]); return o; }
; template <int D> DI void dn_out(float (&x)[64], lf_t Kl, lf_t Ql, lf_t Gn, bf16_t* DW, bf16_t* DQE, bf16_t* DKT, bf16_t* DUT, float* DEG, int item, int t) {
;     ...
;             for (int i = 0; i < 4; ++i) { const int idx = t + 256 * i, dk = idx & 127, pg = idx >> 7; float v[8];
; #pragma unroll
;                 for (int e = 0; e < 8; ++e) { const int pi = 8 * pg + e, n = D ? 63 - pi : pi; v[e] = Kl[n * 132 + dk] * __expf(glast - Gd[n]); }
;                 *(uint4*)(DKT + (((size_t)D * 1152 + item) * 128 + dk) * 64 + 8 * pg) = pack8(v); }
;             if (t == 0) DEG[D * 1152 + item] = __expf(glast);
	v_pk_mul_f32 v[12:13], v[12:13], v[30:31]
	v_and_b32_sdwa v9, v6, v242 dst_sel:DWORD dst_unused:UNUSED_PAD src0_sel:WORD_1 src1_sel:DWORD
	v_and_b32_sdwa v3, v7, v242 dst_sel:DWORD dst_unused:UNUSED_PAD src0_sel:WORD_1 src1_sel:DWORD
	v_add3_u32 v6, v6, v9, s71
	v_and_b32_sdwa v9, v12, v242 dst_sel:DWORD dst_unused:UNUSED_PAD src0_sel:WORD_1 src1_sel:DWORD
	v_add3_u32 v3, v7, v3, s71
	v_and_b32_sdwa v7, v13, v242 dst_sel:DWORD dst_unused:UNUSED_PAD src0_sel:WORD_1 src1_sel:DWORD
	v_add3_u32 v9, v12, v9, s71
	v_add3_u32 v7, v13, v7, s71
	v_and_b32_e32 v9, 0xffff0000, v9
	v_and_b32_e32 v7, 0xffff0000, v7
	v_or_b32_sdwa v12, v9, v6 dst_sel:DWORD dst_unused:UNUSED_PAD src0_sel:DWORD src1_sel:WORD_1
	v_add_co_u32_e32 v6, vcc, s4, v32
	v_or_b32_sdwa v13, v7, v3 dst_sel:DWORD dst_unused:UNUSED_PAD src0_sel:DWORD src1_sel:WORD_1
	s_nop 0
	v_addc_co_u32_e32 v7, vcc, 0, v33, vcc
	global_store_dwordx4 v[6:7], v[10:13], off
	v_and_b32_e32 v6, -8, v2
	v_lshl_add_u32 v3, v6, 2, v104
	v_mad_u64_u32 v[10:11], s[28:29], v6, s84, v[8:9]
	ds_read2_b32 v[12:13], v3 offset1:1
	ds_read2_b32 v[14:15], v10 offset1:132
	ds_read2_b32 v[16:17], v3 offset0:2 offset1:3
	ds_read2_b32 v[22:23], v3 offset0:4 offset1:5
	ds_read_b32 v7, v3 offset:24
	s_waitcnt lgkmcnt(4)
	v_sub_f32_e32 v3, v5, v12
	v_mul_f32_e32 v3, 0x3fb8aa3b, v3
	v_exp_f32_e32 v12, v3
	v_sub_f32_e32 v3, v5, v13
	v_mul_f32_e32 v3, 0x3fb8aa3b, v3
	v_exp_f32_e32 v24, v3
	v_add_u32_e32 v3, 0x400, v10
	ds_read2_b32 v[26:27], v3 offset0:8 offset1:140
	s_waitcnt lgkmcnt(3)
	v_sub_f32_e32 v3, v5, v16
	v_mul_f32_e32 v3, 0x3fb8aa3b, v3
	v_exp_f32_e32 v13, v3
	v_sub_f32_e32 v3, v5, v17
	v_mul_f32_e32 v3, 0x3fb8aa3b, v3
	v_exp_f32_e32 v25, v3
	v_add_u32_e32 v3, 0x800, v10
	ds_read2_b32 v[16:17], v3 offset0:16 offset1:148
	s_waitcnt lgkmcnt(3)
	v_sub_f32_e32 v3, v5, v22
	v_mul_f32_e32 v3, 0x3fb8aa3b, v3
	v_exp_f32_e32 v22, v3
	v_sub_f32_e32 v3, v5, v23
	v_or_b32_e32 v2, 7, v2
	v_mul_f32_e32 v3, 0x3fb8aa3b, v3
	v_lshl_add_u32 v9, v2, 2, v104
	v_exp_f32_e32 v28, v3
	ds_read_b32 v3, v10 offset:3168
	ds_read_b32 v10, v9
	s_waitcnt lgkmcnt(4)
	v_sub_f32_e32 v7, v5, v7
	v_mul_f32_e32 v7, 0x3fb8aa3b, v7
	v_exp_f32_e32 v23, v7
	v_ashrrev_i32_e32 v7, 31, v6
	v_lshl_add_u64 v[6:7], v[6:7], 1, v[0:1]
	v_mad_u64_u32 v[8:9], s[28:29], v2, s84, v[8:9]
	s_waitcnt lgkmcnt(0)
	v_sub_f32_e32 v2, v5, v10
	v_lshl_add_u64 v[10:11], s[20:21], 0, v[6:7]
	v_mov_b32_e32 v6, v14
	v_mov_b32_e32 v7, v26
	v_mul_f32_e32 v2, 0x3fb8aa3b, v2
	v_pk_mul_f32 v[6:7], v[6:7], v[12:13]
	v_mov_b32_e32 v26, v15
	v_exp_f32_e32 v29, v2
	v_pk_mul_f32 v[12:13], v[26:27], v[24:25]
	v_and_b32_sdwa v0, v7, v242 dst_sel:DWORD dst_unused:UNUSED_PAD src0_sel:WORD_1 src1_sel:DWORD
	v_and_b32_sdwa v2, v6, v242 dst_sel:DWORD dst_unused:UNUSED_PAD src0_sel:WORD_1 src1_sel:DWORD
	ds_read_b32 v9, v8
	v_add3_u32 v2, v6, v2, s71
	v_add3_u32 v0, v7, v0, s71
	v_and_b32_sdwa v6, v13, v242 dst_sel:DWORD dst_unused:UNUSED_PAD src0_sel:WORD_1 src1_sel:DWORD
	v_and_b32_sdwa v7, v12, v242 dst_sel:DWORD dst_unused:UNUSED_PAD src0_sel:WORD_1 src1_sel:DWORD
	v_add3_u32 v6, v13, v6, s71
	v_add3_u32 v7, v12, v7, s71
	v_and_b32_e32 v6, 0xffff0000, v6
	v_and_b32_e32 v8, 0xffff0000, v7
	v_or_b32_sdwa v7, v6, v0 dst_sel:DWORD dst_unused:UNUSED_PAD src0_sel:DWORD src1_sel:WORD_1
	v_or_b32_sdwa v6, v8, v2 dst_sel:DWORD dst_unused:UNUSED_PAD src0_sel:DWORD src1_sel:WORD_1
	v_mov_b32_e32 v2, v16
	v_pk_mul_f32 v[2:3], v[2:3], v[22:23]
	v_mov_b32_e32 v8, v17
	s_waitcnt lgkmcnt(0)
	v_pk_mul_f32 v[8:9], v[8:9], v[28:29]
	v_and_b32_sdwa v12, v2, v242 dst_sel:DWORD dst_unused:UNUSED_PAD src0_sel:WORD_1 src1_sel:DWORD
	v_and_b32_sdwa v0, v3, v242 dst_sel:DWORD dst_unused:UNUSED_PAD src0_sel:WORD_1 src1_sel:DWORD
	v_add3_u32 v2, v2, v12, s71
	v_and_b32_sdwa v12, v8, v242 dst_sel:DWORD dst_unused:UNUSED_PAD src0_sel:WORD_1 src1_sel:DWORD
	v_add3_u32 v0, v3, v0, s71
	v_and_b32_sdwa v3, v9, v242 dst_sel:DWORD dst_unused:UNUSED_PAD src0_sel:WORD_1 src1_sel:DWORD
	v_add3_u32 v8, v8, v12, s71
	v_add3_u32 v3, v9, v3, s71
	v_and_b32_e32 v8, 0xffff0000, v8
	v_and_b32_e32 v3, 0xffff0000, v3
	v_or_b32_sdwa v8, v8, v2 dst_sel:DWORD dst_unused:UNUSED_PAD src0_sel:DWORD src1_sel:WORD_1
	v_add_co_u32_e32 v2, vcc, 0x2406a000, v10
	v_or_b32_sdwa v9, v3, v0 dst_sel:DWORD dst_unused:UNUSED_PAD src0_sel:DWORD src1_sel:WORD_1
	s_nop 0
	v_addc_co_u32_e32 v3, vcc, 0, v11, vcc
	v_cmp_eq_u32_e32 vcc, 0, v4
	global_store_dwordx4 v[2:3], v[6:9], off
	s_and_saveexec_b64 s[20:21], vcc
	s_cbranch_execz .LBB0_474
	v_mul_f32_e32 v0, 0x3fb8aa3b, v5
	v_exp_f32_e32 v0, v0
	s_add_u32 s28, s66, s8
	s_addc_u32 s29, s67, s9
	v_mov_b32_e32 v2, 0x2be6a000
	global_store_dword v2, v0, s[28:29]
	s_branch .LBB0_474
